# k57: k56 + nt stores in the P1 (XN), S5 output GEMM (YS) and GLU GEMM (MX) epilogues as well
# baseline (speedup 1.0000x reference)
; #define LAS __attribute__((address_space(3)))
; __global__ void __launch_bounds__(NTHR, 2) hymba_fwd(Params P) {
;     ...
;             { const int pn = (p + 1 < p_hi) ? p + 1 : p; const float* r0 = rowptr(2 * pn); const float* r1 = rowptr(2 * pn + 1);
; #pragma unroll
;               for (int j = 0; j < 4; ++j) { n0[j] = __builtin_nontemporal_load((const f32x4*)r0 + lane + 64 * j); n1[j] = __builtin_nontemporal_load((const f32x4*)r1 + lane + 64 * j); } }
;             float ss0 = 0.f, ss1 = 0.f, v[16];
; #pragma unroll
;             for (int c = 0; c < 16; ++c) v[c] = 0.f;
; #pragma unroll
;             for (int j = 0; j < 4; ++j) { const int k = 4 * lane + 256 * j;
;                 ss0 += (x0[j].x * x0[j].x + x0[j].y * x0[j].y) + (x0[j].z * x0[j].z + x0[j].w * x0[j].w);
;                 ss1 += (x1[j].x * x1[j].x + x1[j].y * x1[j].y) + (x1[j].z * x1[j].z + x1[j].w * x1[j].w);
;                 x0[j] = x0[j] * Ak[j]; x1[j] = x1[j] * Ak[j];
; #pragma unroll
;                 for (int c = 0; c < 8; ++c) { const f32x4 w = *(const LAS f32x4*)(w8 + c * 1024 + k);
;                     v[c] += (x0[j].x * w.x + x0[j].y * w.y) + (x0[j].z * w.z + x0[j].w * w.w);
;                     v[8 + c] += (x1[j].x * w.x + x1[j].y * w.y) + (x1[j].z * w.z + x1[j].w * w.w); }
;                 asm volatile("" ::: "memory"); }
.LBB0_145:
	s_add_i32 s50, s45, 1
	s_cmp_ge_i32 s50, s3
	s_cselect_b64 s[58:59], -1, 0
	s_cmp_lt_i32 s50, s3
	s_cselect_b32 s30, s50, s45
	s_lshl_b32 s45, s30, 1
	s_add_i32 s52, s45, 0xffff0000
	s_ashr_i32 s31, s45, 31
	s_cmp_lt_i32 s30, 0x8000
	s_cselect_b32 s31, s31, 0
	s_cselect_b32 s30, s45, s52
	s_cselect_b32 s52, s37, s39
	s_cselect_b32 s53, s36, s38
	s_lshl_b64 s[30:31], s[30:31], 12
	s_add_u32 s30, s53, s30
	s_addc_u32 s31, s52, s31
	s_or_b32 s52, s45, 1
	s_add_i32 s45, s45, 0xffff0001
	s_ashr_i32 s53, s52, 31
	s_cmp_lt_i32 s52, 0x10000
	s_cselect_b32 s53, s53, 0
	s_cselect_b32 s52, s52, s45
	s_cselect_b32 s45, s37, s39
	s_cselect_b32 s60, s36, s38
	s_lshl_b64 s[52:53], s[52:53], 12
	s_add_u32 s52, s60, s52
	s_addc_u32 s53, s45, s53
	global_load_dwordx4 v[52:55], v130, s[30:31] nt
	global_load_dwordx4 v[68:71], v130, s[52:53] nt
	global_load_dwordx4 v[56:59], v130, s[30:31] offset:1024 nt
	global_load_dwordx4 v[76:79], v130, s[52:53] offset:1024 nt
	global_load_dwordx4 v[60:63], v130, s[30:31] offset:2048 nt
	global_load_dwordx4 v[72:75], v130, s[52:53] offset:2048 nt
	global_load_dwordx4 v[64:67], v130, s[30:31] offset:3072 nt
	global_load_dwordx4 v[80:83], v130, s[52:53] offset:3072 nt
	ds_read_b128 v[138:141], v0
	ds_read_b128 v[142:145], v0 offset:4096
	s_waitcnt vmcnt(15)
	v_pk_mul_f32 v[2:3], v[98:99], v[98:99]
	v_pk_mul_f32 v[118:119], v[96:97], v[96:97]
	v_pk_mul_f32 v[98:99], v[98:99], v[18:19]
	v_pk_mov_b32 v[120:121], v[118:119], v[2:3] op_sel:[1,0]
	v_mov_b32_e32 v119, v3
	v_pk_add_f32 v[122:123], v[120:121], v[118:119]
	s_waitcnt vmcnt(13)
	v_pk_mul_f32 v[2:3], v[94:95], v[94:95]
	v_pk_mul_f32 v[120:121], v[92:93], v[92:93]
	v_pk_mul_f32 v[96:97], v[96:97], v[16:17]
	v_pk_mov_b32 v[126:127], v[120:121], v[2:3] op_sel:[1,0]
	v_mov_b32_e32 v121, v3
	v_pk_mul_f32 v[2:3], v[94:95], v[18:19]
	s_waitcnt lgkmcnt(1)
	v_mul_f32_e32 v94, v97, v139
	v_mul_f32_e32 v95, v99, v141
	v_fmac_f32_e32 v94, v96, v138
	v_fmac_f32_e32 v95, v98, v140
	v_pk_mul_f32 v[92:93], v[92:93], v[16:17]
	v_add_f32_e32 v94, v94, v95
	v_add_f32_e32 v137, 0, v94
	v_mul_f32_e32 v94, v93, v139
	v_mul_f32_e32 v95, v3, v141
	v_fmac_f32_e32 v94, v92, v138
	v_fmac_f32_e32 v95, v2, v140
	v_add_f32_e32 v94, v94, v95
	v_add_f32_e32 v146, 0, v94
	s_waitcnt lgkmcnt(0)
	v_mul_f32_e32 v94, v97, v143
	v_mul_f32_e32 v95, v99, v145
	v_fmac_f32_e32 v94, v96, v142
	v_fmac_f32_e32 v95, v98, v144
	ds_read_b128 v[138:141], v0 offset:8192
	v_add_f32_e32 v94, v94, v95
	v_add_f32_e32 v147, 0, v94
	v_mul_f32_e32 v94, v93, v143
	v_mul_f32_e32 v95, v3, v145
	v_fmac_f32_e32 v94, v92, v142
	v_fmac_f32_e32 v95, v2, v144
	v_add_f32_e32 v94, v94, v95
	v_add_f32_e32 v148, 0, v94
	ds_read_b128 v[142:145], v0 offset:12288
	s_waitcnt lgkmcnt(1)
	v_mul_f32_e32 v94, v97, v139
	v_mul_f32_e32 v95, v99, v141
	v_fmac_f32_e32 v94, v96, v138
	v_fmac_f32_e32 v95, v98, v140
	v_add_f32_e32 v94, v94, v95
	v_add_f32_e32 v149, 0, v94
	v_mul_f32_e32 v94, v93, v139
	v_mul_f32_e32 v95, v3, v141
	v_fmac_f32_e32 v94, v92, v138
	v_fmac_f32_e32 v95, v2, v140
	v_add_f32_e32 v94, v94, v95
	v_add_f32_e32 v150, 0, v94
	s_waitcnt lgkmcnt(0)
	v_mul_f32_e32 v94, v97, v143
	v_mul_f32_e32 v95, v99, v145
	v_fmac_f32_e32 v94, v96, v142
	v_fmac_f32_e32 v95, v98, v144
	ds_read_b128 v[138:141], v0 offset:16384
	v_add_f32_e32 v94, v94, v95
	v_add_f32_e32 v151, 0, v94
	v_mul_f32_e32 v94, v93, v143
	v_mul_f32_e32 v95, v3, v145
	v_fmac_f32_e32 v94, v92, v142
	v_fmac_f32_e32 v95, v2, v144
	v_add_f32_e32 v94, v94, v95
	v_add_f32_e32 v152, 0, v94
	ds_read_b128 v[142:145], v0 offset:20480
	s_waitcnt lgkmcnt(1)
	v_mul_f32_e32 v94, v97, v139
	v_mul_f32_e32 v95, v99, v141
	v_fmac_f32_e32 v94, v96, v138
	v_fmac_f32_e32 v95, v98, v140
	v_add_f32_e32 v94, v94, v95
	v_add_f32_e32 v153, 0, v94
	v_mul_f32_e32 v94, v93, v139
	v_mul_f32_e32 v95, v3, v141
	v_fmac_f32_e32 v94, v92, v138
	v_fmac_f32_e32 v95, v2, v140
	v_add_f32_e32 v94, v94, v95
	v_add_f32_e32 v154, 0, v94
	s_waitcnt lgkmcnt(0)
	v_mul_f32_e32 v94, v97, v143
	v_mul_f32_e32 v95, v99, v145
	v_fmac_f32_e32 v94, v96, v142
	v_fmac_f32_e32 v95, v98, v144
	ds_read_b128 v[138:141], v0 offset:24576
	v_add_f32_e32 v94, v94, v95
	v_add_f32_e32 v155, 0, v94
	v_mul_f32_e32 v94, v93, v143
	v_mul_f32_e32 v95, v3, v145
	v_fmac_f32_e32 v94, v92, v142
	v_fmac_f32_e32 v95, v2, v144
	v_add_f32_e32 v94, v94, v95
	v_add_f32_e32 v156, 0, v94
	ds_read_b128 v[142:145], v0 offset:28672
	s_waitcnt lgkmcnt(1)
	v_mul_f32_e32 v94, v97, v139
	v_mul_f32_e32 v95, v99, v141
	v_fmac_f32_e32 v94, v96, v138
	v_fmac_f32_e32 v95, v98, v140
	v_add_f32_e32 v94, v94, v95
	v_add_f32_e32 v157, 0, v94
	v_mul_f32_e32 v94, v93, v139
	v_mul_f32_e32 v95, v3, v141
	v_fmac_f32_e32 v94, v92, v138
	v_fmac_f32_e32 v95, v2, v140
	v_add_f32_e32 v94, v94, v95
	v_add_f32_e32 v158, 0, v94
	s_waitcnt lgkmcnt(0)
	v_mul_f32_e32 v94, v97, v143
	v_mul_f32_e32 v95, v99, v145
	v_fmac_f32_e32 v94, v96, v142
	v_fmac_f32_e32 v95, v98, v144
	v_add_f32_e32 v94, v94, v95
	v_add_f32_e32 v159, 0, v94
	v_mul_f32_e32 v94, v93, v143
	v_mul_f32_e32 v95, v3, v145
	v_fmac_f32_e32 v94, v92, v142
	v_fmac_f32_e32 v95, v2, v144
	v_pk_mul_f32 v[114:115], v[90:91], v[90:91]
	v_pk_mul_f32 v[116:117], v[88:89], v[88:89]
	v_add_f32_e32 v94, v94, v95
	v_add_f32_e32 v142, 0, v94
	v_pk_mov_b32 v[94:95], v[116:117], v[114:115] op_sel:[1,0]
	v_mov_b32_e32 v117, v115
	v_pk_add_f32 v[120:121], v[126:127], v[120:121]
	v_pk_add_f32 v[126:127], v[94:95], v[116:117]
	ds_read_b128 v[114:117], v0 offset:1024
	ds_read_b128 v[138:141], v0 offset:5120
	s_waitcnt vmcnt(12)
; #define LAS __attribute__((address_space(3)))
; __global__ void __launch_bounds__(NTHR, 2) hymba_fwd(Params P) {
;     ...
;             for (int j = 0; j < 4; ++j) { const int k = 4 * lane + 256 * j;
;                 ss0 += (x0[j].x * x0[j].x + x0[j].y * x0[j].y) + (x0[j].z * x0[j].z + x0[j].w * x0[j].w);
;                 ss1 += (x1[j].x * x1[j].x + x1[j].y * x1[j].y) + (x1[j].z * x1[j].z + x1[j].w * x1[j].w);
;                 x0[j] = x0[j] * Ak[j]; x1[j] = x1[j] * Ak[j];
; #pragma unroll
;                 for (int c = 0; c < 8; ++c) { const f32x4 w = *(const LAS f32x4*)(w8 + c * 1024 + k);
;                     v[c] += (x0[j].x * w.x + x0[j].y * w.y) + (x0[j].z * w.z + x0[j].w * w.w);
;                     v[8 + c] += (x1[j].x * w.x + x1[j].y * w.y) + (x1[j].z * w.z + x1[j].w * w.w); }
;                 asm volatile("" ::: "memory"); }
	v_pk_mul_f32 v[118:119], v[86:87], v[86:87]
	v_pk_mul_f32 v[124:125], v[84:85], v[84:85]
	v_pk_mul_f32 v[90:91], v[90:91], v[22:23]
	v_pk_mov_b32 v[94:95], v[124:125], v[118:119] op_sel:[1,0]
	v_mov_b32_e32 v125, v119
	v_pk_mul_f32 v[88:89], v[88:89], v[20:21]
	v_pk_add_f32 v[124:125], v[94:95], v[124:125]
	s_waitcnt lgkmcnt(1)
	v_mul_f32_e32 v94, v89, v115
	v_mul_f32_e32 v95, v91, v117
	v_fmac_f32_e32 v94, v88, v114
	v_fmac_f32_e32 v95, v90, v116
	v_pk_mul_f32 v[86:87], v[86:87], v[22:23]
	v_pk_mul_f32 v[84:85], v[84:85], v[20:21]
	v_add_f32_e32 v94, v94, v95
	v_add_f32_e32 v137, v137, v94
	v_mul_f32_e32 v94, v85, v115
	v_mul_f32_e32 v95, v87, v117
	v_fmac_f32_e32 v94, v84, v114
	v_fmac_f32_e32 v95, v86, v116
	v_add_f32_e32 v94, v94, v95
	v_add_f32_e32 v146, v146, v94
	s_waitcnt lgkmcnt(0)
	v_mul_f32_e32 v94, v89, v139
	v_mul_f32_e32 v95, v91, v141
	v_fmac_f32_e32 v94, v88, v138
	v_fmac_f32_e32 v95, v90, v140
	ds_read_b128 v[114:117], v0 offset:9216
	v_add_f32_e32 v94, v94, v95
	v_add_f32_e32 v147, v147, v94
	v_mul_f32_e32 v94, v85, v139
	v_mul_f32_e32 v95, v87, v141
	v_fmac_f32_e32 v94, v84, v138
	v_fmac_f32_e32 v95, v86, v140
	v_add_f32_e32 v94, v94, v95
	v_add_f32_e32 v148, v148, v94
	ds_read_b128 v[138:141], v0 offset:13312
	s_waitcnt lgkmcnt(1)
	v_mul_f32_e32 v94, v89, v115
	v_mul_f32_e32 v95, v91, v117
	v_fmac_f32_e32 v94, v88, v114
	v_fmac_f32_e32 v95, v90, v116
	v_add_f32_e32 v94, v94, v95
	v_add_f32_e32 v149, v149, v94
	v_mul_f32_e32 v94, v85, v115
	v_mul_f32_e32 v95, v87, v117
	v_fmac_f32_e32 v94, v84, v114
	v_fmac_f32_e32 v95, v86, v116
	v_add_f32_e32 v94, v94, v95
	v_add_f32_e32 v150, v150, v94
	s_waitcnt lgkmcnt(0)
	v_mul_f32_e32 v94, v89, v139
	v_mul_f32_e32 v95, v91, v141
	v_fmac_f32_e32 v94, v88, v138
	v_fmac_f32_e32 v95, v90, v140
	ds_read_b128 v[114:117], v0 offset:17408
	v_add_f32_e32 v94, v94, v95
	v_add_f32_e32 v151, v151, v94
	v_mul_f32_e32 v94, v85, v139
	v_mul_f32_e32 v95, v87, v141
	v_fmac_f32_e32 v94, v84, v138
	v_fmac_f32_e32 v95, v86, v140
	v_add_f32_e32 v94, v94, v95
	v_add_f32_e32 v152, v152, v94
	ds_read_b128 v[138:141], v0 offset:21504
	s_waitcnt lgkmcnt(1)
	v_mul_f32_e32 v94, v89, v115
	v_mul_f32_e32 v95, v91, v117
	v_fmac_f32_e32 v94, v88, v114
	v_fmac_f32_e32 v95, v90, v116
	v_add_f32_e32 v94, v94, v95
	v_add_f32_e32 v153, v153, v94
	v_mul_f32_e32 v94, v85, v115
	v_mul_f32_e32 v95, v87, v117
	v_fmac_f32_e32 v94, v84, v114
	v_fmac_f32_e32 v95, v86, v116
	v_add_f32_e32 v94, v94, v95
	v_add_f32_e32 v154, v154, v94
	s_waitcnt lgkmcnt(0)
	v_mul_f32_e32 v94, v89, v139
	v_mul_f32_e32 v95, v91, v141
	v_fmac_f32_e32 v94, v88, v138
	v_fmac_f32_e32 v95, v90, v140
	ds_read_b128 v[114:117], v0 offset:25600
	v_add_f32_e32 v94, v94, v95
	v_add_f32_e32 v155, v155, v94
	v_mul_f32_e32 v94, v85, v139
	v_mul_f32_e32 v95, v87, v141
	v_fmac_f32_e32 v94, v84, v138
	v_fmac_f32_e32 v95, v86, v140
	v_add_f32_e32 v94, v94, v95
	v_add_f32_e32 v156, v156, v94
	ds_read_b128 v[138:141], v0 offset:29696
	s_waitcnt lgkmcnt(1)
	v_mul_f32_e32 v94, v89, v115
	v_mul_f32_e32 v95, v91, v117
	v_fmac_f32_e32 v94, v88, v114
	v_fmac_f32_e32 v95, v90, v116
	v_add_f32_e32 v94, v94, v95
	v_add_f32_e32 v157, v157, v94
	v_mul_f32_e32 v94, v85, v115
	v_mul_f32_e32 v95, v87, v117
	v_fmac_f32_e32 v94, v84, v114
	v_fmac_f32_e32 v95, v86, v116
	v_add_f32_e32 v94, v94, v95
	v_add_f32_e32 v158, v158, v94
	s_waitcnt lgkmcnt(0)
	v_mul_f32_e32 v94, v89, v139
	v_mul_f32_e32 v95, v91, v141
	v_fmac_f32_e32 v94, v88, v138
	v_fmac_f32_e32 v95, v90, v140
	v_add_f32_e32 v94, v94, v95
	v_add_f32_e32 v159, v159, v94
	v_mul_f32_e32 v94, v85, v139
	v_mul_f32_e32 v95, v87, v141
	v_fmac_f32_e32 v94, v84, v138
	v_fmac_f32_e32 v95, v86, v140
	ds_read_b128 v[138:141], v0 offset:2048
	v_add_f32_e32 v94, v94, v95
	v_add_f32_e32 v160, v142, v94
	s_waitcnt vmcnt(11)
	v_pk_mul_f32 v[94:95], v[50:51], v[30:31]
	v_pk_mul_f32 v[114:115], v[48:49], v[28:29]
	s_waitcnt lgkmcnt(0)
	v_mul_f32_e32 v143, v95, v141
	v_mul_f32_e32 v142, v115, v139
	v_fmac_f32_e32 v142, v114, v138
	v_fmac_f32_e32 v143, v94, v140
	v_add_f32_e32 v142, v142, v143
	s_waitcnt vmcnt(9)
	v_pk_mul_f32 v[118:119], v[44:45], v[28:29]
	v_add_f32_e32 v161, v137, v142
	ds_read_b128 v[142:145], v0 offset:6144
	v_pk_mul_f32 v[116:117], v[46:47], v[30:31]
	v_mul_f32_e32 v137, v119, v139
	v_fmac_f32_e32 v137, v118, v138
	v_mul_f32_e32 v138, v117, v141
	v_fmac_f32_e32 v138, v116, v140
	v_add_f32_e32 v137, v137, v138
	v_add_f32_e32 v146, v146, v137
	s_waitcnt lgkmcnt(0)
	v_mul_f32_e32 v137, v115, v143
	v_mul_f32_e32 v138, v95, v145
	v_fmac_f32_e32 v137, v114, v142
	v_fmac_f32_e32 v138, v94, v144
	v_add_f32_e32 v137, v137, v138
	ds_read_b128 v[138:141], v0 offset:10240
	v_add_f32_e32 v147, v147, v137
	v_mul_f32_e32 v137, v119, v143
	v_fmac_f32_e32 v137, v118, v142
	v_mul_f32_e32 v142, v117, v145
	v_fmac_f32_e32 v142, v116, v144
	v_add_f32_e32 v137, v137, v142
	v_add_f32_e32 v148, v148, v137
	s_waitcnt lgkmcnt(0)
	v_mul_f32_e32 v137, v115, v139
	v_mul_f32_e32 v142, v95, v141
	v_fmac_f32_e32 v137, v114, v138
	v_fmac_f32_e32 v142, v94, v140
	v_add_f32_e32 v137, v137, v142
	ds_read_b128 v[142:145], v0 offset:14336
	v_add_f32_e32 v149, v149, v137
	v_mul_f32_e32 v137, v119, v139
	v_fmac_f32_e32 v137, v118, v138
	v_mul_f32_e32 v138, v117, v141
	v_fmac_f32_e32 v138, v116, v140
	v_add_f32_e32 v137, v137, v138
	v_add_f32_e32 v150, v150, v137
	s_waitcnt lgkmcnt(0)
	v_mul_f32_e32 v137, v115, v143
	v_mul_f32_e32 v138, v95, v145
	v_fmac_f32_e32 v137, v114, v142
	v_fmac_f32_e32 v138, v94, v144
	v_add_f32_e32 v137, v137, v138
	ds_read_b128 v[138:141], v0 offset:18432
	v_add_f32_e32 v151, v151, v137
	v_mul_f32_e32 v137, v119, v143
	v_fmac_f32_e32 v137, v118, v142
	v_mul_f32_e32 v142, v117, v145
	v_fmac_f32_e32 v142, v116, v144
	v_add_f32_e32 v137, v137, v142
	v_add_f32_e32 v152, v152, v137
	s_waitcnt lgkmcnt(0)
; #define LAS __attribute__((address_space(3)))
; __global__ void __launch_bounds__(NTHR, 2) hymba_fwd(Params P) {
;     ...
;             for (int j = 0; j < 4; ++j) { const int k = 4 * lane + 256 * j;
;                 ss0 += (x0[j].x * x0[j].x + x0[j].y * x0[j].y) + (x0[j].z * x0[j].z + x0[j].w * x0[j].w);
;                 ss1 += (x1[j].x * x1[j].x + x1[j].y * x1[j].y) + (x1[j].z * x1[j].z + x1[j].w * x1[j].w);
;                 x0[j] = x0[j] * Ak[j]; x1[j] = x1[j] * Ak[j];
; #pragma unroll
;                 for (int c = 0; c < 8; ++c) { const f32x4 w = *(const LAS f32x4*)(w8 + c * 1024 + k);
;                     v[c] += (x0[j].x * w.x + x0[j].y * w.y) + (x0[j].z * w.z + x0[j].w * w.w);
;                     v[8 + c] += (x1[j].x * w.x + x1[j].y * w.y) + (x1[j].z * w.z + x1[j].w * w.w); }
;                 asm volatile("" ::: "memory"); }
;             ss0 = wave_sum(ss0); ss1 = wave_sum(ss1);
	v_mul_f32_e32 v137, v115, v139
	v_mul_f32_e32 v142, v95, v141
	v_fmac_f32_e32 v137, v114, v138
	v_fmac_f32_e32 v142, v94, v140
	v_add_f32_e32 v137, v137, v142
	ds_read_b128 v[142:145], v0 offset:22528
	v_add_f32_e32 v153, v153, v137
	v_mul_f32_e32 v137, v119, v139
	v_fmac_f32_e32 v137, v118, v138
	v_mul_f32_e32 v138, v117, v141
	v_fmac_f32_e32 v138, v116, v140
	v_add_f32_e32 v137, v137, v138
	v_add_f32_e32 v154, v154, v137
	s_waitcnt lgkmcnt(0)
	v_mul_f32_e32 v137, v115, v143
	v_mul_f32_e32 v138, v95, v145
	v_fmac_f32_e32 v137, v114, v142
	v_fmac_f32_e32 v138, v94, v144
	v_add_f32_e32 v137, v137, v138
	ds_read_b128 v[138:141], v0 offset:26624
	v_add_f32_e32 v155, v155, v137
	v_mul_f32_e32 v137, v119, v143
	v_fmac_f32_e32 v137, v118, v142
	v_mul_f32_e32 v142, v117, v145
	v_fmac_f32_e32 v142, v116, v144
	v_add_f32_e32 v137, v137, v142
	v_add_f32_e32 v156, v156, v137
	s_waitcnt lgkmcnt(0)
	v_mul_f32_e32 v137, v115, v139
	v_mul_f32_e32 v142, v95, v141
	v_fmac_f32_e32 v137, v114, v138
	v_fmac_f32_e32 v142, v94, v140
	v_add_f32_e32 v137, v137, v142
	ds_read_b128 v[142:145], v0 offset:30720
	v_add_f32_e32 v157, v157, v137
	v_mul_f32_e32 v137, v119, v139
	v_fmac_f32_e32 v137, v118, v138
	v_mul_f32_e32 v138, v117, v141
	v_fmac_f32_e32 v138, v116, v140
	v_add_f32_e32 v137, v137, v138
	v_add_f32_e32 v158, v158, v137
	s_waitcnt lgkmcnt(0)
	v_mul_f32_e32 v137, v115, v143
	v_mul_f32_e32 v138, v95, v145
	v_fmac_f32_e32 v137, v114, v142
	v_fmac_f32_e32 v138, v94, v144
	v_add_f32_e32 v137, v137, v138
	v_add_f32_e32 v159, v159, v137
	v_mul_f32_e32 v137, v119, v143
	v_mul_f32_e32 v138, v117, v145
	v_fmac_f32_e32 v137, v118, v142
	v_fmac_f32_e32 v138, v116, v144
	v_add_f32_e32 v137, v137, v138
	v_mul_f32_e32 v138, v40, v40
	v_mul_f32_e32 v139, v41, v41
	v_pk_add_f32 v[122:123], v[122:123], v[122:123] op_sel:[0,1] op_sel_hi:[1,0]
	v_pk_add_f32 v[126:127], v[126:127], v[126:127] op_sel:[0,1] op_sel_hi:[1,0]
	v_mov_b32_e32 v123, v138
	v_mov_b32_e32 v127, v139
	v_pk_add_f32 v[122:123], v[122:123], v[126:127]
	v_mul_f32_e32 v126, v49, v49
	v_pk_fma_f32 v[48:49], v[48:49], v[48:49], v[126:127] op_sel_hi:[1,1,0]
	v_mul_f32_e32 v126, v51, v51
	v_mul_f32_e32 v140, v42, v42
	v_mul_f32_e32 v141, v43, v43
	v_pk_fma_f32 v[50:51], v[50:51], v[50:51], v[126:127] op_sel_hi:[1,1,0]
	v_mov_b32_e32 v49, v140
	v_mov_b32_e32 v51, v141
	v_pk_add_f32 v[48:49], v[48:49], v[50:51]
	v_pk_add_f32 v[50:51], v[120:121], v[120:121] op_sel:[0,1] op_sel_hi:[1,0]
	v_pk_add_f32 v[48:49], v[122:123], v[48:49]
	s_waitcnt vmcnt(8)
	v_mul_f32_e32 v122, v36, v36
	v_mul_f32_e32 v123, v37, v37
	v_pk_add_f32 v[120:121], v[124:125], v[124:125] op_sel:[0,1] op_sel_hi:[1,0]
	v_mov_b32_e32 v51, v122
	v_mov_b32_e32 v121, v123
	v_pk_add_f32 v[50:51], v[50:51], v[120:121]
	v_mul_f32_e32 v120, v45, v45
	v_pk_fma_f32 v[44:45], v[44:45], v[44:45], v[120:121] op_sel_hi:[1,1,0]
	v_mul_f32_e32 v120, v47, v47
	v_pk_fma_f32 v[46:47], v[46:47], v[46:47], v[120:121] op_sel_hi:[1,1,0]
	ds_read_b128 v[120:123], v0 offset:3072
	v_mul_f32_e32 v126, v38, v38
	v_mul_f32_e32 v127, v39, v39
	v_mov_b32_e32 v45, v126
	v_mov_b32_e32 v47, v127
	v_pk_mul_f32 v[42:43], v[42:43], v[34:35]
	v_pk_mul_f32 v[40:41], v[40:41], v[32:33]
	ds_read_b128 v[124:127], v0 offset:7168
	v_pk_add_f32 v[44:45], v[44:45], v[46:47]
	s_waitcnt lgkmcnt(1)
	v_mul_f32_e32 v46, v41, v121
	v_mul_f32_e32 v47, v43, v123
	v_pk_mul_f32 v[38:39], v[38:39], v[34:35]
	v_pk_mul_f32 v[36:37], v[36:37], v[32:33]
	v_fmac_f32_e32 v46, v40, v120
	v_fmac_f32_e32 v47, v42, v122
	v_pk_add_f32 v[44:45], v[50:51], v[44:45]
	v_add_f32_e32 v46, v46, v47
	v_mul_f32_e32 v47, v37, v121
	v_mul_f32_e32 v50, v39, v123
	v_fmac_f32_e32 v47, v36, v120
	v_fmac_f32_e32 v50, v38, v122
	v_add_f32_e32 v47, v47, v50
	s_waitcnt lgkmcnt(0)
	v_mul_f32_e32 v50, v41, v125
	v_mul_f32_e32 v51, v43, v127
	v_fmac_f32_e32 v50, v40, v124
	v_fmac_f32_e32 v51, v42, v126
	v_add_f32_e32 v50, v50, v51
	v_mul_f32_e32 v51, v37, v125
	v_fmac_f32_e32 v51, v36, v124
	ds_read_b128 v[122:125], v0 offset:11264
	ds_read_b128 v[138:141], v0 offset:15360
	v_mul_f32_e32 v120, v39, v127
	v_fmac_f32_e32 v120, v38, v126
	v_add_f32_e32 v51, v51, v120
	v_add_f32_e32 v120, v148, v51
	s_waitcnt lgkmcnt(1)
	v_mul_f32_e32 v51, v41, v123
	v_mul_f32_e32 v121, v43, v125
	v_fmac_f32_e32 v51, v40, v122
	v_fmac_f32_e32 v121, v42, v124
	v_add_f32_e32 v51, v51, v121
	v_mul_f32_e32 v121, v37, v123
	v_fmac_f32_e32 v121, v36, v122
	v_mul_f32_e32 v122, v39, v125
	v_fmac_f32_e32 v122, v38, v124
	v_add_f32_e32 v121, v121, v122
	s_waitcnt lgkmcnt(0)
	v_mul_f32_e32 v122, v41, v139
	v_mul_f32_e32 v123, v43, v141
	v_fmac_f32_e32 v122, v40, v138
	v_fmac_f32_e32 v123, v42, v140
	v_add_f32_e32 v122, v122, v123
	v_add_f32_e32 v126, v151, v122
	ds_read_b128 v[122:125], v0 offset:19456
	v_mul_f32_e32 v127, v37, v139
	v_fmac_f32_e32 v127, v36, v138
	v_mul_f32_e32 v138, v39, v141
	v_fmac_f32_e32 v138, v38, v140
	v_add_f32_e32 v127, v127, v138
	s_waitcnt lgkmcnt(0)
	v_mul_f32_e32 v138, v41, v123
	v_mul_f32_e32 v139, v43, v125
	v_fmac_f32_e32 v138, v40, v122
	v_fmac_f32_e32 v139, v42, v124
	v_add_f32_e32 v138, v138, v139
	v_add_f32_e32 v142, v153, v138
	ds_read_b128 v[138:141], v0 offset:23552
	v_mul_f32_e32 v123, v37, v123
	v_fmac_f32_e32 v123, v36, v122
	v_mul_f32_e32 v122, v39, v125
	v_fmac_f32_e32 v122, v38, v124
	v_add_f32_e32 v122, v123, v122
	v_add_f32_e32 v143, v154, v122
	s_waitcnt lgkmcnt(0)
	v_mul_f32_e32 v122, v41, v139
	v_mul_f32_e32 v123, v43, v141
	v_fmac_f32_e32 v122, v40, v138
	v_fmac_f32_e32 v123, v42, v140
	v_add_f32_e32 v122, v122, v123
	v_add_f32_e32 v144, v155, v122
	ds_read_b128 v[122:125], v0 offset:27648
	v_mul_f32_e32 v139, v37, v139
	v_fmac_f32_e32 v139, v36, v138
	v_mul_f32_e32 v138, v39, v141
	v_fmac_f32_e32 v138, v38, v140
	v_add_f32_e32 v138, v139, v138
	v_add_f32_e32 v145, v156, v138
	s_waitcnt lgkmcnt(0)
; #define LAS __attribute__((address_space(3)))
; #define P1_STEP(nn, mask) _Pragma("unroll") for (int i = 0; i < nn; ++i) { const bool up = (lane & mask) != 0; const float keep = up ? v[i + nn] : v[i], send = up ? v[i] : v[i + nn]; v[i] = keep + __shfl_xor(send, mask); }
; __global__ void __launch_bounds__(NTHR, 2) hymba_fwd(Params P) {
;     ...
;                 for (int c = 0; c < 8; ++c) { const f32x4 w = *(const LAS f32x4*)(w8 + c * 1024 + k);
;                     v[c] += (x0[j].x * w.x + x0[j].y * w.y) + (x0[j].z * w.z + x0[j].w * w.w);
;                     v[8 + c] += (x1[j].x * w.x + x1[j].y * w.y) + (x1[j].z * w.z + x1[j].w * w.w); }
;                 asm volatile("" ::: "memory"); }
;             ss0 = wave_sum(ss0); ss1 = wave_sum(ss1);
;     ...
;             P1_STEP(8, 32) P1_STEP(4, 16) P1_STEP(2, 8) P1_STEP(1, 4)
;     ...
;             v[0] += __shfl_xor(v[0], 2); v[0] += __shfl_xor(v[0], 1);
	v_mul_f32_e32 v138, v41, v123
	v_mul_f32_e32 v139, v43, v125
	v_fmac_f32_e32 v138, v40, v122
	v_fmac_f32_e32 v139, v42, v124
	v_add_f32_e32 v138, v138, v139
	v_add_f32_e32 v47, v146, v47
	v_add_f32_e32 v146, v157, v138
	ds_read_b128 v[138:141], v0 offset:31744
	v_mul_f32_e32 v123, v37, v123
	v_mul_f32_e32 v0, v39, v125
	v_fmac_f32_e32 v123, v36, v122
	v_fmac_f32_e32 v0, v38, v124
	v_add_f32_e32 v0, v123, v0
	s_waitcnt lgkmcnt(0)
	v_mul_f32_e32 v122, v41, v139
	v_mul_f32_e32 v123, v43, v141
	v_fmac_f32_e32 v122, v40, v138
	v_fmac_f32_e32 v123, v42, v140
	v_add_f32_e32 v122, v122, v123
	v_mul_f32_e32 v123, v37, v139
	v_mul_f32_e32 v124, v39, v141
	v_fmac_f32_e32 v123, v36, v138
	v_fmac_f32_e32 v124, v38, v140
	v_add_f32_e32 v123, v123, v124
	v_and_b32_e32 v124, 64, v131
	v_add_f32_e32 v137, v160, v137
	v_add_u32_e32 v124, 64, v124
	v_xor_b32_e32 v125, 1, v131
	v_add_f32_e32 v123, v137, v123
	v_cmp_lt_i32_e32 vcc, v125, v124
	v_xor_b32_e32 v137, 2, v131
	v_xor_b32_e32 v138, 4, v131
	v_cndmask_b32_e32 v125, v131, v125, vcc
	v_cmp_lt_i32_e32 vcc, v137, v124
	v_xor_b32_e32 v139, 8, v131
	v_xor_b32_e32 v141, 32, v131
	v_cndmask_b32_e32 v137, v131, v137, vcc
	v_cmp_lt_i32_e32 vcc, v138, v124
	v_add_f32_e32 v46, v161, v46
	v_add_f32_e32 v50, v147, v50
	v_cndmask_b32_e32 v138, v131, v138, vcc
	v_cmp_lt_i32_e32 vcc, v139, v124
	v_cndmask_b32_e64 v147, v46, v47, s[0:1]
	v_cndmask_b32_e64 v46, v47, v46, s[0:1]
	v_cndmask_b32_e32 v139, v131, v139, vcc
	v_cmp_lt_i32_e32 vcc, v141, v124
	v_cndmask_b32_e64 v47, v120, v50, s[0:1]
	v_cndmask_b32_e64 v50, v50, v120, s[0:1]
	v_cndmask_b32_e32 v141, v131, v141, vcc
	v_lshlrev_b32_e32 v141, 2, v141
	ds_bpermute_b32 v50, v141, v50
	v_add_f32_e32 v51, v149, v51
	v_add_f32_e32 v121, v150, v121
	v_xor_b32_e32 v140, 16, v131
	v_cndmask_b32_e64 v120, v51, v121, s[0:1]
	v_add_f32_e32 v127, v152, v127
	v_cmp_lt_i32_e32 vcc, v140, v124
	ds_bpermute_b32 v120, v141, v120
	s_waitcnt lgkmcnt(1)
	v_add_f32_e32 v47, v47, v50
	v_cndmask_b32_e64 v50, v121, v51, s[0:1]
	v_cndmask_b32_e64 v121, v142, v143, s[0:1]
	v_add_f32_e32 v0, v158, v0
	ds_bpermute_b32 v147, v141, v147
	v_cndmask_b32_e32 v124, v131, v140, vcc
	v_cndmask_b32_e64 v140, v126, v127, s[0:1]
	v_cndmask_b32_e64 v51, v127, v126, s[0:1]
	ds_bpermute_b32 v121, v141, v121
	v_cndmask_b32_e64 v126, v144, v145, s[0:1]
	ds_bpermute_b32 v126, v141, v126
	v_cndmask_b32_e64 v127, v146, v0, s[0:1]
	ds_bpermute_b32 v127, v141, v127
	s_waitcnt lgkmcnt(4)
	v_add_f32_e32 v50, v50, v120
	v_cndmask_b32_e64 v120, v143, v142, s[0:1]
	v_add_f32_e32 v122, v159, v122
	s_waitcnt lgkmcnt(3)
	v_add_f32_e32 v46, v46, v147
	s_waitcnt lgkmcnt(2)
	v_add_f32_e32 v120, v120, v121
	v_cndmask_b32_e64 v121, v145, v144, s[0:1]
	v_lshlrev_b32_e32 v124, 2, v124
	s_waitcnt lgkmcnt(1)
	v_add_f32_e32 v121, v121, v126
	v_cndmask_b32_e64 v0, v0, v146, s[0:1]
	v_cndmask_b32_e64 v126, v123, v122, s[0:1]
	v_cndmask_b32_e64 v122, v122, v123, s[0:1]
	v_cndmask_b32_e64 v123, v46, v120, s[4:5]
	s_waitcnt lgkmcnt(0)
	v_add_f32_e32 v0, v0, v127
	ds_bpermute_b32 v123, v124, v123
	v_cndmask_b32_e64 v127, v47, v121, s[4:5]
	ds_bpermute_b32 v127, v124, v127
	v_cndmask_b32_e64 v46, v120, v46, s[4:5]
	v_lshlrev_b32_e32 v125, 2, v125
	s_waitcnt lgkmcnt(1)
	v_add_f32_e32 v120, v46, v123
	v_cndmask_b32_e64 v46, v121, v47, s[4:5]
	s_waitcnt lgkmcnt(0)
	v_add_f32_e32 v121, v46, v127
	v_cndmask_b32_e64 v46, v50, v0, s[4:5]
	ds_bpermute_b32 v123, v124, v46
	v_mov_b32_e32 v46, v44
	v_mov_b32_e32 v47, v48
	v_mov_b32_e32 v48, v45
	ds_bpermute_b32 v140, v141, v140
	ds_bpermute_b32 v122, v141, v122
	v_pk_add_f32 v[44:45], v[46:47], v[48:49]
	ds_bpermute_b32 v47, v125, v45
	ds_bpermute_b32 v46, v125, v44
	s_waitcnt lgkmcnt(3)
	v_add_f32_e32 v51, v51, v140
	s_waitcnt lgkmcnt(2)
	v_add_f32_e32 v122, v126, v122
	v_lshlrev_b32_e32 v137, 2, v137
	v_cndmask_b32_e64 v48, v51, v122, s[4:5]
	s_waitcnt lgkmcnt(0)
	v_pk_add_f32 v[44:45], v[44:45], v[46:47]
	ds_bpermute_b32 v48, v124, v48
	ds_bpermute_b32 v47, v137, v45
	ds_bpermute_b32 v46, v137, v44
	v_cndmask_b32_e64 v0, v0, v50, s[4:5]
	v_add_f32_e32 v0, v0, v123
	v_cndmask_b32_e64 v49, v122, v51, s[4:5]
	v_lshlrev_b32_e32 v138, 2, v138
	v_lshlrev_b32_e32 v139, 2, v139
	s_waitcnt lgkmcnt(2)
	v_add_f32_e32 v48, v49, v48
	v_cndmask_b32_e64 v49, v120, v0, s[6:7]
	s_waitcnt lgkmcnt(0)
	v_pk_add_f32 v[44:45], v[44:45], v[46:47]
	ds_bpermute_b32 v49, v139, v49
	ds_bpermute_b32 v47, v138, v45
	ds_bpermute_b32 v46, v138, v44
	v_cndmask_b32_e64 v0, v0, v120, s[6:7]
	s_mov_b32 s30, 0x3a800000
	s_waitcnt lgkmcnt(2)
	v_add_f32_e32 v0, v0, v49
	v_cndmask_b32_e64 v49, v121, v48, s[6:7]
	s_waitcnt lgkmcnt(0)
	v_pk_add_f32 v[44:45], v[44:45], v[46:47]
	ds_bpermute_b32 v49, v139, v49
	ds_bpermute_b32 v47, v139, v45
	ds_bpermute_b32 v46, v139, v44
	v_cndmask_b32_e64 v48, v48, v121, s[6:7]
	s_ashr_i32 s45, s44, 31
	s_waitcnt lgkmcnt(2)
	v_add_f32_e32 v48, v48, v49
	v_cndmask_b32_e64 v49, v0, v48, s[8:9]
	s_waitcnt lgkmcnt(0)
	v_pk_add_f32 v[44:45], v[44:45], v[46:47]
	ds_bpermute_b32 v47, v124, v45
	ds_bpermute_b32 v46, v124, v44
	ds_bpermute_b32 v49, v138, v49
	v_cndmask_b32_e64 v0, v48, v0, s[8:9]
	s_waitcnt lgkmcnt(1)
	v_pk_add_f32 v[46:47], v[44:45], v[46:47]
	s_waitcnt lgkmcnt(0)
	v_add_f32_e32 v0, v0, v49
	ds_bpermute_b32 v49, v141, v47
	ds_bpermute_b32 v48, v141, v46
	ds_bpermute_b32 v50, v137, v0
	s_waitcnt lgkmcnt(1)
	v_pk_add_f32 v[46:47], v[46:47], v[48:49]
	s_nop 0
	v_pk_fma_f32 v[46:47], v[46:47], s[30:31], v[112:113] op_sel_hi:[1,0,0]
	s_waitcnt lgkmcnt(0)
; __device__ __forceinline__ unsigned pk2(float lo, float hi) { typedef __bf16 bf16x2_t_ __attribute__((ext_vector_type(2))); f32x2 v = {lo, hi}; return __builtin_bit_cast(unsigned, __builtin_convertvector(v, bf16x2_t_)); }
; __global__ void __launch_bounds__(NTHR, 2) hymba_fwd(Params P) {
;     ...
;             const float rs0 = rsqrtf(ss0 * (1.f / DM) + NORM_EPS), rs1 = rsqrtf(ss1 * (1.f / DM) + NORM_EPS);
; #pragma unroll
;             for (int j = 0; j < 4; ++j) { const f32x4 h0 = x0[j] * rs0 + Bk[j], h1 = x1[j] * rs1 + Bk[j];
;                 *((u32x2*)(XN + (size_t)m0 * DM) + lane + 64 * j) = (u32x2){pk2(h0.x, h0.y), pk2(h0.z, h0.w)};
;                 *((u32x2*)(XN + (size_t)(m0 + 1) * DM) + lane + 64 * j) = (u32x2){pk2(h1.x, h1.y), pk2(h1.z, h1.w)}; }
	v_add_f32_e32 v45, v0, v50
	v_mul_f32_e32 v0, 0x4b800000, v47
	v_cmp_gt_f32_e64 s[30:31], s33, v47
	v_cmp_gt_f32_e32 vcc, s33, v46
	v_mul_f32_e32 v44, 0x4b800000, v46
	v_cndmask_b32_e64 v0, v47, v0, s[30:31]
	v_rsq_f32_e32 v0, v0
	v_cndmask_b32_e32 v44, v46, v44, vcc
	v_rsq_f32_e32 v44, v44
	ds_bpermute_b32 v46, v125, v45
	v_mul_f32_e32 v47, 0x45800000, v0
	v_cndmask_b32_e64 v0, v0, v47, s[30:31]
	v_mul_f32_e32 v47, 0x45800000, v44
	s_lshl_b64 s[30:31], s[44:45], 11
	v_cndmask_b32_e32 v44, v44, v47, vcc
	v_lshl_add_u64 v[48:49], v[106:107], 0, s[30:31]
	s_add_i32 s30, s44, 1
	s_ashr_i32 s31, s30, 31
	v_pk_fma_f32 v[2:3], v[44:45], v[2:3], v[6:7] op_sel_hi:[0,1,1]
	v_pk_fma_f32 v[92:93], v[44:45], v[92:93], v[4:5] op_sel_hi:[0,1,1]
	s_lshl_b64 s[30:31], s[30:31], 11
	v_cvt_pk_bf16_f32 v92, v92, v93
	v_cvt_pk_bf16_f32 v93, v2, v3
	v_pk_fma_f32 v[2:3], v[0:1], v[90:91], v[10:11] op_sel_hi:[0,1,1]
	v_pk_fma_f32 v[88:89], v[0:1], v[88:89], v[8:9] op_sel_hi:[0,1,1]
	v_pk_fma_f32 v[86:87], v[44:45], v[86:87], v[10:11] op_sel_hi:[0,1,1]
	v_pk_fma_f32 v[84:85], v[44:45], v[84:85], v[8:9] op_sel_hi:[0,1,1]
	v_lshl_add_u64 v[50:51], v[106:107], 0, s[30:31]
	v_cvt_pk_bf16_f32 v88, v88, v89
	v_cvt_pk_bf16_f32 v89, v2, v3
	v_cvt_pk_bf16_f32 v2, v84, v85
	v_cvt_pk_bf16_f32 v3, v86, v87
	global_store_dwordx2 v[48:49], v[88:89], off offset:512 nt
	global_store_dwordx2 v[50:51], v[2:3], off offset:512 nt
	v_pk_fma_f32 v[2:3], v[0:1], v[94:95], v[14:15] op_sel_hi:[0,1,1]
	v_pk_fma_f32 v[84:85], v[0:1], v[114:115], v[12:13] op_sel_hi:[0,1,1]
	v_pk_fma_f32 v[86:87], v[44:45], v[116:117], v[14:15] op_sel_hi:[0,1,1]
	v_pk_fma_f32 v[88:89], v[44:45], v[118:119], v[12:13] op_sel_hi:[0,1,1]
	v_cvt_pk_bf16_f32 v84, v84, v85
	v_cvt_pk_bf16_f32 v85, v2, v3
	v_cvt_pk_bf16_f32 v2, v88, v89
	v_cvt_pk_bf16_f32 v3, v86, v87
	v_pk_fma_f32 v[98:99], v[0:1], v[98:99], v[6:7] op_sel_hi:[0,1,1]
	v_pk_fma_f32 v[96:97], v[0:1], v[96:97], v[4:5] op_sel_hi:[0,1,1]
	global_store_dwordx2 v[50:51], v[2:3], off offset:1024 nt
	v_pk_fma_f32 v[2:3], v[0:1], v[42:43], v[26:27] op_sel_hi:[0,1,1]
	v_pk_fma_f32 v[40:41], v[0:1], v[40:41], v[24:25] op_sel_hi:[0,1,1]
	v_pk_fma_f32 v[38:39], v[44:45], v[38:39], v[26:27] op_sel_hi:[0,1,1]
	v_pk_fma_f32 v[36:37], v[44:45], v[36:37], v[24:25] op_sel_hi:[0,1,1]
	v_cvt_pk_bf16_f32 v96, v96, v97
	v_cvt_pk_bf16_f32 v97, v98, v99
	v_cvt_pk_bf16_f32 v40, v40, v41
	v_cvt_pk_bf16_f32 v41, v2, v3
	v_cvt_pk_bf16_f32 v2, v36, v37
	v_cvt_pk_bf16_f32 v3, v38, v39
	global_store_dwordx2 v[48:49], v[96:97], off nt
	global_store_dwordx2 v[50:51], v[92:93], off nt
	global_store_dwordx2 v[48:49], v[84:85], off offset:1024 nt
	global_store_dwordx2 v[48:49], v[40:41], off offset:1536 nt
	global_store_dwordx2 v[50:51], v[2:3], off offset:1536 nt
	s_and_saveexec_b64 s[30:31], s[10:11]
	s_cbranch_execz .LBB0_142
; #define LFS WSP(float, WS_LFS)
; __global__ void __launch_bounds__(NTHR, 2) hymba_fwd(Params P) {
;     ...
;             if ((lane & 3) == 0) { const int r = lane >> 5, c = (lane >> 2) & 7, m = m0 + r;
;                 const float z = (r ? rs1 : rs0) * v[0] + bsel; const float lf = fminf(z, 0.f) - log1pf(__expf(-fabsf(z)));
;                 if (m < PT) out[O_LFP + (size_t)m * NH + c] = lf;
;                 else { const int sidx = m - PT, b = sidx >> 6, t = sidx & 63; out[O_LFS + (size_t)sidx * NH + c] = lf; LFS[(size_t)(b * SKV + PAST + t) * NH + c] = lf; } }
	s_waitcnt lgkmcnt(0)
	v_add_f32_e32 v2, v45, v46
	v_cndmask_b32_e64 v0, v44, v0, s[12:13]
	v_fma_f32 v0, v0, v2, v136
	s_mov_b32 s45, 0xbfb8aa3b
	v_mul_f32_e64 v2, |v0|, s45
	v_exp_f32_e32 v3, v2
	s_mov_b32 s45, 0x3f2aaaab
	v_add_u32_e32 v2, s44, v103
	v_min_f32_e32 v0, 0, v0
	v_add_f32_e32 v38, 1.0, v3
	v_add_f32_e32 v36, -1.0, v38
	v_sub_f32_e32 v37, v36, v38
	v_add_f32_e32 v37, 1.0, v37
	v_sub_f32_e32 v36, v3, v36
	v_add_f32_e32 v39, v36, v37
	v_frexp_mant_f32_e32 v40, v38
	v_cvt_f64_f32_e32 v[36:37], v38
	v_frexp_exp_i32_f64_e32 v36, v[36:37]
	v_cmp_gt_f32_e32 vcc, s45, v40
	s_mov_b32 s45, 0x3f317218
	s_nop 0
	v_subbrev_co_u32_e32 v36, vcc, 0, v36, vcc
	v_sub_u32_e32 v37, 0, v36
	v_ldexp_f32 v38, v38, v37
	v_ldexp_f32 v37, v39, v37
	v_add_f32_e32 v39, -1.0, v38
	v_add_f32_e32 v42, 1.0, v38
	v_add_f32_e32 v40, 1.0, v39
	v_add_f32_e32 v43, -1.0, v42
	v_sub_f32_e32 v40, v38, v40
	v_sub_f32_e32 v38, v38, v43
	v_add_f32_e32 v40, v37, v40
	v_add_f32_e32 v37, v37, v38
	v_add_f32_e32 v38, v42, v37
	v_rcp_f32_e32 v43, v38
	v_add_f32_e32 v41, v39, v40
	v_sub_f32_e32 v39, v41, v39
	v_sub_f32_e32 v39, v40, v39
	v_sub_f32_e32 v40, v38, v42
	v_sub_f32_e32 v37, v37, v40
	v_mul_f32_e32 v40, v41, v43
	v_mul_f32_e32 v42, v38, v40
	v_fma_f32 v44, v40, v38, -v42
	v_fmac_f32_e32 v44, v40, v37
	v_add_f32_e32 v45, v42, v44
	v_sub_f32_e32 v46, v41, v45
	v_sub_f32_e32 v41, v41, v46
	v_sub_f32_e32 v42, v45, v42
	v_sub_f32_e32 v41, v41, v45
	v_add_f32_e32 v39, v39, v41
	v_sub_f32_e32 v41, v42, v44
	v_add_f32_e32 v39, v41, v39
	v_add_f32_e32 v41, v46, v39
	v_mul_f32_e32 v42, v43, v41
	v_mul_f32_e32 v44, v38, v42
	v_fma_f32 v38, v42, v38, -v44
	v_fmac_f32_e32 v38, v42, v37
	v_sub_f32_e32 v37, v46, v41
	v_add_f32_e32 v37, v39, v37
	v_add_f32_e32 v39, v44, v38
	v_sub_f32_e32 v45, v41, v39
	v_sub_f32_e32 v41, v41, v45
	v_sub_f32_e32 v44, v39, v44
	v_sub_f32_e32 v39, v41, v39
	v_add_f32_e32 v37, v37, v39
	v_sub_f32_e32 v38, v44, v38
	v_cvt_f32_i32_e32 v36, v36
	v_add_f32_e32 v37, v38, v37
	v_add_f32_e32 v38, v40, v42
	v_add_f32_e32 v37, v45, v37
	v_sub_f32_e32 v39, v38, v40
	v_mul_f32_e32 v37, v43, v37
	v_sub_f32_e32 v39, v42, v39
	v_add_f32_e32 v37, v39, v37
	v_mul_f32_e32 v42, 0x3f317218, v36
	v_add_f32_e32 v39, v38, v37
	v_fma_f32 v43, v36, s45, -v42
	v_mul_f32_e32 v40, v39, v39
	v_fmac_f32_e32 v43, 0xb102e308, v36
	v_sub_f32_e32 v36, v39, v38
	v_fmamk_f32 v41, v40, 0x3e9b6dac, v132
	v_sub_f32_e32 v36, v37, v36
	v_add_f32_e32 v37, v42, v43
	v_fmaak_f32 v41, v40, v41, 0x3f2aaada
	v_sub_f32_e32 v38, v37, v42
	v_ldexp_f32 v42, v39, 1
	v_mul_f32_e32 v39, v39, v40
	v_mul_f32_e32 v39, v39, v41
	v_add_f32_e32 v40, v42, v39
	v_sub_f32_e32 v41, v40, v42
	v_ldexp_f32 v36, v36, 1
	v_sub_f32_e32 v39, v39, v41
	v_add_f32_e32 v36, v36, v39
	v_add_f32_e32 v39, v40, v36
	v_sub_f32_e32 v40, v39, v40
	v_sub_f32_e32 v36, v36, v40
	v_add_f32_e32 v40, v37, v39
	v_sub_f32_e32 v41, v40, v37
	v_sub_f32_e32 v42, v40, v41
	v_sub_f32_e32 v38, v43, v38
	v_sub_f32_e32 v37, v37, v42
	v_sub_f32_e32 v39, v39, v41
	v_add_f32_e32 v37, v39, v37
	v_add_f32_e32 v39, v38, v36
	v_sub_f32_e32 v41, v39, v38
	v_sub_f32_e32 v42, v39, v41
	v_sub_f32_e32 v38, v38, v42
	v_sub_f32_e32 v36, v36, v41
	v_add_f32_e32 v37, v39, v37
	v_add_f32_e32 v36, v36, v38
	v_add_f32_e32 v38, v40, v37
	v_sub_f32_e32 v39, v38, v40
	v_sub_f32_e32 v37, v37, v39
	v_add_f32_e32 v36, v36, v37
	s_mov_b32 s45, 0x7f800000
	v_add_f32_e32 v36, v38, v36
	v_cmp_neq_f32_e32 vcc, s45, v3
	s_mov_b32 s45, 0x33800000
	s_nop 0
	v_cndmask_b32_e32 v36, v133, v36, vcc
	v_cmp_ngt_f32_e32 vcc, -1.0, v3
	s_nop 1
	v_cndmask_b32_e32 v36, v134, v36, vcc
	v_cmp_neq_f32_e32 vcc, -1.0, v3
	s_nop 1
	v_cndmask_b32_e32 v36, v135, v36, vcc
	v_cmp_lt_f32_e64 vcc, |v3|, s45
	s_nop 1
	v_cndmask_b32_e32 v3, v36, v3, vcc
	v_sub_f32_e32 v36, v0, v3
	v_cmp_lt_i32_e32 vcc, s34, v2
	v_lshlrev_b32_e32 v0, 2, v102
	s_and_saveexec_b64 s[52:53], vcc
	s_xor_b64 s[60:61], exec, s[52:53]
	s_cbranch_execz .LBB0_148
	v_add_u32_e32 v38, 0xffff0000, v2
	v_mov_b32_e32 v39, v1
	v_lshrrev_b32_e32 v3, 6, v38
	v_lshlrev_b64 v[38:39], 5, v[38:39]
	v_lshl_add_u64 v[38:39], s[90:91], 0, v[38:39]
	v_lshl_add_u64 v[38:39], v[38:39], 0, v[0:1]
	v_mul_lo_u32 v0, v3, s35
	v_and_or_b32 v0, v2, 63, v0
	v_add_u32_e32 v0, 0x800, v0
	v_add_co_u32_e32 v38, vcc, 0x20620000, v38
	v_lshlrev_b64 v[2:3], 5, v[0:1]
	s_nop 0
	v_addc_co_u32_e32 v39, vcc, 0, v39, vcc
	v_lshl_add_u64 v[2:3], v[108:109], 0, v[2:3]
	global_store_dword v[38:39], v36, off nt
	global_store_dword v[2:3], v36, off nt
.LBB0_148:
	s_andn2_saveexec_b64 s[52:53], s[60:61]
	s_cbranch_execz .LBB0_142
	v_ashrrev_i32_e32 v3, 31, v2
	v_lshlrev_b64 v[2:3], 5, v[2:3]
	v_lshl_add_u64 v[2:3], s[90:91], 0, v[2:3]
	v_lshl_add_u64 v[2:3], v[2:3], 0, v[0:1]
	v_add_co_u32_e32 v2, vcc, 0x20200000, v2
	s_nop 1
	v_addc_co_u32_e32 v3, vcc, 0, v3, vcc
	global_store_dword v[2:3], v36, off nt
	s_branch .LBB0_142

; __host__ __device__ __forceinline__ size_t ys_off(int m, int ch) { return ((size_t)(ch >> 4) * PT + m) * 16 + (ch & 15); }
; __device__ __forceinline__ unsigned pk2(float lo, float hi) { typedef __bf16 bf16x2_t_ __attribute__((ext_vector_type(2))); f32x2 v = {lo, hi}; return __builtin_bit_cast(unsigned, __builtin_convertvector(v, bf16x2_t_)); }
; __device__ __forceinline__ float gelu_tanh(float x) { const float z = 0.7978845608028654f * (x + 0.044715f * x * x * x); return x * __builtin_amdgcn_rcpf(1.f + __expf(-2.f * z)); }
;     __device__ __forceinline__ void operator()(const f32x4 (&acc)[2][2][4][2], const pg8::Unit& u, int wr, int wc, int fr, int fq) const {
;     ...
; #pragma unroll
;                 for (int bj = 0; bj < 2; ++bj) {
;                     const int t = 8 * bj + 2 * wc + (fq >> 1), p0 = 8 * (fq & 1);
;                     const f32x4 a = acc[ai][bj][m][0], b = acc[ai][bj][m][1];
;                     u32x4 w; w.x = pk2(gelu_tanh(a[0]), gelu_tanh(a[1])); w.y = pk2(gelu_tanh(a[2]), gelu_tanh(a[3])); w.z = pk2(gelu_tanh(b[0]), gelu_tanh(b[1])); w.w = pk2(gelu_tanh(b[2]), gelu_tanh(b[3]));
;                     *(u32x4*)(YS_ + ys_off(row * CL + t, u.g * 16 + p0)) = w;
;                 }
.LBB0_904:
	v_mul_f32_e32 v138, 0x3d372713, v124
	v_mul_f32_e32 v138, v124, v138
	v_mul_f32_e32 v139, 0x3d372713, v125
	v_fma_f32 v138, v124, v138, v124
	v_mul_f32_e32 v139, v125, v139
	v_mul_f32_e32 v138, 0x3f4c422a, v138
	v_fma_f32 v139, v125, v139, v125
	v_mul_f32_e32 v138, -2.0, v138
	v_mul_f32_e32 v139, 0x3f4c422a, v139
	v_mul_f32_e32 v138, 0x3fb8aa3b, v138
	v_mul_f32_e32 v139, -2.0, v139
	v_exp_f32_e32 v138, v138
	v_mul_f32_e32 v139, 0x3fb8aa3b, v139
	v_exp_f32_e32 v139, v139
	s_ashr_i32 s17, s16, 31
	v_add_f32_e32 v138, 1.0, v138
	v_rcp_f32_e32 v142, v138
	v_add_f32_e32 v138, 1.0, v139
	v_rcp_f32_e32 v143, v138
	v_mul_f32_e32 v139, 0x3d372713, v126
	v_mul_f32_e32 v139, v126, v139
	v_fma_f32 v139, v126, v139, v126
	v_pk_mul_f32 v[124:125], v[124:125], v[142:143]
	v_mul_f32_e32 v142, 0x3d372713, v127
	v_mul_f32_e32 v142, v127, v142
	v_mul_f32_e32 v139, 0x3f4c422a, v139
	v_fma_f32 v142, v127, v142, v127
	v_mul_f32_e32 v139, -2.0, v139
	v_mul_f32_e32 v142, 0x3f4c422a, v142
	v_mul_f32_e32 v139, 0x3fb8aa3b, v139
	v_mul_f32_e32 v142, -2.0, v142
	v_exp_f32_e32 v139, v139
	v_mul_f32_e32 v142, 0x3fb8aa3b, v142
	v_exp_f32_e32 v143, v142
	v_cvt_pk_bf16_f32 v124, v124, v125
	v_add_f32_e32 v125, 1.0, v139
	v_rcp_f32_e32 v142, v125
	v_add_f32_e32 v125, 1.0, v143
	v_rcp_f32_e32 v143, v125
	v_mul_f32_e32 v125, 0x3d372713, v120
	v_mul_f32_e32 v125, v120, v125
	v_mul_f32_e32 v139, 0x3d372713, v121
	v_fma_f32 v125, v120, v125, v120
	v_mul_f32_e32 v139, v121, v139
	v_mul_f32_e32 v125, 0x3f4c422a, v125
	v_fma_f32 v139, v121, v139, v121
	v_mul_f32_e32 v125, -2.0, v125
	v_mul_f32_e32 v139, 0x3f4c422a, v139
	v_mul_f32_e32 v125, 0x3fb8aa3b, v125
	v_mul_f32_e32 v139, -2.0, v139
	v_exp_f32_e32 v125, v125
	v_mul_f32_e32 v139, 0x3fb8aa3b, v139
	v_exp_f32_e32 v139, v139
	v_pk_mul_f32 v[126:127], v[126:127], v[142:143]
	v_add_f32_e32 v125, 1.0, v125
	v_rcp_f32_e32 v142, v125
	v_add_f32_e32 v125, 1.0, v139
	v_mul_f32_e32 v139, 0x3d372713, v122
	v_mul_f32_e32 v139, v122, v139
	v_mul_f32_e32 v143, 0x3d372713, v123
	v_fma_f32 v139, v122, v139, v122
	v_mul_f32_e32 v143, v123, v143
	v_mul_f32_e32 v139, 0x3f4c422a, v139
	v_fma_f32 v143, v123, v143, v123
	v_mul_f32_e32 v139, -2.0, v139
	v_mul_f32_e32 v143, 0x3f4c422a, v143
	v_mul_f32_e32 v139, 0x3fb8aa3b, v139
	v_mul_f32_e32 v143, -2.0, v143
	v_exp_f32_e32 v139, v139
	v_mul_f32_e32 v143, 0x3fb8aa3b, v143
	v_exp_f32_e32 v153, v143
	v_rcp_f32_e32 v143, v125
	v_add_f32_e32 v125, 1.0, v139
	v_rcp_f32_e32 v152, v125
	v_add_f32_e32 v125, 1.0, v153
	v_rcp_f32_e32 v153, v125
	v_pk_mul_f32 v[120:121], v[120:121], v[142:143]
	v_cvt_pk_bf16_f32 v125, v126, v127
	v_cvt_pk_bf16_f32 v126, v120, v121
	v_pk_mul_f32 v[120:121], v[122:123], v[152:153]
	v_lshl_add_u32 v151, s88, 12, v146
	v_cvt_pk_bf16_f32 v127, v120, v121
	v_mul_f32_e32 v120, 0x3d372713, v116
	v_mul_f32_e32 v120, v116, v120
	v_fma_f32 v120, v116, v120, v116
	v_mul_f32_e32 v120, 0x3f4c422a, v120
	v_mul_f32_e32 v120, -2.0, v120
	v_mul_f32_e32 v120, 0x3fb8aa3b, v120
	v_exp_f32_e32 v122, v120
	v_mul_f32_e32 v120, 0x3d372713, v117
	v_mul_f32_e32 v120, v117, v120
	v_fma_f32 v120, v117, v120, v117
	v_mul_f32_e32 v120, 0x3f4c422a, v120
	s_lshl_b64 s[16:17], s[16:17], 21
	v_or_b32_e32 v138, v151, v141
	v_mul_f32_e32 v120, -2.0, v120
	v_ashrrev_i32_e32 v139, 31, v138
	s_add_u32 s16, s4, s16
	v_mul_f32_e32 v120, 0x3fb8aa3b, v120
	s_addc_u32 s17, s5, s17
	v_exp_f32_e32 v123, v120
	v_lshlrev_b64 v[120:121], 5, v[138:139]
	v_lshl_add_u64 v[120:121], s[16:17], 0, v[120:121]
	v_lshl_add_u64 v[120:121], v[120:121], 0, v[136:137]
	global_store_dwordx4 v[120:121], v[124:127], off nt
	v_mul_f32_e32 v120, 0x3d372713, v118
	v_mul_f32_e32 v120, v118, v120
	v_mul_f32_e32 v121, 0x3d372713, v119
	v_fma_f32 v120, v118, v120, v118
	v_mul_f32_e32 v121, v119, v121
	v_mul_f32_e32 v120, 0x3f4c422a, v120
	v_fma_f32 v121, v119, v121, v119
	v_add_f32_e32 v122, 1.0, v122
	v_add_f32_e32 v123, 1.0, v123
	v_mul_f32_e32 v120, -2.0, v120
	v_mul_f32_e32 v121, 0x3f4c422a, v121
	v_rcp_f32_e32 v122, v122
	v_rcp_f32_e32 v123, v123
	v_mul_f32_e32 v120, 0x3fb8aa3b, v120
	v_mul_f32_e32 v121, -2.0, v121
	v_exp_f32_e32 v120, v120
	v_mul_f32_e32 v121, 0x3fb8aa3b, v121
	v_exp_f32_e32 v121, v121
	v_pk_mul_f32 v[116:117], v[116:117], v[122:123]
	v_mul_f32_e32 v122, 0x3d372713, v113
	v_cvt_pk_bf16_f32 v116, v116, v117
	v_add_f32_e32 v117, 1.0, v120
	v_rcp_f32_e32 v120, v117
	v_add_f32_e32 v117, 1.0, v121
	v_rcp_f32_e32 v121, v117
	v_mul_f32_e32 v117, 0x3d372713, v112
	v_mul_f32_e32 v117, v112, v117
	v_fma_f32 v117, v112, v117, v112
	v_mul_f32_e32 v122, v113, v122
	v_mul_f32_e32 v117, 0x3f4c422a, v117
	v_fma_f32 v122, v113, v122, v113
	v_mul_f32_e32 v117, -2.0, v117
	v_mul_f32_e32 v122, 0x3f4c422a, v122
	v_mul_f32_e32 v117, 0x3fb8aa3b, v117
	v_mul_f32_e32 v122, -2.0, v122
	v_pk_mul_f32 v[118:119], v[118:119], v[120:121]
	v_mul_f32_e32 v121, 0x3d372713, v114
	v_exp_f32_e32 v117, v117
	v_mul_f32_e32 v122, 0x3fb8aa3b, v122
	v_mul_f32_e32 v121, v114, v121
	v_exp_f32_e32 v122, v122
	v_fma_f32 v121, v114, v121, v114
	v_mul_f32_e32 v121, 0x3f4c422a, v121
	v_mul_f32_e32 v121, -2.0, v121
	v_add_f32_e32 v117, 1.0, v117
	v_mul_f32_e32 v121, 0x3fb8aa3b, v121
	v_rcp_f32_e32 v120, v117
	v_add_f32_e32 v117, 1.0, v122
	v_exp_f32_e32 v122, v121
	v_mul_f32_e32 v121, 0x3d372713, v115
	v_mul_f32_e32 v121, v115, v121
	v_fma_f32 v121, v115, v121, v115
	v_mul_f32_e32 v121, 0x3f4c422a, v121
	v_mul_f32_e32 v121, -2.0, v121
	v_mul_f32_e32 v121, 0x3fb8aa3b, v121
	v_exp_f32_e32 v123, v121
	v_rcp_f32_e32 v121, v117
	v_add_f32_e32 v117, 1.0, v122
	v_rcp_f32_e32 v122, v117
	v_add_f32_e32 v117, 1.0, v123
	v_rcp_f32_e32 v123, v117
	v_pk_mul_f32 v[112:113], v[112:113], v[120:121]
; __host__ __device__ __forceinline__ size_t ys_off(int m, int ch) { return ((size_t)(ch >> 4) * PT + m) * 16 + (ch & 15); }
; __device__ __forceinline__ unsigned pk2(float lo, float hi) { typedef __bf16 bf16x2_t_ __attribute__((ext_vector_type(2))); f32x2 v = {lo, hi}; return __builtin_bit_cast(unsigned, __builtin_convertvector(v, bf16x2_t_)); }
; __device__ __forceinline__ float gelu_tanh(float x) { const float z = 0.7978845608028654f * (x + 0.044715f * x * x * x); return x * __builtin_amdgcn_rcpf(1.f + __expf(-2.f * z)); }
;     __device__ __forceinline__ void operator()(const f32x4 (&acc)[2][2][4][2], const pg8::Unit& u, int wr, int wc, int fr, int fq) const {
;     ...
; #pragma unroll
;                 for (int bj = 0; bj < 2; ++bj) {
;                     const int t = 8 * bj + 2 * wc + (fq >> 1), p0 = 8 * (fq & 1);
;                     const f32x4 a = acc[ai][bj][m][0], b = acc[ai][bj][m][1];
;                     u32x4 w; w.x = pk2(gelu_tanh(a[0]), gelu_tanh(a[1])); w.y = pk2(gelu_tanh(a[2]), gelu_tanh(a[3])); w.z = pk2(gelu_tanh(b[0]), gelu_tanh(b[1])); w.w = pk2(gelu_tanh(b[2]), gelu_tanh(b[3]));
;                     *(u32x4*)(YS_ + ys_off(row * CL + t, u.g * 16 + p0)) = w;
;                 }
	v_cvt_pk_bf16_f32 v117, v118, v119
	v_cvt_pk_bf16_f32 v118, v112, v113
	v_pk_mul_f32 v[112:113], v[114:115], v[122:123]
	v_mul_f32_e32 v114, 0x3d372713, v108
	v_mul_f32_e32 v115, 0x3d372713, v109
	v_mul_f32_e32 v114, v108, v114
	v_mul_f32_e32 v115, v109, v115
	v_fma_f32 v114, v108, v114, v108
	v_fma_f32 v115, v109, v115, v109
	v_mul_f32_e32 v114, 0x3f4c422a, v114
	v_mul_f32_e32 v115, 0x3f4c422a, v115
	v_mul_f32_e32 v114, -2.0, v114
	v_mul_f32_e32 v115, -2.0, v115
	v_mul_f32_e32 v114, 0x3fb8aa3b, v114
	v_mul_f32_e32 v115, 0x3fb8aa3b, v115
	v_exp_f32_e32 v114, v114
	v_exp_f32_e32 v115, v115
	v_cvt_pk_bf16_f32 v119, v112, v113
	v_or_b32_e32 v112, 8, v138
	v_ashrrev_i32_e32 v113, 31, v112
	v_add_f32_e32 v114, 1.0, v114
	v_add_f32_e32 v115, 1.0, v115
	v_lshlrev_b64 v[112:113], 5, v[112:113]
	v_rcp_f32_e32 v114, v114
	v_rcp_f32_e32 v115, v115
	v_lshl_add_u64 v[112:113], s[16:17], 0, v[112:113]
	v_lshl_add_u64 v[112:113], v[112:113], 0, v[136:137]
	global_store_dwordx4 v[112:113], v[116:119], off nt
	v_mul_f32_e32 v113, 0x3d372713, v110
	v_pk_mul_f32 v[108:109], v[108:109], v[114:115]
	v_mul_f32_e32 v113, v110, v113
	v_mul_f32_e32 v114, 0x3d372713, v111
	v_fma_f32 v113, v110, v113, v110
	v_mul_f32_e32 v114, v111, v114
	v_mul_f32_e32 v113, 0x3f4c422a, v113
	v_fma_f32 v114, v111, v114, v111
	v_mul_f32_e32 v113, -2.0, v113
	v_mul_f32_e32 v114, 0x3f4c422a, v114
	v_mul_f32_e32 v113, 0x3fb8aa3b, v113
	v_mul_f32_e32 v114, -2.0, v114
	v_exp_f32_e32 v113, v113
	v_mul_f32_e32 v114, 0x3fb8aa3b, v114
	v_exp_f32_e32 v115, v114
	v_cvt_pk_bf16_f32 v108, v108, v109
	v_add_f32_e32 v109, 1.0, v113
	v_rcp_f32_e32 v114, v109
	v_add_f32_e32 v109, 1.0, v115
	v_rcp_f32_e32 v115, v109
	v_mul_f32_e32 v109, 0x3d372713, v104
	v_mul_f32_e32 v109, v104, v109
	v_mul_f32_e32 v113, 0x3d372713, v105
	v_fma_f32 v109, v104, v109, v104
	v_mul_f32_e32 v113, v105, v113
	v_mul_f32_e32 v109, 0x3f4c422a, v109
	v_fma_f32 v113, v105, v113, v105
	v_mul_f32_e32 v109, -2.0, v109
	v_mul_f32_e32 v113, 0x3f4c422a, v113
	v_mul_f32_e32 v109, 0x3fb8aa3b, v109
	v_mul_f32_e32 v113, -2.0, v113
	v_exp_f32_e32 v109, v109
	v_mul_f32_e32 v113, 0x3fb8aa3b, v113
	v_exp_f32_e32 v113, v113
	v_pk_mul_f32 v[110:111], v[110:111], v[114:115]
	v_add_f32_e32 v109, 1.0, v109
	v_rcp_f32_e32 v114, v109
	v_add_f32_e32 v109, 1.0, v113
	v_mul_f32_e32 v113, 0x3d372713, v106
	v_mul_f32_e32 v113, v106, v113
	v_mul_f32_e32 v115, 0x3d372713, v107
	v_fma_f32 v113, v106, v113, v106
	v_mul_f32_e32 v115, v107, v115
	v_mul_f32_e32 v113, 0x3f4c422a, v113
	v_fma_f32 v115, v107, v115, v107
	v_mul_f32_e32 v113, -2.0, v113
	v_mul_f32_e32 v115, 0x3f4c422a, v115
	v_mul_f32_e32 v113, 0x3fb8aa3b, v113
	v_mul_f32_e32 v115, -2.0, v115
	v_exp_f32_e32 v113, v113
	v_mul_f32_e32 v115, 0x3fb8aa3b, v115
	v_exp_f32_e32 v117, v115
	v_rcp_f32_e32 v115, v109
	v_add_f32_e32 v109, 1.0, v113
	v_rcp_f32_e32 v116, v109
	v_add_f32_e32 v109, 1.0, v117
	v_rcp_f32_e32 v117, v109
	v_pk_mul_f32 v[104:105], v[104:105], v[114:115]
	v_cvt_pk_bf16_f32 v109, v110, v111
	v_cvt_pk_bf16_f32 v110, v104, v105
	v_pk_mul_f32 v[104:105], v[106:107], v[116:117]
	v_or_b32_e32 v112, 0x100, v138
	v_cvt_pk_bf16_f32 v111, v104, v105
	v_mul_f32_e32 v104, 0x3d372713, v100
	v_mul_f32_e32 v104, v100, v104
	v_fma_f32 v104, v100, v104, v100
	v_mul_f32_e32 v104, 0x3f4c422a, v104
	v_mul_f32_e32 v104, -2.0, v104
	v_mul_f32_e32 v104, 0x3fb8aa3b, v104
	v_exp_f32_e32 v106, v104
	v_mul_f32_e32 v104, 0x3d372713, v101
	v_mul_f32_e32 v104, v101, v104
	v_fma_f32 v104, v101, v104, v101
	v_mul_f32_e32 v104, 0x3f4c422a, v104
	v_mul_f32_e32 v104, -2.0, v104
	v_ashrrev_i32_e32 v113, 31, v112
	v_mul_f32_e32 v104, 0x3fb8aa3b, v104
	v_exp_f32_e32 v107, v104
	v_lshlrev_b64 v[104:105], 5, v[112:113]
	v_lshl_add_u64 v[104:105], s[16:17], 0, v[104:105]
	v_lshl_add_u64 v[104:105], v[104:105], 0, v[136:137]
	global_store_dwordx4 v[104:105], v[108:111], off nt
	v_mul_f32_e32 v104, 0x3d372713, v102
	v_mul_f32_e32 v104, v102, v104
	v_mul_f32_e32 v105, 0x3d372713, v103
	v_fma_f32 v104, v102, v104, v102
	v_mul_f32_e32 v105, v103, v105
	v_mul_f32_e32 v104, 0x3f4c422a, v104
	v_fma_f32 v105, v103, v105, v103
	v_add_f32_e32 v106, 1.0, v106
	v_add_f32_e32 v107, 1.0, v107
	v_mul_f32_e32 v104, -2.0, v104
	v_mul_f32_e32 v105, 0x3f4c422a, v105
	v_rcp_f32_e32 v106, v106
	v_rcp_f32_e32 v107, v107
	v_mul_f32_e32 v104, 0x3fb8aa3b, v104
	v_mul_f32_e32 v105, -2.0, v105
	v_exp_f32_e32 v104, v104
	v_mul_f32_e32 v105, 0x3fb8aa3b, v105
	v_exp_f32_e32 v105, v105
	v_pk_mul_f32 v[100:101], v[100:101], v[106:107]
	v_mul_f32_e32 v106, 0x3d372713, v97
	v_cvt_pk_bf16_f32 v100, v100, v101
	v_add_f32_e32 v101, 1.0, v104
	v_rcp_f32_e32 v104, v101
	v_add_f32_e32 v101, 1.0, v105
	v_rcp_f32_e32 v105, v101
	v_mul_f32_e32 v101, 0x3d372713, v96
	v_mul_f32_e32 v101, v96, v101
	v_fma_f32 v101, v96, v101, v96
	v_mul_f32_e32 v106, v97, v106
	v_mul_f32_e32 v101, 0x3f4c422a, v101
	v_fma_f32 v106, v97, v106, v97
	v_mul_f32_e32 v101, -2.0, v101
	v_mul_f32_e32 v106, 0x3f4c422a, v106
	v_mul_f32_e32 v101, 0x3fb8aa3b, v101
	v_mul_f32_e32 v106, -2.0, v106
	v_pk_mul_f32 v[102:103], v[102:103], v[104:105]
	v_mul_f32_e32 v105, 0x3d372713, v98
	v_exp_f32_e32 v101, v101
	v_mul_f32_e32 v106, 0x3fb8aa3b, v106
	v_mul_f32_e32 v105, v98, v105
	v_exp_f32_e32 v106, v106
	v_fma_f32 v105, v98, v105, v98
	v_mul_f32_e32 v105, 0x3f4c422a, v105
	v_mul_f32_e32 v105, -2.0, v105
	v_add_f32_e32 v101, 1.0, v101
	v_mul_f32_e32 v105, 0x3fb8aa3b, v105
	v_rcp_f32_e32 v104, v101
	v_add_f32_e32 v101, 1.0, v106
	v_exp_f32_e32 v106, v105
	v_mul_f32_e32 v105, 0x3d372713, v99
	v_mul_f32_e32 v105, v99, v105
	v_fma_f32 v105, v99, v105, v99
	v_mul_f32_e32 v105, 0x3f4c422a, v105
; __host__ __device__ __forceinline__ size_t ys_off(int m, int ch) { return ((size_t)(ch >> 4) * PT + m) * 16 + (ch & 15); }
; __device__ __forceinline__ unsigned pk2(float lo, float hi) { typedef __bf16 bf16x2_t_ __attribute__((ext_vector_type(2))); f32x2 v = {lo, hi}; return __builtin_bit_cast(unsigned, __builtin_convertvector(v, bf16x2_t_)); }
; __device__ __forceinline__ float gelu_tanh(float x) { const float z = 0.7978845608028654f * (x + 0.044715f * x * x * x); return x * __builtin_amdgcn_rcpf(1.f + __expf(-2.f * z)); }
;     __device__ __forceinline__ void operator()(const f32x4 (&acc)[2][2][4][2], const pg8::Unit& u, int wr, int wc, int fr, int fq) const {
;     ...
; #pragma unroll
;                 for (int bj = 0; bj < 2; ++bj) {
;                     const int t = 8 * bj + 2 * wc + (fq >> 1), p0 = 8 * (fq & 1);
;                     const f32x4 a = acc[ai][bj][m][0], b = acc[ai][bj][m][1];
;                     u32x4 w; w.x = pk2(gelu_tanh(a[0]), gelu_tanh(a[1])); w.y = pk2(gelu_tanh(a[2]), gelu_tanh(a[3])); w.z = pk2(gelu_tanh(b[0]), gelu_tanh(b[1])); w.w = pk2(gelu_tanh(b[2]), gelu_tanh(b[3]));
;                     *(u32x4*)(YS_ + ys_off(row * CL + t, u.g * 16 + p0)) = w;
;                 }
	v_mul_f32_e32 v105, -2.0, v105
	v_mul_f32_e32 v105, 0x3fb8aa3b, v105
	v_exp_f32_e32 v107, v105
	v_rcp_f32_e32 v105, v101
	v_add_f32_e32 v101, 1.0, v106
	v_rcp_f32_e32 v106, v101
	v_add_f32_e32 v101, 1.0, v107
	v_rcp_f32_e32 v107, v101
	v_pk_mul_f32 v[96:97], v[96:97], v[104:105]
	v_cvt_pk_bf16_f32 v101, v102, v103
	v_cvt_pk_bf16_f32 v102, v96, v97
	v_pk_mul_f32 v[96:97], v[98:99], v[106:107]
	v_mul_f32_e32 v98, 0x3d372713, v92
	v_mul_f32_e32 v99, 0x3d372713, v93
	v_mul_f32_e32 v98, v92, v98
	v_mul_f32_e32 v99, v93, v99
	v_fma_f32 v98, v92, v98, v92
	v_fma_f32 v99, v93, v99, v93
	v_mul_f32_e32 v98, 0x3f4c422a, v98
	v_mul_f32_e32 v99, 0x3f4c422a, v99
	v_mul_f32_e32 v98, -2.0, v98
	v_mul_f32_e32 v99, -2.0, v99
	v_mul_f32_e32 v98, 0x3fb8aa3b, v98
	v_mul_f32_e32 v99, 0x3fb8aa3b, v99
	v_exp_f32_e32 v98, v98
	v_exp_f32_e32 v99, v99
	v_cvt_pk_bf16_f32 v103, v96, v97
	v_or_b32_e32 v96, 0x108, v138
	v_ashrrev_i32_e32 v97, 31, v96
	v_add_f32_e32 v98, 1.0, v98
	v_add_f32_e32 v99, 1.0, v99
	v_lshlrev_b64 v[96:97], 5, v[96:97]
	v_rcp_f32_e32 v98, v98
	v_rcp_f32_e32 v99, v99
	v_lshl_add_u64 v[96:97], s[16:17], 0, v[96:97]
	v_lshl_add_u64 v[96:97], v[96:97], 0, v[136:137]
	global_store_dwordx4 v[96:97], v[100:103], off nt
	v_mul_f32_e32 v97, 0x3d372713, v94
	v_pk_mul_f32 v[92:93], v[92:93], v[98:99]
	v_mul_f32_e32 v97, v94, v97
	v_mul_f32_e32 v98, 0x3d372713, v95
	v_fma_f32 v97, v94, v97, v94
	v_mul_f32_e32 v98, v95, v98
	v_mul_f32_e32 v97, 0x3f4c422a, v97
	v_fma_f32 v98, v95, v98, v95
	v_mul_f32_e32 v97, -2.0, v97
	v_mul_f32_e32 v98, 0x3f4c422a, v98
	v_mul_f32_e32 v97, 0x3fb8aa3b, v97
	v_mul_f32_e32 v98, -2.0, v98
	v_exp_f32_e32 v97, v97
	v_mul_f32_e32 v98, 0x3fb8aa3b, v98
	v_exp_f32_e32 v99, v98
	v_cvt_pk_bf16_f32 v92, v92, v93
	v_add_f32_e32 v93, 1.0, v97
	v_rcp_f32_e32 v98, v93
	v_add_f32_e32 v93, 1.0, v99
	v_rcp_f32_e32 v99, v93
	v_mul_f32_e32 v93, 0x3d372713, v88
	v_mul_f32_e32 v93, v88, v93
	v_mul_f32_e32 v97, 0x3d372713, v89
	v_fma_f32 v93, v88, v93, v88
	v_mul_f32_e32 v97, v89, v97
	v_mul_f32_e32 v93, 0x3f4c422a, v93
	v_fma_f32 v97, v89, v97, v89
	v_mul_f32_e32 v93, -2.0, v93
	v_mul_f32_e32 v97, 0x3f4c422a, v97
	v_mul_f32_e32 v93, 0x3fb8aa3b, v93
	v_mul_f32_e32 v97, -2.0, v97
	v_exp_f32_e32 v93, v93
	v_mul_f32_e32 v97, 0x3fb8aa3b, v97
	v_exp_f32_e32 v97, v97
	v_pk_mul_f32 v[94:95], v[94:95], v[98:99]
	v_add_f32_e32 v93, 1.0, v93
	v_rcp_f32_e32 v98, v93
	v_add_f32_e32 v93, 1.0, v97
	v_mul_f32_e32 v97, 0x3d372713, v90
	v_mul_f32_e32 v97, v90, v97
	v_mul_f32_e32 v99, 0x3d372713, v91
	v_fma_f32 v97, v90, v97, v90
	v_mul_f32_e32 v99, v91, v99
	v_mul_f32_e32 v97, 0x3f4c422a, v97
	v_fma_f32 v99, v91, v99, v91
	v_mul_f32_e32 v97, -2.0, v97
	v_mul_f32_e32 v99, 0x3f4c422a, v99
	v_mul_f32_e32 v97, 0x3fb8aa3b, v97
	v_mul_f32_e32 v99, -2.0, v99
	v_exp_f32_e32 v97, v97
	v_mul_f32_e32 v99, 0x3fb8aa3b, v99
	v_exp_f32_e32 v101, v99
	v_rcp_f32_e32 v99, v93
	v_add_f32_e32 v93, 1.0, v97
	v_rcp_f32_e32 v100, v93
	v_add_f32_e32 v93, 1.0, v101
	v_rcp_f32_e32 v101, v93
	v_pk_mul_f32 v[88:89], v[88:89], v[98:99]
	v_cvt_pk_bf16_f32 v93, v94, v95
	v_cvt_pk_bf16_f32 v94, v88, v89
	v_pk_mul_f32 v[88:89], v[90:91], v[100:101]
	v_or_b32_e32 v96, 0x200, v138
	v_cvt_pk_bf16_f32 v95, v88, v89
	v_mul_f32_e32 v88, 0x3d372713, v84
	v_mul_f32_e32 v88, v84, v88
	v_fma_f32 v88, v84, v88, v84
	v_mul_f32_e32 v88, 0x3f4c422a, v88
	v_mul_f32_e32 v88, -2.0, v88
	v_mul_f32_e32 v88, 0x3fb8aa3b, v88
	v_exp_f32_e32 v90, v88
	v_mul_f32_e32 v88, 0x3d372713, v85
	v_mul_f32_e32 v88, v85, v88
	v_fma_f32 v88, v85, v88, v85
	v_mul_f32_e32 v88, 0x3f4c422a, v88
	v_mul_f32_e32 v88, -2.0, v88
	v_ashrrev_i32_e32 v97, 31, v96
	v_mul_f32_e32 v88, 0x3fb8aa3b, v88
	v_exp_f32_e32 v91, v88
	v_lshlrev_b64 v[88:89], 5, v[96:97]
	v_lshl_add_u64 v[88:89], s[16:17], 0, v[88:89]
	v_lshl_add_u64 v[88:89], v[88:89], 0, v[136:137]
	global_store_dwordx4 v[88:89], v[92:95], off nt
	v_mul_f32_e32 v88, 0x3d372713, v86
	v_mul_f32_e32 v88, v86, v88
	v_mul_f32_e32 v89, 0x3d372713, v87
	v_fma_f32 v88, v86, v88, v86
	v_mul_f32_e32 v89, v87, v89
	v_mul_f32_e32 v88, 0x3f4c422a, v88
	v_fma_f32 v89, v87, v89, v87
	v_add_f32_e32 v90, 1.0, v90
	v_add_f32_e32 v91, 1.0, v91
	v_mul_f32_e32 v88, -2.0, v88
	v_mul_f32_e32 v89, 0x3f4c422a, v89
	v_rcp_f32_e32 v90, v90
	v_rcp_f32_e32 v91, v91
	v_mul_f32_e32 v88, 0x3fb8aa3b, v88
	v_mul_f32_e32 v89, -2.0, v89
	v_exp_f32_e32 v88, v88
	v_mul_f32_e32 v89, 0x3fb8aa3b, v89
	v_exp_f32_e32 v89, v89
	v_pk_mul_f32 v[84:85], v[84:85], v[90:91]
	v_mul_f32_e32 v90, 0x3d372713, v81
	v_cvt_pk_bf16_f32 v84, v84, v85
	v_add_f32_e32 v85, 1.0, v88
	v_rcp_f32_e32 v88, v85
	v_add_f32_e32 v85, 1.0, v89
	v_rcp_f32_e32 v89, v85
	v_mul_f32_e32 v85, 0x3d372713, v80
	v_mul_f32_e32 v85, v80, v85
	v_fma_f32 v85, v80, v85, v80
	v_mul_f32_e32 v90, v81, v90
	v_mul_f32_e32 v85, 0x3f4c422a, v85
	v_fma_f32 v90, v81, v90, v81
	v_mul_f32_e32 v85, -2.0, v85
	v_mul_f32_e32 v90, 0x3f4c422a, v90
	v_mul_f32_e32 v85, 0x3fb8aa3b, v85
	v_mul_f32_e32 v90, -2.0, v90
	v_pk_mul_f32 v[86:87], v[86:87], v[88:89]
	v_mul_f32_e32 v89, 0x3d372713, v82
	v_exp_f32_e32 v85, v85
	v_mul_f32_e32 v90, 0x3fb8aa3b, v90
	v_mul_f32_e32 v89, v82, v89
	v_exp_f32_e32 v90, v90
	v_fma_f32 v89, v82, v89, v82
	v_mul_f32_e32 v89, 0x3f4c422a, v89
	v_mul_f32_e32 v89, -2.0, v89
	v_add_f32_e32 v85, 1.0, v85
	v_mul_f32_e32 v89, 0x3fb8aa3b, v89
	v_rcp_f32_e32 v88, v85
	v_add_f32_e32 v85, 1.0, v90
	v_exp_f32_e32 v90, v89
	v_mul_f32_e32 v89, 0x3d372713, v83
	v_mul_f32_e32 v89, v83, v89
	v_fma_f32 v89, v83, v89, v83
	v_mul_f32_e32 v89, 0x3f4c422a, v89
	v_mul_f32_e32 v89, -2.0, v89
	v_mul_f32_e32 v89, 0x3fb8aa3b, v89
	v_exp_f32_e32 v91, v89
	v_rcp_f32_e32 v89, v85
; __host__ __device__ __forceinline__ size_t ys_off(int m, int ch) { return ((size_t)(ch >> 4) * PT + m) * 16 + (ch & 15); }
; __device__ __forceinline__ unsigned pk2(float lo, float hi) { typedef __bf16 bf16x2_t_ __attribute__((ext_vector_type(2))); f32x2 v = {lo, hi}; return __builtin_bit_cast(unsigned, __builtin_convertvector(v, bf16x2_t_)); }
; __device__ __forceinline__ float gelu_tanh(float x) { const float z = 0.7978845608028654f * (x + 0.044715f * x * x * x); return x * __builtin_amdgcn_rcpf(1.f + __expf(-2.f * z)); }
;     __device__ __forceinline__ void operator()(const f32x4 (&acc)[2][2][4][2], const pg8::Unit& u, int wr, int wc, int fr, int fq) const {
;     ...
; #pragma unroll
;                 for (int bj = 0; bj < 2; ++bj) {
;                     const int t = 8 * bj + 2 * wc + (fq >> 1), p0 = 8 * (fq & 1);
;                     const f32x4 a = acc[ai][bj][m][0], b = acc[ai][bj][m][1];
;                     u32x4 w; w.x = pk2(gelu_tanh(a[0]), gelu_tanh(a[1])); w.y = pk2(gelu_tanh(a[2]), gelu_tanh(a[3])); w.z = pk2(gelu_tanh(b[0]), gelu_tanh(b[1])); w.w = pk2(gelu_tanh(b[2]), gelu_tanh(b[3]));
;                     *(u32x4*)(YS_ + ys_off(row * CL + t, u.g * 16 + p0)) = w;
;                 }
	v_add_f32_e32 v85, 1.0, v90
	v_rcp_f32_e32 v90, v85
	v_add_f32_e32 v85, 1.0, v91
	v_rcp_f32_e32 v91, v85
	v_pk_mul_f32 v[80:81], v[80:81], v[88:89]
	v_cvt_pk_bf16_f32 v85, v86, v87
	v_cvt_pk_bf16_f32 v86, v80, v81
	v_pk_mul_f32 v[80:81], v[82:83], v[90:91]
	v_mul_f32_e32 v82, 0x3d372713, v76
	v_mul_f32_e32 v83, 0x3d372713, v77
	v_mul_f32_e32 v82, v76, v82
	v_mul_f32_e32 v83, v77, v83
	v_fma_f32 v82, v76, v82, v76
	v_fma_f32 v83, v77, v83, v77
	v_mul_f32_e32 v82, 0x3f4c422a, v82
	v_mul_f32_e32 v83, 0x3f4c422a, v83
	v_mul_f32_e32 v82, -2.0, v82
	v_mul_f32_e32 v83, -2.0, v83
	v_mul_f32_e32 v82, 0x3fb8aa3b, v82
	v_mul_f32_e32 v83, 0x3fb8aa3b, v83
	v_exp_f32_e32 v82, v82
	v_exp_f32_e32 v83, v83
	v_cvt_pk_bf16_f32 v87, v80, v81
	v_or_b32_e32 v80, 0x208, v138
	v_ashrrev_i32_e32 v81, 31, v80
	v_add_f32_e32 v82, 1.0, v82
	v_add_f32_e32 v83, 1.0, v83
	v_lshlrev_b64 v[80:81], 5, v[80:81]
	v_rcp_f32_e32 v82, v82
	v_rcp_f32_e32 v83, v83
	v_lshl_add_u64 v[80:81], s[16:17], 0, v[80:81]
	v_lshl_add_u64 v[80:81], v[80:81], 0, v[136:137]
	global_store_dwordx4 v[80:81], v[84:87], off nt
	v_mul_f32_e32 v81, 0x3d372713, v78
	v_pk_mul_f32 v[76:77], v[76:77], v[82:83]
	v_mul_f32_e32 v81, v78, v81
	v_mul_f32_e32 v82, 0x3d372713, v79
	v_fma_f32 v81, v78, v81, v78
	v_mul_f32_e32 v82, v79, v82
	v_mul_f32_e32 v81, 0x3f4c422a, v81
	v_fma_f32 v82, v79, v82, v79
	v_mul_f32_e32 v81, -2.0, v81
	v_mul_f32_e32 v82, 0x3f4c422a, v82
	v_mul_f32_e32 v81, 0x3fb8aa3b, v81
	v_mul_f32_e32 v82, -2.0, v82
	v_exp_f32_e32 v81, v81
	v_mul_f32_e32 v82, 0x3fb8aa3b, v82
	v_exp_f32_e32 v83, v82
	v_cvt_pk_bf16_f32 v76, v76, v77
	v_add_f32_e32 v77, 1.0, v81
	v_rcp_f32_e32 v82, v77
	v_add_f32_e32 v77, 1.0, v83
	v_rcp_f32_e32 v83, v77
	v_mul_f32_e32 v77, 0x3d372713, v72
	v_mul_f32_e32 v77, v72, v77
	v_mul_f32_e32 v81, 0x3d372713, v73
	v_fma_f32 v77, v72, v77, v72
	v_mul_f32_e32 v81, v73, v81
	v_mul_f32_e32 v77, 0x3f4c422a, v77
	v_fma_f32 v81, v73, v81, v73
	v_mul_f32_e32 v77, -2.0, v77
	v_mul_f32_e32 v81, 0x3f4c422a, v81
	v_mul_f32_e32 v77, 0x3fb8aa3b, v77
	v_mul_f32_e32 v81, -2.0, v81
	v_exp_f32_e32 v77, v77
	v_mul_f32_e32 v81, 0x3fb8aa3b, v81
	v_exp_f32_e32 v81, v81
	v_pk_mul_f32 v[78:79], v[78:79], v[82:83]
	v_add_f32_e32 v77, 1.0, v77
	v_rcp_f32_e32 v82, v77
	v_add_f32_e32 v77, 1.0, v81
	v_mul_f32_e32 v81, 0x3d372713, v74
	v_mul_f32_e32 v81, v74, v81
	v_mul_f32_e32 v83, 0x3d372713, v75
	v_fma_f32 v81, v74, v81, v74
	v_mul_f32_e32 v83, v75, v83
	v_mul_f32_e32 v81, 0x3f4c422a, v81
	v_fma_f32 v83, v75, v83, v75
	v_mul_f32_e32 v81, -2.0, v81
	v_mul_f32_e32 v83, 0x3f4c422a, v83
	v_mul_f32_e32 v81, 0x3fb8aa3b, v81
	v_mul_f32_e32 v83, -2.0, v83
	v_exp_f32_e32 v81, v81
	v_mul_f32_e32 v83, 0x3fb8aa3b, v83
	v_exp_f32_e32 v85, v83
	v_rcp_f32_e32 v83, v77
	v_add_f32_e32 v77, 1.0, v81
	v_rcp_f32_e32 v84, v77
	v_add_f32_e32 v77, 1.0, v85
	v_rcp_f32_e32 v85, v77
	v_pk_mul_f32 v[72:73], v[72:73], v[82:83]
	v_cvt_pk_bf16_f32 v77, v78, v79
	v_cvt_pk_bf16_f32 v78, v72, v73
	v_pk_mul_f32 v[72:73], v[74:75], v[84:85]
	v_or_b32_e32 v80, 0x300, v138
	v_cvt_pk_bf16_f32 v79, v72, v73
	v_mul_f32_e32 v72, 0x3d372713, v68
	v_mul_f32_e32 v72, v68, v72
	v_fma_f32 v72, v68, v72, v68
	v_mul_f32_e32 v72, 0x3f4c422a, v72
	v_mul_f32_e32 v72, -2.0, v72
	v_mul_f32_e32 v72, 0x3fb8aa3b, v72
	v_exp_f32_e32 v74, v72
	v_mul_f32_e32 v72, 0x3d372713, v69
	v_mul_f32_e32 v72, v69, v72
	v_fma_f32 v72, v69, v72, v69
	v_mul_f32_e32 v72, 0x3f4c422a, v72
	v_mul_f32_e32 v72, -2.0, v72
	v_ashrrev_i32_e32 v81, 31, v80
	v_mul_f32_e32 v72, 0x3fb8aa3b, v72
	v_exp_f32_e32 v75, v72
	v_lshlrev_b64 v[72:73], 5, v[80:81]
	v_lshl_add_u64 v[72:73], s[16:17], 0, v[72:73]
	v_lshl_add_u64 v[72:73], v[72:73], 0, v[136:137]
	global_store_dwordx4 v[72:73], v[76:79], off nt
	v_mul_f32_e32 v72, 0x3d372713, v70
	v_mul_f32_e32 v72, v70, v72
	v_mul_f32_e32 v73, 0x3d372713, v71
	v_fma_f32 v72, v70, v72, v70
	v_mul_f32_e32 v73, v71, v73
	v_mul_f32_e32 v72, 0x3f4c422a, v72
	v_fma_f32 v73, v71, v73, v71
	v_add_f32_e32 v74, 1.0, v74
	v_add_f32_e32 v75, 1.0, v75
	v_mul_f32_e32 v72, -2.0, v72
	v_mul_f32_e32 v73, 0x3f4c422a, v73
	v_rcp_f32_e32 v74, v74
	v_rcp_f32_e32 v75, v75
	v_mul_f32_e32 v72, 0x3fb8aa3b, v72
	v_mul_f32_e32 v73, -2.0, v73
	v_exp_f32_e32 v72, v72
	v_mul_f32_e32 v73, 0x3fb8aa3b, v73
	v_exp_f32_e32 v73, v73
	v_pk_mul_f32 v[68:69], v[68:69], v[74:75]
	v_mul_f32_e32 v74, 0x3d372713, v65
	v_cvt_pk_bf16_f32 v68, v68, v69
	v_add_f32_e32 v69, 1.0, v72
	v_rcp_f32_e32 v72, v69
	v_add_f32_e32 v69, 1.0, v73
	v_rcp_f32_e32 v73, v69
	v_mul_f32_e32 v69, 0x3d372713, v64
	v_mul_f32_e32 v69, v64, v69
	v_fma_f32 v69, v64, v69, v64
	v_mul_f32_e32 v74, v65, v74
	v_mul_f32_e32 v69, 0x3f4c422a, v69
	v_fma_f32 v74, v65, v74, v65
	v_mul_f32_e32 v69, -2.0, v69
	v_mul_f32_e32 v74, 0x3f4c422a, v74
	v_mul_f32_e32 v69, 0x3fb8aa3b, v69
	v_mul_f32_e32 v74, -2.0, v74
	v_pk_mul_f32 v[70:71], v[70:71], v[72:73]
	v_mul_f32_e32 v73, 0x3d372713, v66
	v_exp_f32_e32 v69, v69
	v_mul_f32_e32 v74, 0x3fb8aa3b, v74
	v_mul_f32_e32 v73, v66, v73
	v_exp_f32_e32 v74, v74
	v_fma_f32 v73, v66, v73, v66
	v_mul_f32_e32 v73, 0x3f4c422a, v73
	v_mul_f32_e32 v73, -2.0, v73
	v_add_f32_e32 v69, 1.0, v69
	v_mul_f32_e32 v73, 0x3fb8aa3b, v73
	v_rcp_f32_e32 v72, v69
	v_add_f32_e32 v69, 1.0, v74
	v_exp_f32_e32 v74, v73
	v_mul_f32_e32 v73, 0x3d372713, v67
	v_mul_f32_e32 v73, v67, v73
	v_fma_f32 v73, v67, v73, v67
	v_mul_f32_e32 v73, 0x3f4c422a, v73
	v_mul_f32_e32 v73, -2.0, v73
	v_mul_f32_e32 v73, 0x3fb8aa3b, v73
	v_exp_f32_e32 v75, v73
	v_rcp_f32_e32 v73, v69
	v_add_f32_e32 v69, 1.0, v74
	v_rcp_f32_e32 v74, v69
	v_add_f32_e32 v69, 1.0, v75
	v_rcp_f32_e32 v75, v69
	v_pk_mul_f32 v[64:65], v[64:65], v[72:73]
; __host__ __device__ __forceinline__ size_t ys_off(int m, int ch) { return ((size_t)(ch >> 4) * PT + m) * 16 + (ch & 15); }
; __device__ __forceinline__ unsigned pk2(float lo, float hi) { typedef __bf16 bf16x2_t_ __attribute__((ext_vector_type(2))); f32x2 v = {lo, hi}; return __builtin_bit_cast(unsigned, __builtin_convertvector(v, bf16x2_t_)); }
; __device__ __forceinline__ float gelu_tanh(float x) { const float z = 0.7978845608028654f * (x + 0.044715f * x * x * x); return x * __builtin_amdgcn_rcpf(1.f + __expf(-2.f * z)); }
;     __device__ __forceinline__ void operator()(const f32x4 (&acc)[2][2][4][2], const pg8::Unit& u, int wr, int wc, int fr, int fq) const {
;     ...
; #pragma unroll
;                 for (int bj = 0; bj < 2; ++bj) {
;                     const int t = 8 * bj + 2 * wc + (fq >> 1), p0 = 8 * (fq & 1);
;                     const f32x4 a = acc[ai][bj][m][0], b = acc[ai][bj][m][1];
;                     u32x4 w; w.x = pk2(gelu_tanh(a[0]), gelu_tanh(a[1])); w.y = pk2(gelu_tanh(a[2]), gelu_tanh(a[3])); w.z = pk2(gelu_tanh(b[0]), gelu_tanh(b[1])); w.w = pk2(gelu_tanh(b[2]), gelu_tanh(b[3]));
;                     *(u32x4*)(YS_ + ys_off(row * CL + t, u.g * 16 + p0)) = w;
;                 }
	v_cvt_pk_bf16_f32 v69, v70, v71
	v_cvt_pk_bf16_f32 v70, v64, v65
	v_pk_mul_f32 v[64:65], v[66:67], v[74:75]
	v_mul_f32_e32 v66, 0x3d372713, v60
	v_mul_f32_e32 v67, 0x3d372713, v61
	v_mul_f32_e32 v66, v60, v66
	v_mul_f32_e32 v67, v61, v67
	v_fma_f32 v66, v60, v66, v60
	v_fma_f32 v67, v61, v67, v61
	v_mul_f32_e32 v66, 0x3f4c422a, v66
	v_mul_f32_e32 v67, 0x3f4c422a, v67
	v_mul_f32_e32 v66, -2.0, v66
	v_mul_f32_e32 v67, -2.0, v67
	v_mul_f32_e32 v66, 0x3fb8aa3b, v66
	v_mul_f32_e32 v67, 0x3fb8aa3b, v67
	v_exp_f32_e32 v66, v66
	v_exp_f32_e32 v67, v67
	v_cvt_pk_bf16_f32 v71, v64, v65
	v_or_b32_e32 v64, 0x308, v138
	v_ashrrev_i32_e32 v65, 31, v64
	v_add_f32_e32 v66, 1.0, v66
	v_add_f32_e32 v67, 1.0, v67
	v_lshlrev_b64 v[64:65], 5, v[64:65]
	v_rcp_f32_e32 v66, v66
	v_rcp_f32_e32 v67, v67
	v_lshl_add_u64 v[64:65], s[16:17], 0, v[64:65]
	v_lshl_add_u64 v[64:65], v[64:65], 0, v[136:137]
	global_store_dwordx4 v[64:65], v[68:71], off nt
	v_mul_f32_e32 v65, 0x3d372713, v62
	v_pk_mul_f32 v[60:61], v[60:61], v[66:67]
	v_mul_f32_e32 v65, v62, v65
	v_mul_f32_e32 v66, 0x3d372713, v63
	v_fma_f32 v65, v62, v65, v62
	v_mul_f32_e32 v66, v63, v66
	v_mul_f32_e32 v65, 0x3f4c422a, v65
	v_fma_f32 v66, v63, v66, v63
	v_mul_f32_e32 v65, -2.0, v65
	v_mul_f32_e32 v66, 0x3f4c422a, v66
	v_mul_f32_e32 v65, 0x3fb8aa3b, v65
	v_mul_f32_e32 v66, -2.0, v66
	v_exp_f32_e32 v65, v65
	v_mul_f32_e32 v66, 0x3fb8aa3b, v66
	v_exp_f32_e32 v67, v66
	v_cvt_pk_bf16_f32 v60, v60, v61
	v_add_f32_e32 v61, 1.0, v65
	v_rcp_f32_e32 v66, v61
	v_add_f32_e32 v61, 1.0, v67
	v_rcp_f32_e32 v67, v61
	v_mul_f32_e32 v61, 0x3d372713, v56
	v_mul_f32_e32 v61, v56, v61
	v_mul_f32_e32 v65, 0x3d372713, v57
	v_fma_f32 v61, v56, v61, v56
	v_mul_f32_e32 v65, v57, v65
	v_mul_f32_e32 v61, 0x3f4c422a, v61
	v_fma_f32 v65, v57, v65, v57
	v_mul_f32_e32 v61, -2.0, v61
	v_mul_f32_e32 v65, 0x3f4c422a, v65
	v_mul_f32_e32 v61, 0x3fb8aa3b, v61
	v_mul_f32_e32 v65, -2.0, v65
	v_exp_f32_e32 v61, v61
	v_mul_f32_e32 v65, 0x3fb8aa3b, v65
	v_exp_f32_e32 v65, v65
	v_pk_mul_f32 v[62:63], v[62:63], v[66:67]
	v_add_f32_e32 v61, 1.0, v61
	v_rcp_f32_e32 v66, v61
	v_add_f32_e32 v61, 1.0, v65
	v_mul_f32_e32 v65, 0x3d372713, v58
	v_mul_f32_e32 v65, v58, v65
	v_mul_f32_e32 v67, 0x3d372713, v59
	v_fma_f32 v65, v58, v65, v58
	v_mul_f32_e32 v67, v59, v67
	v_mul_f32_e32 v65, 0x3f4c422a, v65
	v_fma_f32 v67, v59, v67, v59
	v_mul_f32_e32 v65, -2.0, v65
	v_mul_f32_e32 v67, 0x3f4c422a, v67
	v_mul_f32_e32 v65, 0x3fb8aa3b, v65
	v_mul_f32_e32 v67, -2.0, v67
	v_exp_f32_e32 v65, v65
	v_mul_f32_e32 v67, 0x3fb8aa3b, v67
	v_exp_f32_e32 v69, v67
	v_rcp_f32_e32 v67, v61
	v_add_f32_e32 v61, 1.0, v65
	v_rcp_f32_e32 v68, v61
	v_add_f32_e32 v61, 1.0, v69
	v_rcp_f32_e32 v69, v61
	v_pk_mul_f32 v[56:57], v[56:57], v[66:67]
	v_cvt_pk_bf16_f32 v61, v62, v63
	v_cvt_pk_bf16_f32 v62, v56, v57
	v_pk_mul_f32 v[56:57], v[58:59], v[68:69]
	v_add_u32_e32 v64, v151, v209
	v_cvt_pk_bf16_f32 v63, v56, v57
	v_mul_f32_e32 v56, 0x3d372713, v52
	v_mul_f32_e32 v56, v52, v56
	v_fma_f32 v56, v52, v56, v52
	v_mul_f32_e32 v56, 0x3f4c422a, v56
	v_mul_f32_e32 v56, -2.0, v56
	v_mul_f32_e32 v56, 0x3fb8aa3b, v56
	v_exp_f32_e32 v58, v56
	v_mul_f32_e32 v56, 0x3d372713, v53
	v_mul_f32_e32 v56, v53, v56
	v_fma_f32 v56, v53, v56, v53
	v_mul_f32_e32 v56, 0x3f4c422a, v56
	v_mul_f32_e32 v56, -2.0, v56
	v_ashrrev_i32_e32 v65, 31, v64
	v_mul_f32_e32 v56, 0x3fb8aa3b, v56
	v_exp_f32_e32 v59, v56
	v_lshlrev_b64 v[56:57], 5, v[64:65]
	v_lshl_add_u64 v[56:57], s[16:17], 0, v[56:57]
	v_lshl_add_u64 v[56:57], v[56:57], 0, v[136:137]
	global_store_dwordx4 v[56:57], v[60:63], off nt
	v_mul_f32_e32 v56, 0x3d372713, v54
	v_mul_f32_e32 v56, v54, v56
	v_mul_f32_e32 v57, 0x3d372713, v55
	v_fma_f32 v56, v54, v56, v54
	v_mul_f32_e32 v57, v55, v57
	v_mul_f32_e32 v56, 0x3f4c422a, v56
	v_fma_f32 v57, v55, v57, v55
	v_add_f32_e32 v58, 1.0, v58
	v_add_f32_e32 v59, 1.0, v59
	v_mul_f32_e32 v56, -2.0, v56
	v_mul_f32_e32 v57, 0x3f4c422a, v57
	v_rcp_f32_e32 v58, v58
	v_rcp_f32_e32 v59, v59
	v_mul_f32_e32 v56, 0x3fb8aa3b, v56
	v_mul_f32_e32 v57, -2.0, v57
	v_exp_f32_e32 v56, v56
	v_mul_f32_e32 v57, 0x3fb8aa3b, v57
	v_exp_f32_e32 v57, v57
	v_pk_mul_f32 v[52:53], v[52:53], v[58:59]
	v_mul_f32_e32 v58, 0x3d372713, v49
	v_cvt_pk_bf16_f32 v52, v52, v53
	v_add_f32_e32 v53, 1.0, v56
	v_rcp_f32_e32 v56, v53
	v_add_f32_e32 v53, 1.0, v57
	v_rcp_f32_e32 v57, v53
	v_mul_f32_e32 v53, 0x3d372713, v48
	v_mul_f32_e32 v53, v48, v53
	v_fma_f32 v53, v48, v53, v48
	v_mul_f32_e32 v58, v49, v58
	v_mul_f32_e32 v53, 0x3f4c422a, v53
	v_fma_f32 v58, v49, v58, v49
	v_mul_f32_e32 v53, -2.0, v53
	v_mul_f32_e32 v58, 0x3f4c422a, v58
	v_mul_f32_e32 v53, 0x3fb8aa3b, v53
	v_mul_f32_e32 v58, -2.0, v58
	v_pk_mul_f32 v[54:55], v[54:55], v[56:57]
	v_mul_f32_e32 v57, 0x3d372713, v50
	v_exp_f32_e32 v53, v53
	v_mul_f32_e32 v58, 0x3fb8aa3b, v58
	v_mul_f32_e32 v57, v50, v57
	v_exp_f32_e32 v58, v58
	v_fma_f32 v57, v50, v57, v50
	v_mul_f32_e32 v57, 0x3f4c422a, v57
	v_mul_f32_e32 v57, -2.0, v57
	v_add_f32_e32 v53, 1.0, v53
	v_mul_f32_e32 v57, 0x3fb8aa3b, v57
	v_rcp_f32_e32 v56, v53
	v_add_f32_e32 v53, 1.0, v58
	v_exp_f32_e32 v58, v57
	v_mul_f32_e32 v57, 0x3d372713, v51
	v_mul_f32_e32 v57, v51, v57
	v_fma_f32 v57, v51, v57, v51
	v_mul_f32_e32 v57, 0x3f4c422a, v57
	v_mul_f32_e32 v57, -2.0, v57
	v_mul_f32_e32 v57, 0x3fb8aa3b, v57
	v_exp_f32_e32 v59, v57
	v_rcp_f32_e32 v57, v53
	v_add_f32_e32 v53, 1.0, v58
	v_rcp_f32_e32 v58, v53
	v_add_f32_e32 v53, 1.0, v59
	v_rcp_f32_e32 v59, v53
	v_pk_mul_f32 v[48:49], v[48:49], v[56:57]
	v_cvt_pk_bf16_f32 v53, v54, v55
	v_cvt_pk_bf16_f32 v54, v48, v49
	v_pk_mul_f32 v[48:49], v[50:51], v[58:59]
	v_mul_f32_e32 v50, 0x3d372713, v44
; __host__ __device__ __forceinline__ size_t ys_off(int m, int ch) { return ((size_t)(ch >> 4) * PT + m) * 16 + (ch & 15); }
; __device__ __forceinline__ unsigned pk2(float lo, float hi) { typedef __bf16 bf16x2_t_ __attribute__((ext_vector_type(2))); f32x2 v = {lo, hi}; return __builtin_bit_cast(unsigned, __builtin_convertvector(v, bf16x2_t_)); }
; __device__ __forceinline__ float gelu_tanh(float x) { const float z = 0.7978845608028654f * (x + 0.044715f * x * x * x); return x * __builtin_amdgcn_rcpf(1.f + __expf(-2.f * z)); }
;     __device__ __forceinline__ void operator()(const f32x4 (&acc)[2][2][4][2], const pg8::Unit& u, int wr, int wc, int fr, int fq) const {
;     ...
; #pragma unroll
;                 for (int bj = 0; bj < 2; ++bj) {
;                     const int t = 8 * bj + 2 * wc + (fq >> 1), p0 = 8 * (fq & 1);
;                     const f32x4 a = acc[ai][bj][m][0], b = acc[ai][bj][m][1];
;                     u32x4 w; w.x = pk2(gelu_tanh(a[0]), gelu_tanh(a[1])); w.y = pk2(gelu_tanh(a[2]), gelu_tanh(a[3])); w.z = pk2(gelu_tanh(b[0]), gelu_tanh(b[1])); w.w = pk2(gelu_tanh(b[2]), gelu_tanh(b[3]));
;                     *(u32x4*)(YS_ + ys_off(row * CL + t, u.g * 16 + p0)) = w;
;                 }
	v_mul_f32_e32 v51, 0x3d372713, v45
	v_mul_f32_e32 v50, v44, v50
	v_mul_f32_e32 v51, v45, v51
	v_fma_f32 v50, v44, v50, v44
	v_fma_f32 v51, v45, v51, v45
	v_mul_f32_e32 v50, 0x3f4c422a, v50
	v_mul_f32_e32 v51, 0x3f4c422a, v51
	v_mul_f32_e32 v50, -2.0, v50
	v_mul_f32_e32 v51, -2.0, v51
	v_mul_f32_e32 v50, 0x3fb8aa3b, v50
	v_mul_f32_e32 v51, 0x3fb8aa3b, v51
	v_exp_f32_e32 v50, v50
	v_exp_f32_e32 v51, v51
	v_cvt_pk_bf16_f32 v55, v48, v49
	v_or_b32_e32 v48, 8, v64
	v_ashrrev_i32_e32 v49, 31, v48
	v_add_f32_e32 v50, 1.0, v50
	v_add_f32_e32 v51, 1.0, v51
	v_lshlrev_b64 v[48:49], 5, v[48:49]
	v_rcp_f32_e32 v50, v50
	v_rcp_f32_e32 v51, v51
	v_lshl_add_u64 v[48:49], s[16:17], 0, v[48:49]
	v_lshl_add_u64 v[48:49], v[48:49], 0, v[136:137]
	global_store_dwordx4 v[48:49], v[52:55], off nt
	v_mul_f32_e32 v49, 0x3d372713, v46
	v_pk_mul_f32 v[44:45], v[44:45], v[50:51]
	v_mul_f32_e32 v49, v46, v49
	v_mul_f32_e32 v50, 0x3d372713, v47
	v_fma_f32 v49, v46, v49, v46
	v_mul_f32_e32 v50, v47, v50
	v_mul_f32_e32 v49, 0x3f4c422a, v49
	v_fma_f32 v50, v47, v50, v47
	v_mul_f32_e32 v49, -2.0, v49
	v_mul_f32_e32 v50, 0x3f4c422a, v50
	v_mul_f32_e32 v49, 0x3fb8aa3b, v49
	v_mul_f32_e32 v50, -2.0, v50
	v_exp_f32_e32 v49, v49
	v_mul_f32_e32 v50, 0x3fb8aa3b, v50
	v_exp_f32_e32 v51, v50
	v_cvt_pk_bf16_f32 v44, v44, v45
	v_add_f32_e32 v45, 1.0, v49
	v_rcp_f32_e32 v50, v45
	v_add_f32_e32 v45, 1.0, v51
	v_rcp_f32_e32 v51, v45
	v_mul_f32_e32 v45, 0x3d372713, v40
	v_mul_f32_e32 v45, v40, v45
	v_mul_f32_e32 v49, 0x3d372713, v41
	v_fma_f32 v45, v40, v45, v40
	v_mul_f32_e32 v49, v41, v49
	v_mul_f32_e32 v45, 0x3f4c422a, v45
	v_fma_f32 v49, v41, v49, v41
	v_mul_f32_e32 v45, -2.0, v45
	v_mul_f32_e32 v49, 0x3f4c422a, v49
	v_mul_f32_e32 v45, 0x3fb8aa3b, v45
	v_mul_f32_e32 v49, -2.0, v49
	v_exp_f32_e32 v45, v45
	v_mul_f32_e32 v49, 0x3fb8aa3b, v49
	v_exp_f32_e32 v49, v49
	v_pk_mul_f32 v[46:47], v[46:47], v[50:51]
	v_add_f32_e32 v45, 1.0, v45
	v_rcp_f32_e32 v50, v45
	v_add_f32_e32 v45, 1.0, v49
	v_mul_f32_e32 v49, 0x3d372713, v42
	v_mul_f32_e32 v49, v42, v49
	v_mul_f32_e32 v51, 0x3d372713, v43
	v_fma_f32 v49, v42, v49, v42
	v_mul_f32_e32 v51, v43, v51
	v_mul_f32_e32 v49, 0x3f4c422a, v49
	v_fma_f32 v51, v43, v51, v43
	v_mul_f32_e32 v49, -2.0, v49
	v_mul_f32_e32 v51, 0x3f4c422a, v51
	v_mul_f32_e32 v49, 0x3fb8aa3b, v49
	v_mul_f32_e32 v51, -2.0, v51
	v_exp_f32_e32 v49, v49
	v_mul_f32_e32 v51, 0x3fb8aa3b, v51
	v_exp_f32_e32 v53, v51
	v_rcp_f32_e32 v51, v45
	v_add_f32_e32 v45, 1.0, v49
	v_rcp_f32_e32 v52, v45
	v_add_f32_e32 v45, 1.0, v53
	v_rcp_f32_e32 v53, v45
	v_pk_mul_f32 v[40:41], v[40:41], v[50:51]
	v_cvt_pk_bf16_f32 v45, v46, v47
	v_cvt_pk_bf16_f32 v46, v40, v41
	v_pk_mul_f32 v[40:41], v[42:43], v[52:53]
	v_add_u32_e32 v48, v151, v254
	v_cvt_pk_bf16_f32 v47, v40, v41
	v_mul_f32_e32 v40, 0x3d372713, v36
	v_mul_f32_e32 v40, v36, v40
	v_fma_f32 v40, v36, v40, v36
	v_mul_f32_e32 v40, 0x3f4c422a, v40
	v_mul_f32_e32 v40, -2.0, v40
	v_mul_f32_e32 v40, 0x3fb8aa3b, v40
	v_exp_f32_e32 v42, v40
	v_mul_f32_e32 v40, 0x3d372713, v37
	v_mul_f32_e32 v40, v37, v40
	v_fma_f32 v40, v37, v40, v37
	v_mul_f32_e32 v40, 0x3f4c422a, v40
	v_mul_f32_e32 v40, -2.0, v40
	v_ashrrev_i32_e32 v49, 31, v48
	v_mul_f32_e32 v40, 0x3fb8aa3b, v40
	v_exp_f32_e32 v43, v40
	v_lshlrev_b64 v[40:41], 5, v[48:49]
	v_lshl_add_u64 v[40:41], s[16:17], 0, v[40:41]
	v_lshl_add_u64 v[40:41], v[40:41], 0, v[136:137]
	global_store_dwordx4 v[40:41], v[44:47], off nt
	v_mul_f32_e32 v40, 0x3d372713, v38
	v_mul_f32_e32 v40, v38, v40
	v_mul_f32_e32 v41, 0x3d372713, v39
	v_fma_f32 v40, v38, v40, v38
	v_mul_f32_e32 v41, v39, v41
	v_mul_f32_e32 v40, 0x3f4c422a, v40
	v_fma_f32 v41, v39, v41, v39
	v_add_f32_e32 v42, 1.0, v42
	v_add_f32_e32 v43, 1.0, v43
	v_mul_f32_e32 v40, -2.0, v40
	v_mul_f32_e32 v41, 0x3f4c422a, v41
	v_rcp_f32_e32 v42, v42
	v_rcp_f32_e32 v43, v43
	v_mul_f32_e32 v40, 0x3fb8aa3b, v40
	v_mul_f32_e32 v41, -2.0, v41
	v_exp_f32_e32 v40, v40
	v_mul_f32_e32 v41, 0x3fb8aa3b, v41
	v_exp_f32_e32 v41, v41
	v_pk_mul_f32 v[36:37], v[36:37], v[42:43]
	v_mul_f32_e32 v42, 0x3d372713, v33
	v_cvt_pk_bf16_f32 v36, v36, v37
	v_add_f32_e32 v37, 1.0, v40
	v_rcp_f32_e32 v40, v37
	v_add_f32_e32 v37, 1.0, v41
	v_rcp_f32_e32 v41, v37
	v_mul_f32_e32 v37, 0x3d372713, v32
	v_mul_f32_e32 v37, v32, v37
	v_fma_f32 v37, v32, v37, v32
	v_mul_f32_e32 v42, v33, v42
	v_mul_f32_e32 v37, 0x3f4c422a, v37
	v_fma_f32 v42, v33, v42, v33
	v_mul_f32_e32 v37, -2.0, v37
	v_mul_f32_e32 v42, 0x3f4c422a, v42
	v_mul_f32_e32 v37, 0x3fb8aa3b, v37
	v_mul_f32_e32 v42, -2.0, v42
	v_pk_mul_f32 v[38:39], v[38:39], v[40:41]
	v_mul_f32_e32 v41, 0x3d372713, v34
	v_exp_f32_e32 v37, v37
	v_mul_f32_e32 v42, 0x3fb8aa3b, v42
	v_mul_f32_e32 v41, v34, v41
	v_exp_f32_e32 v42, v42
	v_fma_f32 v41, v34, v41, v34
	v_mul_f32_e32 v41, 0x3f4c422a, v41
	v_mul_f32_e32 v41, -2.0, v41
	v_add_f32_e32 v37, 1.0, v37
	v_mul_f32_e32 v41, 0x3fb8aa3b, v41
	v_rcp_f32_e32 v40, v37
	v_add_f32_e32 v37, 1.0, v42
	v_exp_f32_e32 v42, v41
	v_mul_f32_e32 v41, 0x3d372713, v35
	v_mul_f32_e32 v41, v35, v41
	v_fma_f32 v41, v35, v41, v35
	v_mul_f32_e32 v41, 0x3f4c422a, v41
	v_mul_f32_e32 v41, -2.0, v41
	v_mul_f32_e32 v41, 0x3fb8aa3b, v41
	v_exp_f32_e32 v43, v41
	v_rcp_f32_e32 v41, v37
	v_add_f32_e32 v37, 1.0, v42
	v_rcp_f32_e32 v42, v37
	v_add_f32_e32 v37, 1.0, v43
	v_rcp_f32_e32 v43, v37
	v_pk_mul_f32 v[32:33], v[32:33], v[40:41]
	v_cvt_pk_bf16_f32 v37, v38, v39
	v_cvt_pk_bf16_f32 v38, v32, v33
	v_pk_mul_f32 v[32:33], v[34:35], v[42:43]
	v_mul_f32_e32 v34, 0x3d372713, v28
	v_mul_f32_e32 v35, 0x3d372713, v29
	v_mul_f32_e32 v34, v28, v34
	v_mul_f32_e32 v35, v29, v35
	v_fma_f32 v34, v28, v34, v28
	v_fma_f32 v35, v29, v35, v29
; __host__ __device__ __forceinline__ size_t ys_off(int m, int ch) { return ((size_t)(ch >> 4) * PT + m) * 16 + (ch & 15); }
; __device__ __forceinline__ unsigned pk2(float lo, float hi) { typedef __bf16 bf16x2_t_ __attribute__((ext_vector_type(2))); f32x2 v = {lo, hi}; return __builtin_bit_cast(unsigned, __builtin_convertvector(v, bf16x2_t_)); }
; __device__ __forceinline__ float gelu_tanh(float x) { const float z = 0.7978845608028654f * (x + 0.044715f * x * x * x); return x * __builtin_amdgcn_rcpf(1.f + __expf(-2.f * z)); }
;     __device__ __forceinline__ void operator()(const f32x4 (&acc)[2][2][4][2], const pg8::Unit& u, int wr, int wc, int fr, int fq) const {
;     ...
; #pragma unroll
;                 for (int bj = 0; bj < 2; ++bj) {
;                     const int t = 8 * bj + 2 * wc + (fq >> 1), p0 = 8 * (fq & 1);
;                     const f32x4 a = acc[ai][bj][m][0], b = acc[ai][bj][m][1];
;                     u32x4 w; w.x = pk2(gelu_tanh(a[0]), gelu_tanh(a[1])); w.y = pk2(gelu_tanh(a[2]), gelu_tanh(a[3])); w.z = pk2(gelu_tanh(b[0]), gelu_tanh(b[1])); w.w = pk2(gelu_tanh(b[2]), gelu_tanh(b[3]));
;                     *(u32x4*)(YS_ + ys_off(row * CL + t, u.g * 16 + p0)) = w;
;                 }
	v_mul_f32_e32 v34, 0x3f4c422a, v34
	v_mul_f32_e32 v35, 0x3f4c422a, v35
	v_mul_f32_e32 v34, -2.0, v34
	v_mul_f32_e32 v35, -2.0, v35
	v_mul_f32_e32 v34, 0x3fb8aa3b, v34
	v_mul_f32_e32 v35, 0x3fb8aa3b, v35
	v_exp_f32_e32 v34, v34
	v_exp_f32_e32 v35, v35
	v_cvt_pk_bf16_f32 v39, v32, v33
	v_or_b32_e32 v32, 8, v48
	v_ashrrev_i32_e32 v33, 31, v32
	v_add_f32_e32 v34, 1.0, v34
	v_add_f32_e32 v35, 1.0, v35
	v_lshlrev_b64 v[32:33], 5, v[32:33]
	v_rcp_f32_e32 v34, v34
	v_rcp_f32_e32 v35, v35
	v_lshl_add_u64 v[32:33], s[16:17], 0, v[32:33]
	v_lshl_add_u64 v[32:33], v[32:33], 0, v[136:137]
	global_store_dwordx4 v[32:33], v[36:39], off nt
	v_mul_f32_e32 v33, 0x3d372713, v30
	v_pk_mul_f32 v[28:29], v[28:29], v[34:35]
	v_mul_f32_e32 v33, v30, v33
	v_mul_f32_e32 v34, 0x3d372713, v31
	v_fma_f32 v33, v30, v33, v30
	v_mul_f32_e32 v34, v31, v34
	v_mul_f32_e32 v33, 0x3f4c422a, v33
	v_fma_f32 v34, v31, v34, v31
	v_mul_f32_e32 v33, -2.0, v33
	v_mul_f32_e32 v34, 0x3f4c422a, v34
	v_mul_f32_e32 v33, 0x3fb8aa3b, v33
	v_mul_f32_e32 v34, -2.0, v34
	v_exp_f32_e32 v33, v33
	v_mul_f32_e32 v34, 0x3fb8aa3b, v34
	v_exp_f32_e32 v35, v34
	v_cvt_pk_bf16_f32 v28, v28, v29
	v_add_f32_e32 v29, 1.0, v33
	v_rcp_f32_e32 v34, v29
	v_add_f32_e32 v29, 1.0, v35
	v_rcp_f32_e32 v35, v29
	v_mul_f32_e32 v29, 0x3d372713, v24
	v_mul_f32_e32 v29, v24, v29
	v_mul_f32_e32 v33, 0x3d372713, v25
	v_fma_f32 v29, v24, v29, v24
	v_mul_f32_e32 v33, v25, v33
	v_mul_f32_e32 v29, 0x3f4c422a, v29
	v_fma_f32 v33, v25, v33, v25
	v_mul_f32_e32 v29, -2.0, v29
	v_mul_f32_e32 v33, 0x3f4c422a, v33
	v_mul_f32_e32 v29, 0x3fb8aa3b, v29
	v_mul_f32_e32 v33, -2.0, v33
	v_exp_f32_e32 v29, v29
	v_mul_f32_e32 v33, 0x3fb8aa3b, v33
	v_exp_f32_e32 v33, v33
	v_pk_mul_f32 v[30:31], v[30:31], v[34:35]
	v_add_f32_e32 v29, 1.0, v29
	v_rcp_f32_e32 v34, v29
	v_add_f32_e32 v29, 1.0, v33
	v_mul_f32_e32 v33, 0x3d372713, v26
	v_mul_f32_e32 v33, v26, v33
	v_mul_f32_e32 v35, 0x3d372713, v27
	v_fma_f32 v33, v26, v33, v26
	v_mul_f32_e32 v35, v27, v35
	v_mul_f32_e32 v33, 0x3f4c422a, v33
	v_fma_f32 v35, v27, v35, v27
	v_mul_f32_e32 v33, -2.0, v33
	v_mul_f32_e32 v35, 0x3f4c422a, v35
	v_mul_f32_e32 v33, 0x3fb8aa3b, v33
	v_mul_f32_e32 v35, -2.0, v35
	v_exp_f32_e32 v33, v33
	v_mul_f32_e32 v35, 0x3fb8aa3b, v35
	v_exp_f32_e32 v37, v35
	v_rcp_f32_e32 v35, v29
	v_add_f32_e32 v29, 1.0, v33
	v_rcp_f32_e32 v36, v29
	v_add_f32_e32 v29, 1.0, v37
	v_rcp_f32_e32 v37, v29
	v_pk_mul_f32 v[24:25], v[24:25], v[34:35]
	v_cvt_pk_bf16_f32 v29, v30, v31
	v_cvt_pk_bf16_f32 v30, v24, v25
	v_pk_mul_f32 v[24:25], v[26:27], v[36:37]
	v_add_u32_e32 v32, v151, v144
	v_cvt_pk_bf16_f32 v31, v24, v25
	v_mul_f32_e32 v24, 0x3d372713, v20
	v_mul_f32_e32 v24, v20, v24
	v_fma_f32 v24, v20, v24, v20
	v_mul_f32_e32 v24, 0x3f4c422a, v24
	v_mul_f32_e32 v24, -2.0, v24
	v_mul_f32_e32 v24, 0x3fb8aa3b, v24
	v_exp_f32_e32 v26, v24
	v_mul_f32_e32 v24, 0x3d372713, v21
	v_mul_f32_e32 v24, v21, v24
	v_fma_f32 v24, v21, v24, v21
	v_mul_f32_e32 v24, 0x3f4c422a, v24
	v_mul_f32_e32 v24, -2.0, v24
	v_ashrrev_i32_e32 v33, 31, v32
	v_mul_f32_e32 v24, 0x3fb8aa3b, v24
	v_exp_f32_e32 v27, v24
	v_lshlrev_b64 v[24:25], 5, v[32:33]
	v_lshl_add_u64 v[24:25], s[16:17], 0, v[24:25]
	v_lshl_add_u64 v[24:25], v[24:25], 0, v[136:137]
	global_store_dwordx4 v[24:25], v[28:31], off nt
	v_mul_f32_e32 v24, 0x3d372713, v22
	v_mul_f32_e32 v24, v22, v24
	v_mul_f32_e32 v25, 0x3d372713, v23
	v_fma_f32 v24, v22, v24, v22
	v_mul_f32_e32 v25, v23, v25
	v_mul_f32_e32 v24, 0x3f4c422a, v24
	v_fma_f32 v25, v23, v25, v23
	v_add_f32_e32 v26, 1.0, v26
	v_add_f32_e32 v27, 1.0, v27
	v_mul_f32_e32 v24, -2.0, v24
	v_mul_f32_e32 v25, 0x3f4c422a, v25
	v_rcp_f32_e32 v26, v26
	v_rcp_f32_e32 v27, v27
	v_mul_f32_e32 v24, 0x3fb8aa3b, v24
	v_mul_f32_e32 v25, -2.0, v25
	v_exp_f32_e32 v24, v24
	v_mul_f32_e32 v25, 0x3fb8aa3b, v25
	v_exp_f32_e32 v25, v25
	v_pk_mul_f32 v[20:21], v[20:21], v[26:27]
	v_mul_f32_e32 v26, 0x3d372713, v17
	v_cvt_pk_bf16_f32 v20, v20, v21
	v_add_f32_e32 v21, 1.0, v24
	v_rcp_f32_e32 v24, v21
	v_add_f32_e32 v21, 1.0, v25
	v_rcp_f32_e32 v25, v21
	v_mul_f32_e32 v21, 0x3d372713, v16
	v_mul_f32_e32 v21, v16, v21
	v_fma_f32 v21, v16, v21, v16
	v_mul_f32_e32 v26, v17, v26
	v_mul_f32_e32 v21, 0x3f4c422a, v21
	v_fma_f32 v26, v17, v26, v17
	v_mul_f32_e32 v21, -2.0, v21
	v_mul_f32_e32 v26, 0x3f4c422a, v26
	v_mul_f32_e32 v21, 0x3fb8aa3b, v21
	v_mul_f32_e32 v26, -2.0, v26
	v_pk_mul_f32 v[22:23], v[22:23], v[24:25]
	v_mul_f32_e32 v25, 0x3d372713, v18
	v_exp_f32_e32 v21, v21
	v_mul_f32_e32 v26, 0x3fb8aa3b, v26
	v_mul_f32_e32 v25, v18, v25
	v_exp_f32_e32 v26, v26
	v_fma_f32 v25, v18, v25, v18
	v_mul_f32_e32 v25, 0x3f4c422a, v25
	v_mul_f32_e32 v25, -2.0, v25
	v_add_f32_e32 v21, 1.0, v21
	v_mul_f32_e32 v25, 0x3fb8aa3b, v25
	v_rcp_f32_e32 v24, v21
	v_add_f32_e32 v21, 1.0, v26
	v_exp_f32_e32 v26, v25
	v_mul_f32_e32 v25, 0x3d372713, v19
	v_mul_f32_e32 v25, v19, v25
	v_fma_f32 v25, v19, v25, v19
	v_mul_f32_e32 v25, 0x3f4c422a, v25
	v_mul_f32_e32 v25, -2.0, v25
	v_mul_f32_e32 v25, 0x3fb8aa3b, v25
	v_exp_f32_e32 v27, v25
	v_rcp_f32_e32 v25, v21
	v_add_f32_e32 v21, 1.0, v26
	v_rcp_f32_e32 v26, v21
	v_add_f32_e32 v21, 1.0, v27
	v_rcp_f32_e32 v27, v21
	v_pk_mul_f32 v[16:17], v[16:17], v[24:25]
	v_cvt_pk_bf16_f32 v21, v22, v23
	v_cvt_pk_bf16_f32 v22, v16, v17
	v_pk_mul_f32 v[16:17], v[18:19], v[26:27]
	v_mul_f32_e32 v18, 0x3d372713, v12
	v_mul_f32_e32 v19, 0x3d372713, v13
	v_mul_f32_e32 v18, v12, v18
	v_mul_f32_e32 v19, v13, v19
	v_fma_f32 v18, v12, v18, v12
	v_fma_f32 v19, v13, v19, v13
	v_mul_f32_e32 v18, 0x3f4c422a, v18
; __host__ __device__ __forceinline__ size_t ys_off(int m, int ch) { return ((size_t)(ch >> 4) * PT + m) * 16 + (ch & 15); }
; __device__ __forceinline__ unsigned pk2(float lo, float hi) { typedef __bf16 bf16x2_t_ __attribute__((ext_vector_type(2))); f32x2 v = {lo, hi}; return __builtin_bit_cast(unsigned, __builtin_convertvector(v, bf16x2_t_)); }
; __device__ __forceinline__ float gelu_tanh(float x) { const float z = 0.7978845608028654f * (x + 0.044715f * x * x * x); return x * __builtin_amdgcn_rcpf(1.f + __expf(-2.f * z)); }
;     __device__ __forceinline__ void operator()(const f32x4 (&acc)[2][2][4][2], const pg8::Unit& u, int wr, int wc, int fr, int fq) const {
;     ...
;         for (int ai = 0; ai < 2; ++ai)
; #pragma unroll
;             for (int m = 0; m < 4; ++m) {
;                 const int row = u.pm * 256 + ai * 128 + wr * 64 + m * 16 + fr;
; #pragma unroll
;                 for (int bj = 0; bj < 2; ++bj) {
;                     const int t = 8 * bj + 2 * wc + (fq >> 1), p0 = 8 * (fq & 1);
;                     const f32x4 a = acc[ai][bj][m][0], b = acc[ai][bj][m][1];
;                     u32x4 w; w.x = pk2(gelu_tanh(a[0]), gelu_tanh(a[1])); w.y = pk2(gelu_tanh(a[2]), gelu_tanh(a[3])); w.z = pk2(gelu_tanh(b[0]), gelu_tanh(b[1])); w.w = pk2(gelu_tanh(b[2]), gelu_tanh(b[3]));
;                     *(u32x4*)(YS_ + ys_off(row * CL + t, u.g * 16 + p0)) = w;
;                 }
	v_mul_f32_e32 v19, 0x3f4c422a, v19
	v_mul_f32_e32 v18, -2.0, v18
	v_mul_f32_e32 v19, -2.0, v19
	v_mul_f32_e32 v18, 0x3fb8aa3b, v18
	v_mul_f32_e32 v19, 0x3fb8aa3b, v19
	v_exp_f32_e32 v18, v18
	v_exp_f32_e32 v19, v19
	v_cvt_pk_bf16_f32 v23, v16, v17
	v_or_b32_e32 v16, 8, v32
	v_ashrrev_i32_e32 v17, 31, v16
	v_add_f32_e32 v18, 1.0, v18
	v_add_f32_e32 v19, 1.0, v19
	v_lshlrev_b64 v[16:17], 5, v[16:17]
	v_rcp_f32_e32 v18, v18
	v_rcp_f32_e32 v19, v19
	v_lshl_add_u64 v[16:17], s[16:17], 0, v[16:17]
	v_lshl_add_u64 v[16:17], v[16:17], 0, v[136:137]
	global_store_dwordx4 v[16:17], v[20:23], off nt
	v_mul_f32_e32 v17, 0x3d372713, v14
	v_pk_mul_f32 v[12:13], v[12:13], v[18:19]
	v_mul_f32_e32 v17, v14, v17
	v_mul_f32_e32 v18, 0x3d372713, v15
	v_fma_f32 v17, v14, v17, v14
	v_mul_f32_e32 v18, v15, v18
	v_mul_f32_e32 v17, 0x3f4c422a, v17
	v_fma_f32 v18, v15, v18, v15
	v_mul_f32_e32 v17, -2.0, v17
	v_mul_f32_e32 v18, 0x3f4c422a, v18
	v_mul_f32_e32 v17, 0x3fb8aa3b, v17
	v_mul_f32_e32 v18, -2.0, v18
	v_exp_f32_e32 v17, v17
	v_mul_f32_e32 v18, 0x3fb8aa3b, v18
	v_exp_f32_e32 v19, v18
	v_cvt_pk_bf16_f32 v12, v12, v13
	v_add_f32_e32 v13, 1.0, v17
	v_rcp_f32_e32 v18, v13
	v_add_f32_e32 v13, 1.0, v19
	v_rcp_f32_e32 v19, v13
	v_mul_f32_e32 v13, 0x3d372713, v8
	v_mul_f32_e32 v13, v8, v13
	v_mul_f32_e32 v17, 0x3d372713, v9
	v_fma_f32 v13, v8, v13, v8
	v_mul_f32_e32 v17, v9, v17
	v_mul_f32_e32 v13, 0x3f4c422a, v13
	v_fma_f32 v17, v9, v17, v9
	v_mul_f32_e32 v13, -2.0, v13
	v_mul_f32_e32 v17, 0x3f4c422a, v17
	v_mul_f32_e32 v13, 0x3fb8aa3b, v13
	v_mul_f32_e32 v17, -2.0, v17
	v_exp_f32_e32 v13, v13
	v_mul_f32_e32 v17, 0x3fb8aa3b, v17
	v_exp_f32_e32 v17, v17
	v_pk_mul_f32 v[14:15], v[14:15], v[18:19]
	v_add_f32_e32 v13, 1.0, v13
	v_rcp_f32_e32 v18, v13
	v_add_f32_e32 v13, 1.0, v17
	v_mul_f32_e32 v17, 0x3d372713, v10
	v_mul_f32_e32 v17, v10, v17
	v_mul_f32_e32 v19, 0x3d372713, v11
	v_fma_f32 v17, v10, v17, v10
	v_mul_f32_e32 v19, v11, v19
	v_mul_f32_e32 v17, 0x3f4c422a, v17
	v_fma_f32 v19, v11, v19, v11
	v_mul_f32_e32 v17, -2.0, v17
	v_mul_f32_e32 v19, 0x3f4c422a, v19
	v_mul_f32_e32 v17, 0x3fb8aa3b, v17
	v_mul_f32_e32 v19, -2.0, v19
	v_exp_f32_e32 v17, v17
	v_mul_f32_e32 v19, 0x3fb8aa3b, v19
	v_exp_f32_e32 v21, v19
	v_rcp_f32_e32 v19, v13
	v_add_f32_e32 v13, 1.0, v17
	v_rcp_f32_e32 v20, v13
	v_add_f32_e32 v13, 1.0, v21
	v_rcp_f32_e32 v21, v13
	v_pk_mul_f32 v[8:9], v[8:9], v[18:19]
	v_cvt_pk_bf16_f32 v13, v14, v15
	v_cvt_pk_bf16_f32 v14, v8, v9
	v_pk_mul_f32 v[8:9], v[10:11], v[20:21]
	v_add_u32_e32 v16, v151, v145
	v_cvt_pk_bf16_f32 v15, v8, v9
	v_mul_f32_e32 v8, 0x3d372713, v4
	v_mul_f32_e32 v8, v4, v8
	v_fma_f32 v8, v4, v8, v4
	v_mul_f32_e32 v8, 0x3f4c422a, v8
	v_mul_f32_e32 v8, -2.0, v8
	v_mul_f32_e32 v8, 0x3fb8aa3b, v8
	v_exp_f32_e32 v10, v8
	v_mul_f32_e32 v8, 0x3d372713, v5
	v_mul_f32_e32 v8, v5, v8
	v_fma_f32 v8, v5, v8, v5
	v_mul_f32_e32 v8, 0x3f4c422a, v8
	v_mul_f32_e32 v8, -2.0, v8
	v_ashrrev_i32_e32 v17, 31, v16
	v_mul_f32_e32 v8, 0x3fb8aa3b, v8
	v_exp_f32_e32 v11, v8
	v_lshlrev_b64 v[8:9], 5, v[16:17]
	v_lshl_add_u64 v[8:9], s[16:17], 0, v[8:9]
	v_lshl_add_u64 v[8:9], v[8:9], 0, v[136:137]
	global_store_dwordx4 v[8:9], v[12:15], off nt
	v_mul_f32_e32 v8, 0x3d372713, v6
	v_mul_f32_e32 v8, v6, v8
	v_mul_f32_e32 v9, 0x3d372713, v7
	v_fma_f32 v8, v6, v8, v6
	v_mul_f32_e32 v9, v7, v9
	v_mul_f32_e32 v8, 0x3f4c422a, v8
	v_fma_f32 v9, v7, v9, v7
	v_add_f32_e32 v10, 1.0, v10
	v_add_f32_e32 v11, 1.0, v11
	v_mul_f32_e32 v8, -2.0, v8
	v_mul_f32_e32 v9, 0x3f4c422a, v9
	v_rcp_f32_e32 v10, v10
	v_rcp_f32_e32 v11, v11
	v_mul_f32_e32 v8, 0x3fb8aa3b, v8
	v_mul_f32_e32 v9, -2.0, v9
	v_exp_f32_e32 v8, v8
	v_mul_f32_e32 v9, 0x3fb8aa3b, v9
	v_exp_f32_e32 v9, v9
	v_pk_mul_f32 v[4:5], v[4:5], v[10:11]
	v_mul_f32_e32 v10, 0x3d372713, v1
	v_cvt_pk_bf16_f32 v4, v4, v5
	v_add_f32_e32 v5, 1.0, v8
	v_rcp_f32_e32 v8, v5
	v_add_f32_e32 v5, 1.0, v9
	v_rcp_f32_e32 v9, v5
	v_mul_f32_e32 v5, 0x3d372713, v0
	v_mul_f32_e32 v5, v0, v5
	v_fma_f32 v5, v0, v5, v0
	v_mul_f32_e32 v10, v1, v10
	v_mul_f32_e32 v5, 0x3f4c422a, v5
	v_fma_f32 v10, v1, v10, v1
	v_mul_f32_e32 v5, -2.0, v5
	v_mul_f32_e32 v10, 0x3f4c422a, v10
	v_mul_f32_e32 v5, 0x3fb8aa3b, v5
	v_mul_f32_e32 v10, -2.0, v10
	v_pk_mul_f32 v[6:7], v[6:7], v[8:9]
	v_mul_f32_e32 v9, 0x3d372713, v2
	v_exp_f32_e32 v5, v5
	v_mul_f32_e32 v10, 0x3fb8aa3b, v10
	v_mul_f32_e32 v9, v2, v9
	v_exp_f32_e32 v10, v10
	v_fma_f32 v9, v2, v9, v2
	v_mul_f32_e32 v9, 0x3f4c422a, v9
	v_mul_f32_e32 v9, -2.0, v9
	v_add_f32_e32 v5, 1.0, v5
	v_mul_f32_e32 v9, 0x3fb8aa3b, v9
	v_rcp_f32_e32 v8, v5
	v_add_f32_e32 v5, 1.0, v10
	v_exp_f32_e32 v10, v9
	v_mul_f32_e32 v9, 0x3d372713, v3
	v_mul_f32_e32 v9, v3, v9
	v_fma_f32 v9, v3, v9, v3
	v_mul_f32_e32 v9, 0x3f4c422a, v9
	v_mul_f32_e32 v9, -2.0, v9
	v_mul_f32_e32 v9, 0x3fb8aa3b, v9
	v_exp_f32_e32 v11, v9
	v_rcp_f32_e32 v9, v5
	v_add_f32_e32 v5, 1.0, v10
	v_rcp_f32_e32 v10, v5
	v_add_f32_e32 v5, 1.0, v11
	v_rcp_f32_e32 v11, v5
	v_pk_mul_f32 v[0:1], v[0:1], v[8:9]
	v_cvt_pk_bf16_f32 v5, v6, v7
	v_cvt_pk_bf16_f32 v6, v0, v1
	v_pk_mul_f32 v[0:1], v[2:3], v[10:11]
	s_andn2_b64 vcc, exec, s[38:39]
	v_cvt_pk_bf16_f32 v7, v0, v1
	v_or_b32_e32 v0, 8, v16
	v_ashrrev_i32_e32 v1, 31, v0
	v_lshlrev_b64 v[0:1], 5, v[0:1]
	v_lshl_add_u64 v[0:1], s[16:17], 0, v[0:1]
	v_lshl_add_u64 v[0:1], v[0:1], 0, v[136:137]
	s_mov_b64 s[16:17], -1
	global_store_dwordx4 v[0:1], v[4:7], off nt
	s_cbranch_vccnz .LBB0_899
	s_andn2_b64 vcc, exec, s[6:7]
	s_cbranch_vccnz .LBB0_898
	s_barrier
	s_branch .LBB0_898

; __host__ __device__ __forceinline__ size_t ys_off(int m, int ch) { return ((size_t)(ch >> 4) * PT + m) * 16 + (ch & 15); }
; __device__ __forceinline__ unsigned pk2(float lo, float hi) { typedef __bf16 bf16x2_t_ __attribute__((ext_vector_type(2))); f32x2 v = {lo, hi}; return __builtin_bit_cast(unsigned, __builtin_convertvector(v, bf16x2_t_)); }
; __device__ __forceinline__ float sigmoidf_(float x) { return __builtin_amdgcn_rcpf(1.f + __expf(-x)); }
;     __device__ __forceinline__ void operator()(const f32x4 (&acc)[2][2][4][2], const pg8::Unit& u, int wr, int wc, int fr, int fq) const {
;     ...
;             const int col = u.pn * 256 + bj * 128 + wc * 32 + fq * 8;
;             const f32x4 b0 = *(const f32x4*)(bglu + col), b1 = *(const f32x4*)(bglu + col + 4);
; #pragma unroll
;             for (int ai = 0; ai < 2; ++ai) {
;                 u32x4 ysv[4], zsv[4];
; #pragma unroll
;                 for (int m = 0; m < 4; ++m) { const int row = u.pm * 256 + ai * 128 + wr * 64 + m * 16 + fr;
;                     ysv[m] = *(const u32x4*)(YS_ + ys_off(row, col)); zsv[m] = *(const u32x4*)(ZS_ + (size_t)row * 512 + col); }
;                 asm volatile("" ::: "memory");
; #pragma unroll
;                 for (int m = 0; m < 4; ++m) {
;                     const int row = u.pm * 256 + ai * 128 + wr * 64 + m * 16 + fr;
;                     const u32x4 ys = ysv[m], zs = zsv[m];
;                     const f32x4 a = acc[ai][bj][m][0] + b0, b = acc[ai][bj][m][1] + b1;
;                     u32x4 w;
;                     w.x = pk2(bflo(ys.x) * sigmoidf_(a[0]) * bflo(zs.x), bfhi(ys.x) * sigmoidf_(a[1]) * bfhi(zs.x));
;                     w.y = pk2(bflo(ys.y) * sigmoidf_(a[2]) * bflo(zs.y), bfhi(ys.y) * sigmoidf_(a[3]) * bfhi(zs.y));
;                     w.z = pk2(bflo(ys.z) * sigmoidf_(b[0]) * bflo(zs.z), bfhi(ys.z) * sigmoidf_(b[1]) * bfhi(zs.z));
;                     w.w = pk2(bflo(ys.w) * sigmoidf_(b[2]) * bflo(zs.w), bfhi(ys.w) * sigmoidf_(b[3]) * bfhi(zs.w));
;                     *(u32x4*)(MX_ + (size_t)row * 1024 + col) = w;
.LBB0_977:
	v_lshl_or_b32 v174, s49, 8, v211
	v_ashrrev_i32_e32 v175, 31, v174
	v_lshl_add_u64 v[176:177], v[174:175], 2, s[86:87]
	global_load_dwordx4 v[116:119], v[176:177], off
	global_load_dwordx4 v[112:115], v[176:177], off offset:16
	v_ashrrev_i32_e32 v136, 4, v174
	v_lshl_add_u32 v196, s24, 8, v209
	v_ashrrev_i32_e32 v137, 31, v136
	v_ashrrev_i32_e32 v197, 31, v196
	v_lshlrev_b64 v[136:137], 21, v[136:137]
	v_lshlrev_b64 v[182:183], 1, v[174:175]
	v_lshlrev_b64 v[178:179], 5, v[196:197]
	v_lshl_add_u64 v[200:201], v[164:165], 0, v[136:137]
	v_lshlrev_b64 v[180:181], 10, v[196:197]
	v_lshl_add_u64 v[198:199], s[18:19], 0, v[182:183]
	v_lshl_add_u64 v[136:137], v[200:201], 0, v[178:179]
	global_load_dwordx4 v[216:219], v[136:137], off
	v_lshl_add_u64 v[136:137], v[198:199], 0, v[180:181]
	global_load_dwordx4 v[220:223], v[136:137], off
	v_or_b32_e32 v206, 16, v196
	v_or_b32_e32 v204, 32, v196
	v_or_b32_e32 v202, 48, v196
	v_ashrrev_i32_e32 v207, 31, v206
	v_ashrrev_i32_e32 v205, 31, v204
	v_ashrrev_i32_e32 v203, 31, v202
	v_lshlrev_b64 v[194:195], 5, v[206:207]
	v_lshlrev_b64 v[192:193], 10, v[206:207]
	v_lshlrev_b64 v[190:191], 5, v[204:205]
	v_lshlrev_b64 v[186:187], 10, v[204:205]
	v_lshlrev_b64 v[184:185], 5, v[202:203]
	v_lshlrev_b64 v[188:189], 10, v[202:203]
	v_lshl_add_u64 v[136:137], v[198:199], 0, v[192:193]
	v_lshl_add_u64 v[138:139], v[198:199], 0, v[186:187]
	v_lshl_add_u64 v[140:141], v[200:201], 0, v[194:195]
	v_lshl_add_u64 v[142:143], v[200:201], 0, v[190:191]
	v_lshl_add_u64 v[228:229], v[198:199], 0, v[188:189]
	v_lshl_add_u64 v[230:231], v[200:201], 0, v[184:185]
	global_load_dwordx4 v[224:227], v[140:141], off
	global_load_dwordx4 v[152:155], v[136:137], off
	global_load_dwordx4 v[148:151], v[142:143], off
	global_load_dwordx4 v[144:147], v[138:139], off
	s_nop 0
	global_load_dwordx4 v[140:143], v[230:231], off
	global_load_dwordx4 v[136:139], v[228:229], off
	s_andn2_b64 vcc, exec, s[0:1]
	s_mov_b64 s[0:1], -1
	s_waitcnt vmcnt(0)
	v_pk_add_f32 v[132:133], v[132:133], v[116:117]
	v_pk_add_f32 v[134:135], v[134:135], v[118:119]
	v_mul_f32_e32 v132, 0xbfb8aa3b, v132
	v_mul_f32_e32 v133, 0xbfb8aa3b, v133
	v_mul_f32_e32 v134, 0xbfb8aa3b, v134
	v_mul_f32_e32 v135, 0xbfb8aa3b, v135
	v_exp_f32_e32 v175, v132
	v_exp_f32_e32 v215, v133
	v_exp_f32_e32 v228, v134
	v_exp_f32_e32 v229, v135
	v_pk_add_f32 v[128:129], v[128:129], v[112:113]
	v_pk_add_f32 v[130:131], v[130:131], v[114:115]
	v_mul_f32_e32 v128, 0xbfb8aa3b, v128
	v_mul_f32_e32 v129, 0xbfb8aa3b, v129
	v_mul_f32_e32 v130, 0xbfb8aa3b, v130
	v_mul_f32_e32 v131, 0xbfb8aa3b, v131
	v_exp_f32_e32 v230, v128
	v_exp_f32_e32 v231, v129
	v_add_f32_e32 v175, 1.0, v175
	v_add_f32_e32 v215, 1.0, v215
	v_exp_f32_e32 v234, v130
	v_exp_f32_e32 v235, v131
	v_lshlrev_b32_e32 v128, 16, v216
	v_and_b32_e32 v129, 0xffff0000, v216
	v_lshlrev_b32_e32 v130, 16, v220
	v_and_b32_e32 v131, 0xffff0000, v220
	v_lshlrev_b32_e32 v132, 16, v217
	v_and_b32_e32 v133, 0xffff0000, v217
	v_lshlrev_b32_e32 v134, 16, v221
	v_and_b32_e32 v135, 0xffff0000, v221
	v_lshlrev_b32_e32 v216, 16, v218
	v_and_b32_e32 v217, 0xffff0000, v218
	v_lshlrev_b32_e32 v220, 16, v222
	v_and_b32_e32 v221, 0xffff0000, v222
	v_add_f32_e32 v218, 1.0, v228
	v_add_f32_e32 v222, 1.0, v229
	v_rcp_f32_e32 v228, v175
	v_rcp_f32_e32 v229, v215
	v_add_f32_e32 v232, 1.0, v230
	v_add_f32_e32 v233, 1.0, v231
	v_rcp_f32_e32 v230, v218
	v_rcp_f32_e32 v231, v222
	v_rcp_f32_e32 v232, v232
	v_rcp_f32_e32 v233, v233
	v_pk_mul_f32 v[128:129], v[228:229], v[128:129]
	v_add_f32_e32 v175, 1.0, v234
	v_pk_mul_f32 v[128:129], v[128:129], v[130:131]
	v_pk_mul_f32 v[132:133], v[230:231], v[132:133]
	v_cvt_pk_bf16_f32 v130, v128, v129
	v_add_f32_e32 v129, 1.0, v235
	v_rcp_f32_e32 v128, v175
	v_rcp_f32_e32 v129, v129
	v_pk_mul_f32 v[216:217], v[232:233], v[216:217]
	v_pk_mul_f32 v[132:133], v[132:133], v[134:135]
	v_pk_mul_f32 v[134:135], v[216:217], v[220:221]
	v_cvt_pk_bf16_f32 v131, v132, v133
	v_cvt_pk_bf16_f32 v132, v134, v135
	v_lshlrev_b32_e32 v134, 16, v219
	v_and_b32_e32 v135, 0xffff0000, v219
	v_pk_mul_f32 v[128:129], v[128:129], v[134:135]
	v_lshlrev_b32_e32 v134, 16, v223
	v_and_b32_e32 v135, 0xffff0000, v223
	v_pk_mul_f32 v[128:129], v[128:129], v[134:135]
	v_pk_add_f32 v[124:125], v[124:125], v[116:117]
	v_cvt_pk_bf16_f32 v133, v128, v129
	v_lshlrev_b64 v[128:129], 11, v[196:197]
	v_lshl_add_u64 v[128:129], s[40:41], 0, v[128:129]
	v_lshl_add_u64 v[128:129], v[128:129], 0, v[182:183]
	v_mul_f32_e32 v124, 0xbfb8aa3b, v124
	global_store_dwordx4 v[128:129], v[130:133], off nt
	v_pk_add_f32 v[126:127], v[126:127], v[118:119]
	v_pk_add_f32 v[120:121], v[120:121], v[112:113]
	v_exp_f32_e32 v130, v124
	v_mul_f32_e32 v124, 0xbfb8aa3b, v125
	v_exp_f32_e32 v131, v124
	v_pk_add_f32 v[124:125], v[122:123], v[114:115]
	v_add_f32_e32 v122, 1.0, v130
	v_rcp_f32_e32 v122, v122
	v_add_f32_e32 v123, 1.0, v131
	v_rcp_f32_e32 v123, v123
	v_mul_f32_e32 v126, 0xbfb8aa3b, v126
	v_mul_f32_e32 v127, 0xbfb8aa3b, v127
	v_exp_f32_e32 v126, v126
	v_exp_f32_e32 v127, v127
	v_lshlrev_b32_e32 v130, 16, v224
	v_and_b32_e32 v131, 0xffff0000, v224
	v_pk_mul_f32 v[122:123], v[122:123], v[130:131]
	v_lshlrev_b32_e32 v130, 16, v152
	v_and_b32_e32 v131, 0xffff0000, v152
	v_pk_mul_f32 v[122:123], v[122:123], v[130:131]
	v_add_f32_e32 v126, 1.0, v126
	v_add_f32_e32 v127, 1.0, v127
	v_mul_f32_e32 v120, 0xbfb8aa3b, v120
	v_rcp_f32_e32 v126, v126
	v_rcp_f32_e32 v127, v127
	v_cvt_pk_bf16_f32 v122, v122, v123
	v_exp_f32_e32 v123, v120
	v_mul_f32_e32 v120, 0xbfb8aa3b, v121
	v_exp_f32_e32 v132, v120
	v_lshlrev_b32_e32 v130, 16, v225
	v_and_b32_e32 v131, 0xffff0000, v225
; __device__ __forceinline__ unsigned pk2(float lo, float hi) { typedef __bf16 bf16x2_t_ __attribute__((ext_vector_type(2))); f32x2 v = {lo, hi}; return __builtin_bit_cast(unsigned, __builtin_convertvector(v, bf16x2_t_)); }
; __device__ __forceinline__ float sigmoidf_(float x) { return __builtin_amdgcn_rcpf(1.f + __expf(-x)); }
;     __device__ __forceinline__ void operator()(const f32x4 (&acc)[2][2][4][2], const pg8::Unit& u, int wr, int wc, int fr, int fq) const {
;     ...
;                 for (int m = 0; m < 4; ++m) {
;                     const int row = u.pm * 256 + ai * 128 + wr * 64 + m * 16 + fr;
;                     const u32x4 ys = ysv[m], zs = zsv[m];
;                     const f32x4 a = acc[ai][bj][m][0] + b0, b = acc[ai][bj][m][1] + b1;
;                     u32x4 w;
;                     w.x = pk2(bflo(ys.x) * sigmoidf_(a[0]) * bflo(zs.x), bfhi(ys.x) * sigmoidf_(a[1]) * bfhi(zs.x));
;                     w.y = pk2(bflo(ys.y) * sigmoidf_(a[2]) * bflo(zs.y), bfhi(ys.y) * sigmoidf_(a[3]) * bfhi(zs.y));
;                     w.z = pk2(bflo(ys.z) * sigmoidf_(b[0]) * bflo(zs.z), bfhi(ys.z) * sigmoidf_(b[1]) * bfhi(zs.z));
;                     w.w = pk2(bflo(ys.w) * sigmoidf_(b[2]) * bflo(zs.w), bfhi(ys.w) * sigmoidf_(b[3]) * bfhi(zs.w));
;                     *(u32x4*)(MX_ + (size_t)row * 1024 + col) = w;
	v_pk_mul_f32 v[126:127], v[126:127], v[130:131]
	v_lshlrev_b32_e32 v130, 16, v153
	v_and_b32_e32 v131, 0xffff0000, v153
	v_add_f32_e32 v123, 1.0, v123
	v_pk_mul_f32 v[120:121], v[126:127], v[130:131]
	v_rcp_f32_e32 v126, v123
	v_add_f32_e32 v123, 1.0, v132
	v_mul_f32_e32 v124, 0xbfb8aa3b, v124
	v_rcp_f32_e32 v127, v123
	v_exp_f32_e32 v124, v124
	v_mul_f32_e32 v125, 0xbfb8aa3b, v125
	v_exp_f32_e32 v125, v125
	v_cvt_pk_bf16_f32 v123, v120, v121
	v_lshlrev_b32_e32 v120, 16, v226
	v_and_b32_e32 v121, 0xffff0000, v226
	v_pk_mul_f32 v[120:121], v[126:127], v[120:121]
	v_lshlrev_b32_e32 v126, 16, v154
	v_and_b32_e32 v127, 0xffff0000, v154
	v_add_f32_e32 v124, 1.0, v124
	v_pk_mul_f32 v[120:121], v[120:121], v[126:127]
	v_rcp_f32_e32 v126, v124
	v_add_f32_e32 v124, 1.0, v125
	v_pk_add_f32 v[108:109], v[108:109], v[116:117]
	v_rcp_f32_e32 v127, v124
	v_mul_f32_e32 v108, 0xbfb8aa3b, v108
	v_mul_f32_e32 v109, 0xbfb8aa3b, v109
	v_exp_f32_e32 v108, v108
	v_exp_f32_e32 v109, v109
	v_cvt_pk_bf16_f32 v124, v120, v121
	v_lshlrev_b32_e32 v120, 16, v227
	v_and_b32_e32 v121, 0xffff0000, v227
	v_pk_mul_f32 v[120:121], v[126:127], v[120:121]
	v_lshlrev_b32_e32 v126, 16, v155
	v_and_b32_e32 v127, 0xffff0000, v155
	v_pk_mul_f32 v[120:121], v[120:121], v[126:127]
	v_add_f32_e32 v108, 1.0, v108
	v_add_f32_e32 v109, 1.0, v109
	v_cvt_pk_bf16_f32 v125, v120, v121
	v_lshlrev_b64 v[120:121], 11, v[206:207]
	v_pk_add_f32 v[110:111], v[110:111], v[118:119]
	v_rcp_f32_e32 v108, v108
	v_rcp_f32_e32 v109, v109
	v_lshl_add_u64 v[120:121], s[40:41], 0, v[120:121]
	v_mul_f32_e32 v110, 0xbfb8aa3b, v110
	v_mul_f32_e32 v111, 0xbfb8aa3b, v111
	v_lshl_add_u64 v[120:121], v[120:121], 0, v[182:183]
	v_exp_f32_e32 v110, v110
	v_exp_f32_e32 v111, v111
	global_store_dwordx4 v[120:121], v[122:125], off nt
	v_pk_add_f32 v[106:107], v[106:107], v[114:115]
	v_pk_add_f32 v[100:101], v[100:101], v[116:117]
	v_pk_add_f32 v[122:123], v[104:105], v[112:113]
	v_lshlrev_b32_e32 v104, 16, v148
	v_and_b32_e32 v105, 0xffff0000, v148
	v_pk_mul_f32 v[104:105], v[108:109], v[104:105]
	v_lshlrev_b32_e32 v108, 16, v144
	v_and_b32_e32 v109, 0xffff0000, v144
	v_pk_mul_f32 v[104:105], v[104:105], v[108:109]
	v_add_f32_e32 v108, 1.0, v110
	v_add_f32_e32 v109, 1.0, v111
	v_cvt_pk_bf16_f32 v104, v104, v105
	v_mul_f32_e32 v105, 0xbfb8aa3b, v122
	v_rcp_f32_e32 v108, v108
	v_rcp_f32_e32 v109, v109
	v_exp_f32_e32 v105, v105
	v_mul_f32_e32 v122, 0xbfb8aa3b, v123
	v_exp_f32_e32 v122, v122
	v_lshlrev_b32_e32 v110, 16, v149
	v_and_b32_e32 v111, 0xffff0000, v149
	v_pk_mul_f32 v[108:109], v[108:109], v[110:111]
	v_lshlrev_b32_e32 v110, 16, v145
	v_and_b32_e32 v111, 0xffff0000, v145
	v_add_f32_e32 v105, 1.0, v105
	v_pk_mul_f32 v[108:109], v[108:109], v[110:111]
	v_rcp_f32_e32 v110, v105
	v_add_f32_e32 v105, 1.0, v122
	v_mul_f32_e32 v106, 0xbfb8aa3b, v106
	v_rcp_f32_e32 v111, v105
	v_exp_f32_e32 v122, v106
	v_mul_f32_e32 v106, 0xbfb8aa3b, v107
	v_exp_f32_e32 v123, v106
	v_cvt_pk_bf16_f32 v105, v108, v109
	v_lshlrev_b32_e32 v108, 16, v150
	v_and_b32_e32 v109, 0xffff0000, v150
	v_pk_mul_f32 v[108:109], v[110:111], v[108:109]
	v_lshlrev_b32_e32 v110, 16, v146
	v_and_b32_e32 v111, 0xffff0000, v146
	v_pk_mul_f32 v[106:107], v[108:109], v[110:111]
	v_add_f32_e32 v108, 1.0, v122
	v_add_f32_e32 v109, 1.0, v123
	v_rcp_f32_e32 v108, v108
	v_rcp_f32_e32 v109, v109
	v_mul_f32_e32 v100, 0xbfb8aa3b, v100
	v_mul_f32_e32 v101, 0xbfb8aa3b, v101
	v_exp_f32_e32 v100, v100
	v_exp_f32_e32 v101, v101
	v_lshlrev_b32_e32 v110, 16, v151
	v_and_b32_e32 v111, 0xffff0000, v151
	v_pk_mul_f32 v[108:109], v[108:109], v[110:111]
	v_lshlrev_b32_e32 v110, 16, v147
	v_and_b32_e32 v111, 0xffff0000, v147
	v_pk_mul_f32 v[108:109], v[108:109], v[110:111]
	v_add_f32_e32 v100, 1.0, v100
	v_add_f32_e32 v101, 1.0, v101
	v_cvt_pk_bf16_f32 v106, v106, v107
	v_cvt_pk_bf16_f32 v107, v108, v109
	v_lshlrev_b64 v[108:109], 11, v[204:205]
	v_pk_add_f32 v[102:103], v[102:103], v[118:119]
	v_rcp_f32_e32 v100, v100
	v_rcp_f32_e32 v101, v101
	v_lshl_add_u64 v[108:109], s[40:41], 0, v[108:109]
	v_mul_f32_e32 v102, 0xbfb8aa3b, v102
	v_mul_f32_e32 v103, 0xbfb8aa3b, v103
	v_lshl_add_u64 v[122:123], v[108:109], 0, v[182:183]
	v_exp_f32_e32 v102, v102
	v_exp_f32_e32 v103, v103
	global_store_dwordx4 v[122:123], v[104:107], off nt
	v_pk_add_f32 v[98:99], v[98:99], v[114:115]
	v_add_u32_e32 v154, 0x80, v196
	v_pk_add_f32 v[104:105], v[96:97], v[112:113]
	v_lshlrev_b32_e32 v96, 16, v140
	v_and_b32_e32 v97, 0xffff0000, v140
	v_pk_mul_f32 v[96:97], v[100:101], v[96:97]
	v_lshlrev_b32_e32 v100, 16, v136
	v_and_b32_e32 v101, 0xffff0000, v136
	v_pk_mul_f32 v[96:97], v[96:97], v[100:101]
	v_add_f32_e32 v100, 1.0, v102
	v_add_f32_e32 v101, 1.0, v103
	v_cvt_pk_bf16_f32 v96, v96, v97
	v_mul_f32_e32 v97, 0xbfb8aa3b, v104
	v_rcp_f32_e32 v100, v100
	v_rcp_f32_e32 v101, v101
	v_exp_f32_e32 v97, v97
	v_mul_f32_e32 v104, 0xbfb8aa3b, v105
	v_exp_f32_e32 v104, v104
	v_lshlrev_b32_e32 v102, 16, v141
	v_and_b32_e32 v103, 0xffff0000, v141
	v_pk_mul_f32 v[100:101], v[100:101], v[102:103]
	v_lshlrev_b32_e32 v102, 16, v137
	v_and_b32_e32 v103, 0xffff0000, v137
	v_add_f32_e32 v97, 1.0, v97
	v_pk_mul_f32 v[100:101], v[100:101], v[102:103]
	v_rcp_f32_e32 v102, v97
	v_add_f32_e32 v97, 1.0, v104
	v_mul_f32_e32 v98, 0xbfb8aa3b, v98
	v_rcp_f32_e32 v103, v97
	v_exp_f32_e32 v104, v98
	v_mul_f32_e32 v98, 0xbfb8aa3b, v99
	v_exp_f32_e32 v105, v98
	v_cvt_pk_bf16_f32 v97, v100, v101
	v_lshlrev_b32_e32 v100, 16, v142
	v_and_b32_e32 v101, 0xffff0000, v142
	v_pk_mul_f32 v[100:101], v[102:103], v[100:101]
	v_lshlrev_b32_e32 v102, 16, v138
	v_and_b32_e32 v103, 0xffff0000, v138
	v_pk_mul_f32 v[98:99], v[100:101], v[102:103]
; __host__ __device__ __forceinline__ size_t ys_off(int m, int ch) { return ((size_t)(ch >> 4) * PT + m) * 16 + (ch & 15); }
; __device__ __forceinline__ unsigned pk2(float lo, float hi) { typedef __bf16 bf16x2_t_ __attribute__((ext_vector_type(2))); f32x2 v = {lo, hi}; return __builtin_bit_cast(unsigned, __builtin_convertvector(v, bf16x2_t_)); }
; __device__ __forceinline__ float sigmoidf_(float x) { return __builtin_amdgcn_rcpf(1.f + __expf(-x)); }
;     __device__ __forceinline__ void operator()(const f32x4 (&acc)[2][2][4][2], const pg8::Unit& u, int wr, int wc, int fr, int fq) const {
;     ...
;                 u32x4 ysv[4], zsv[4];
; #pragma unroll
;                 for (int m = 0; m < 4; ++m) { const int row = u.pm * 256 + ai * 128 + wr * 64 + m * 16 + fr;
;                     ysv[m] = *(const u32x4*)(YS_ + ys_off(row, col)); zsv[m] = *(const u32x4*)(ZS_ + (size_t)row * 512 + col); }
;                 asm volatile("" ::: "memory");
; #pragma unroll
;                 for (int m = 0; m < 4; ++m) {
;                     const int row = u.pm * 256 + ai * 128 + wr * 64 + m * 16 + fr;
;                     const u32x4 ys = ysv[m], zs = zsv[m];
;                     const f32x4 a = acc[ai][bj][m][0] + b0, b = acc[ai][bj][m][1] + b1;
;                     u32x4 w;
;                     w.x = pk2(bflo(ys.x) * sigmoidf_(a[0]) * bflo(zs.x), bfhi(ys.x) * sigmoidf_(a[1]) * bfhi(zs.x));
;                     w.y = pk2(bflo(ys.y) * sigmoidf_(a[2]) * bflo(zs.y), bfhi(ys.y) * sigmoidf_(a[3]) * bfhi(zs.y));
;                     w.z = pk2(bflo(ys.z) * sigmoidf_(b[0]) * bflo(zs.z), bfhi(ys.z) * sigmoidf_(b[1]) * bfhi(zs.z));
;                     w.w = pk2(bflo(ys.w) * sigmoidf_(b[2]) * bflo(zs.w), bfhi(ys.w) * sigmoidf_(b[3]) * bfhi(zs.w));
;                     *(u32x4*)(MX_ + (size_t)row * 1024 + col) = w;
	v_add_f32_e32 v100, 1.0, v104
	v_add_f32_e32 v101, 1.0, v105
	v_rcp_f32_e32 v100, v100
	v_rcp_f32_e32 v101, v101
	v_lshlrev_b32_e32 v102, 16, v143
	v_and_b32_e32 v103, 0xffff0000, v143
	v_cvt_pk_bf16_f32 v98, v98, v99
	v_pk_mul_f32 v[100:101], v[100:101], v[102:103]
	v_lshlrev_b32_e32 v102, 16, v139
	v_and_b32_e32 v103, 0xffff0000, v139
	v_pk_mul_f32 v[100:101], v[100:101], v[102:103]
	v_ashrrev_i32_e32 v155, 31, v154
	v_cvt_pk_bf16_f32 v99, v100, v101
	v_lshlrev_b64 v[100:101], 11, v[202:203]
	v_lshl_add_u64 v[100:101], s[40:41], 0, v[100:101]
	v_lshl_add_u64 v[124:125], v[100:101], 0, v[182:183]
	global_store_dwordx4 v[124:125], v[96:99], off nt
	v_lshlrev_b64 v[126:127], 5, v[154:155]
	v_lshlrev_b64 v[130:131], 10, v[154:155]
	v_lshl_add_u64 v[96:97], v[200:201], 0, v[126:127]
	global_load_dwordx4 v[150:153], v[96:97], off
	v_lshl_add_u64 v[96:97], v[198:199], 0, v[130:131]
	global_load_dwordx4 v[202:205], v[96:97], off
	v_add_u32_e32 v148, 0x90, v196
	v_ashrrev_i32_e32 v149, 31, v148
	v_lshlrev_b64 v[132:133], 5, v[148:149]
	v_lshl_add_u64 v[96:97], v[200:201], 0, v[132:133]
	v_lshlrev_b64 v[134:135], 10, v[148:149]
	v_lshl_add_u64 v[98:99], v[198:199], 0, v[134:135]
	global_load_dwordx4 v[216:219], v[96:97], off
	global_load_dwordx4 v[220:223], v[98:99], off
	v_add_u32_e32 v146, 0xa0, v196
	v_ashrrev_i32_e32 v147, 31, v146
	v_lshlrev_b64 v[136:137], 5, v[146:147]
	v_lshl_add_u64 v[96:97], v[200:201], 0, v[136:137]
	v_lshlrev_b64 v[138:139], 10, v[146:147]
	v_lshl_add_u64 v[98:99], v[198:199], 0, v[138:139]
	global_load_dwordx4 v[108:111], v[96:97], off
	global_load_dwordx4 v[104:107], v[98:99], off
	v_pk_add_f32 v[92:93], v[92:93], v[116:117]
	v_add_u32_e32 v144, 0xb0, v196
	v_mul_f32_e32 v92, 0xbfb8aa3b, v92
	v_exp_f32_e32 v175, v92
	v_mul_f32_e32 v92, 0xbfb8aa3b, v93
	v_ashrrev_i32_e32 v145, 31, v144
	v_exp_f32_e32 v196, v92
	v_lshlrev_b64 v[140:141], 5, v[144:145]
	v_lshlrev_b64 v[142:143], 10, v[144:145]
	v_lshl_add_u64 v[96:97], v[200:201], 0, v[140:141]
	v_lshl_add_u64 v[98:99], v[198:199], 0, v[142:143]
	global_load_dwordx4 v[100:103], v[96:97], off
	s_nop 0
	global_load_dwordx4 v[96:99], v[98:99], off
	v_pk_add_f32 v[94:95], v[94:95], v[118:119]
	v_pk_add_f32 v[92:93], v[90:91], v[114:115]
	v_add_f32_e32 v90, 1.0, v175
	v_add_f32_e32 v91, 1.0, v196
	v_rcp_f32_e32 v90, v90
	v_rcp_f32_e32 v91, v91
	v_mul_f32_e32 v94, 0xbfb8aa3b, v94
	v_mul_f32_e32 v95, 0xbfb8aa3b, v95
	v_exp_f32_e32 v94, v94
	v_exp_f32_e32 v95, v95
	v_pk_add_f32 v[88:89], v[88:89], v[112:113]
	v_mul_f32_e32 v92, 0xbfb8aa3b, v92
	v_add_f32_e32 v94, 1.0, v94
	v_add_f32_e32 v95, 1.0, v95
	v_mul_f32_e32 v88, 0xbfb8aa3b, v88
	v_rcp_f32_e32 v94, v94
	v_rcp_f32_e32 v95, v95
	v_exp_f32_e32 v92, v92
	v_mul_f32_e32 v93, 0xbfb8aa3b, v93
	v_exp_f32_e32 v93, v93
	v_pk_add_f32 v[84:85], v[84:85], v[116:117]
	v_add_f32_e32 v92, 1.0, v92
	v_mul_f32_e32 v84, 0xbfb8aa3b, v84
	v_mul_f32_e32 v85, 0xbfb8aa3b, v85
	v_exp_f32_e32 v84, v84
	v_exp_f32_e32 v85, v85
	v_pk_add_f32 v[86:87], v[86:87], v[118:119]
	v_add_f32_e32 v84, 1.0, v84
	v_add_f32_e32 v85, 1.0, v85
	v_rcp_f32_e32 v84, v84
	v_rcp_f32_e32 v85, v85
	v_mul_f32_e32 v86, 0xbfb8aa3b, v86
	v_mul_f32_e32 v87, 0xbfb8aa3b, v87
	v_exp_f32_e32 v86, v86
	v_exp_f32_e32 v87, v87
	v_pk_add_f32 v[82:83], v[82:83], v[114:115]
	v_pk_add_f32 v[76:77], v[76:77], v[116:117]
	v_mul_f32_e32 v82, 0xbfb8aa3b, v82
	v_mul_f32_e32 v76, 0xbfb8aa3b, v76
	v_mul_f32_e32 v77, 0xbfb8aa3b, v77
	v_exp_f32_e32 v76, v76
	v_exp_f32_e32 v77, v77
	v_pk_add_f32 v[78:79], v[78:79], v[118:119]
	v_pk_add_f32 v[74:75], v[74:75], v[114:115]
	v_add_f32_e32 v76, 1.0, v76
	v_add_f32_e32 v77, 1.0, v77
	v_rcp_f32_e32 v76, v76
	v_rcp_f32_e32 v77, v77
	v_mul_f32_e32 v78, 0xbfb8aa3b, v78
	v_mul_f32_e32 v79, 0xbfb8aa3b, v79
	s_waitcnt vmcnt(7)
	v_lshlrev_b32_e32 v196, 16, v150
	v_and_b32_e32 v197, 0xffff0000, v150
	v_pk_mul_f32 v[90:91], v[90:91], v[196:197]
	s_waitcnt vmcnt(6)
	v_lshlrev_b32_e32 v196, 16, v202
	v_and_b32_e32 v197, 0xffff0000, v202
	v_pk_mul_f32 v[90:91], v[90:91], v[196:197]
	v_lshlrev_b32_e32 v150, 16, v151
	v_cvt_pk_bf16_f32 v90, v90, v91
	v_exp_f32_e32 v91, v88
	v_mul_f32_e32 v88, 0xbfb8aa3b, v89
	v_exp_f32_e32 v175, v88
	v_and_b32_e32 v151, 0xffff0000, v151
	v_pk_mul_f32 v[94:95], v[94:95], v[150:151]
	v_lshlrev_b32_e32 v150, 16, v203
	v_and_b32_e32 v151, 0xffff0000, v203
	v_add_f32_e32 v91, 1.0, v91
	v_pk_mul_f32 v[88:89], v[94:95], v[150:151]
	v_rcp_f32_e32 v94, v91
	v_add_f32_e32 v91, 1.0, v175
	v_rcp_f32_e32 v95, v91
	v_cvt_pk_bf16_f32 v91, v88, v89
	v_lshlrev_b32_e32 v88, 16, v152
	v_and_b32_e32 v89, 0xffff0000, v152
	v_pk_mul_f32 v[88:89], v[94:95], v[88:89]
	v_lshlrev_b32_e32 v94, 16, v204
	v_and_b32_e32 v95, 0xffff0000, v204
	v_pk_mul_f32 v[88:89], v[88:89], v[94:95]
	v_rcp_f32_e32 v94, v92
	v_add_f32_e32 v92, 1.0, v93
	v_rcp_f32_e32 v95, v92
	v_cvt_pk_bf16_f32 v92, v88, v89
	v_lshlrev_b32_e32 v88, 16, v153
	v_and_b32_e32 v89, 0xffff0000, v153
	v_pk_mul_f32 v[88:89], v[94:95], v[88:89]
	v_lshlrev_b32_e32 v94, 16, v205
	v_and_b32_e32 v95, 0xffff0000, v205
	v_pk_mul_f32 v[88:89], v[88:89], v[94:95]
	v_exp_f32_e32 v78, v78
	v_cvt_pk_bf16_f32 v93, v88, v89
	v_lshlrev_b64 v[88:89], 11, v[154:155]
	v_lshl_add_u64 v[88:89], s[40:41], 0, v[88:89]
	v_lshl_add_u64 v[88:89], v[88:89], 0, v[182:183]
	global_store_dwordx4 v[88:89], v[90:93], off nt
	v_exp_f32_e32 v79, v79
	v_mul_f32_e32 v74, 0xbfb8aa3b, v74
	v_pk_add_f32 v[90:91], v[80:81], v[112:113]
	s_waitcnt vmcnt(6)
	v_lshlrev_b32_e32 v80, 16, v216
	v_and_b32_e32 v81, 0xffff0000, v216
	v_pk_mul_f32 v[80:81], v[84:85], v[80:81]
	s_waitcnt vmcnt(5)
; __device__ __forceinline__ unsigned pk2(float lo, float hi) { typedef __bf16 bf16x2_t_ __attribute__((ext_vector_type(2))); f32x2 v = {lo, hi}; return __builtin_bit_cast(unsigned, __builtin_convertvector(v, bf16x2_t_)); }
; __device__ __forceinline__ float sigmoidf_(float x) { return __builtin_amdgcn_rcpf(1.f + __expf(-x)); }
;     __device__ __forceinline__ void operator()(const f32x4 (&acc)[2][2][4][2], const pg8::Unit& u, int wr, int wc, int fr, int fq) const {
;     ...
;                 for (int m = 0; m < 4; ++m) {
;                     const int row = u.pm * 256 + ai * 128 + wr * 64 + m * 16 + fr;
;                     const u32x4 ys = ysv[m], zs = zsv[m];
;                     const f32x4 a = acc[ai][bj][m][0] + b0, b = acc[ai][bj][m][1] + b1;
;                     u32x4 w;
;                     w.x = pk2(bflo(ys.x) * sigmoidf_(a[0]) * bflo(zs.x), bfhi(ys.x) * sigmoidf_(a[1]) * bfhi(zs.x));
;                     w.y = pk2(bflo(ys.y) * sigmoidf_(a[2]) * bflo(zs.y), bfhi(ys.y) * sigmoidf_(a[3]) * bfhi(zs.y));
;                     w.z = pk2(bflo(ys.z) * sigmoidf_(b[0]) * bflo(zs.z), bfhi(ys.z) * sigmoidf_(b[1]) * bfhi(zs.z));
;                     w.w = pk2(bflo(ys.w) * sigmoidf_(b[2]) * bflo(zs.w), bfhi(ys.w) * sigmoidf_(b[3]) * bfhi(zs.w));
;                     *(u32x4*)(MX_ + (size_t)row * 1024 + col) = w;
	v_lshlrev_b32_e32 v84, 16, v220
	v_and_b32_e32 v85, 0xffff0000, v220
	v_pk_mul_f32 v[80:81], v[80:81], v[84:85]
	v_add_f32_e32 v84, 1.0, v86
	v_add_f32_e32 v85, 1.0, v87
	v_cvt_pk_bf16_f32 v80, v80, v81
	v_mul_f32_e32 v81, 0xbfb8aa3b, v90
	v_rcp_f32_e32 v84, v84
	v_rcp_f32_e32 v85, v85
	v_exp_f32_e32 v81, v81
	v_mul_f32_e32 v90, 0xbfb8aa3b, v91
	v_exp_f32_e32 v90, v90
	v_lshlrev_b32_e32 v86, 16, v217
	v_and_b32_e32 v87, 0xffff0000, v217
	v_pk_mul_f32 v[84:85], v[84:85], v[86:87]
	v_lshlrev_b32_e32 v86, 16, v221
	v_and_b32_e32 v87, 0xffff0000, v221
	v_add_f32_e32 v81, 1.0, v81
	v_pk_mul_f32 v[84:85], v[84:85], v[86:87]
	v_rcp_f32_e32 v86, v81
	v_add_f32_e32 v81, 1.0, v90
	v_rcp_f32_e32 v87, v81
	v_exp_f32_e32 v90, v82
	v_mul_f32_e32 v82, 0xbfb8aa3b, v83
	v_exp_f32_e32 v91, v82
	v_cvt_pk_bf16_f32 v81, v84, v85
	v_lshlrev_b32_e32 v84, 16, v218
	v_and_b32_e32 v85, 0xffff0000, v218
	v_pk_mul_f32 v[84:85], v[86:87], v[84:85]
	v_lshlrev_b32_e32 v86, 16, v222
	v_and_b32_e32 v87, 0xffff0000, v222
	v_pk_mul_f32 v[82:83], v[84:85], v[86:87]
	v_add_f32_e32 v84, 1.0, v90
	v_add_f32_e32 v85, 1.0, v91
	v_rcp_f32_e32 v84, v84
	v_rcp_f32_e32 v85, v85
	v_lshlrev_b32_e32 v86, 16, v219
	v_and_b32_e32 v87, 0xffff0000, v219
	v_cvt_pk_bf16_f32 v82, v82, v83
	v_pk_mul_f32 v[84:85], v[84:85], v[86:87]
	v_lshlrev_b32_e32 v86, 16, v223
	v_and_b32_e32 v87, 0xffff0000, v223
	v_pk_mul_f32 v[84:85], v[84:85], v[86:87]
	v_pk_add_f32 v[68:69], v[68:69], v[116:117]
	v_cvt_pk_bf16_f32 v83, v84, v85
	v_lshlrev_b64 v[84:85], 11, v[148:149]
	v_lshl_add_u64 v[84:85], s[40:41], 0, v[84:85]
	v_lshl_add_u64 v[90:91], v[84:85], 0, v[182:183]
	global_store_dwordx4 v[90:91], v[80:83], off nt
	v_mul_f32_e32 v68, 0xbfb8aa3b, v68
	v_mul_f32_e32 v69, 0xbfb8aa3b, v69
	v_pk_add_f32 v[80:81], v[72:73], v[112:113]
	s_waitcnt vmcnt(5)
	v_lshlrev_b32_e32 v72, 16, v108
	v_and_b32_e32 v73, 0xffff0000, v108
	v_pk_mul_f32 v[72:73], v[76:77], v[72:73]
	s_waitcnt vmcnt(4)
	v_lshlrev_b32_e32 v76, 16, v104
	v_and_b32_e32 v77, 0xffff0000, v104
	v_pk_mul_f32 v[72:73], v[72:73], v[76:77]
	v_add_f32_e32 v76, 1.0, v78
	v_add_f32_e32 v77, 1.0, v79
	v_cvt_pk_bf16_f32 v72, v72, v73
	v_mul_f32_e32 v73, 0xbfb8aa3b, v80
	v_rcp_f32_e32 v76, v76
	v_rcp_f32_e32 v77, v77
	v_exp_f32_e32 v73, v73
	v_mul_f32_e32 v80, 0xbfb8aa3b, v81
	v_exp_f32_e32 v80, v80
	v_lshlrev_b32_e32 v78, 16, v109
	v_and_b32_e32 v79, 0xffff0000, v109
	v_pk_mul_f32 v[76:77], v[76:77], v[78:79]
	v_lshlrev_b32_e32 v78, 16, v105
	v_and_b32_e32 v79, 0xffff0000, v105
	v_add_f32_e32 v73, 1.0, v73
	v_pk_mul_f32 v[76:77], v[76:77], v[78:79]
	v_rcp_f32_e32 v78, v73
	v_add_f32_e32 v73, 1.0, v80
	v_rcp_f32_e32 v79, v73
	v_exp_f32_e32 v80, v74
	v_mul_f32_e32 v74, 0xbfb8aa3b, v75
	v_exp_f32_e32 v81, v74
	v_cvt_pk_bf16_f32 v73, v76, v77
	v_lshlrev_b32_e32 v76, 16, v110
	v_and_b32_e32 v77, 0xffff0000, v110
	v_pk_mul_f32 v[76:77], v[78:79], v[76:77]
	v_lshlrev_b32_e32 v78, 16, v106
	v_and_b32_e32 v79, 0xffff0000, v106
	v_pk_mul_f32 v[74:75], v[76:77], v[78:79]
	v_add_f32_e32 v76, 1.0, v80
	v_add_f32_e32 v77, 1.0, v81
	v_rcp_f32_e32 v76, v76
	v_rcp_f32_e32 v77, v77
	v_exp_f32_e32 v68, v68
	v_exp_f32_e32 v69, v69
	v_lshlrev_b32_e32 v78, 16, v111
	v_and_b32_e32 v79, 0xffff0000, v111
	v_pk_mul_f32 v[76:77], v[76:77], v[78:79]
	v_lshlrev_b32_e32 v78, 16, v107
	v_and_b32_e32 v79, 0xffff0000, v107
	v_pk_mul_f32 v[76:77], v[76:77], v[78:79]
	v_add_f32_e32 v68, 1.0, v68
	v_add_f32_e32 v69, 1.0, v69
	v_cvt_pk_bf16_f32 v74, v74, v75
	v_cvt_pk_bf16_f32 v75, v76, v77
	v_lshlrev_b64 v[76:77], 11, v[146:147]
	v_pk_add_f32 v[70:71], v[70:71], v[118:119]
	v_rcp_f32_e32 v68, v68
	v_rcp_f32_e32 v69, v69
	v_lshl_add_u64 v[76:77], s[40:41], 0, v[76:77]
	v_mul_f32_e32 v70, 0xbfb8aa3b, v70
	v_mul_f32_e32 v71, 0xbfb8aa3b, v71
	v_lshl_add_u64 v[92:93], v[76:77], 0, v[182:183]
	v_exp_f32_e32 v70, v70
	v_exp_f32_e32 v71, v71
	global_store_dwordx4 v[92:93], v[72:75], off nt
	v_pk_add_f32 v[66:67], v[66:67], v[114:115]
	s_nop 0
	v_pk_add_f32 v[72:73], v[64:65], v[112:113]
	s_waitcnt vmcnt(4)
	v_lshlrev_b32_e32 v64, 16, v100
	v_and_b32_e32 v65, 0xffff0000, v100
	v_pk_mul_f32 v[64:65], v[68:69], v[64:65]
	s_waitcnt vmcnt(3)
	v_lshlrev_b32_e32 v68, 16, v96
	v_and_b32_e32 v69, 0xffff0000, v96
	v_pk_mul_f32 v[64:65], v[64:65], v[68:69]
	v_add_f32_e32 v68, 1.0, v70
	v_add_f32_e32 v69, 1.0, v71
	v_cvt_pk_bf16_f32 v64, v64, v65
	v_mul_f32_e32 v65, 0xbfb8aa3b, v72
	v_rcp_f32_e32 v68, v68
	v_rcp_f32_e32 v69, v69
	v_exp_f32_e32 v65, v65
	v_mul_f32_e32 v72, 0xbfb8aa3b, v73
	v_exp_f32_e32 v72, v72
	v_lshlrev_b32_e32 v70, 16, v101
	v_and_b32_e32 v71, 0xffff0000, v101
	v_pk_mul_f32 v[68:69], v[68:69], v[70:71]
	v_lshlrev_b32_e32 v70, 16, v97
	v_and_b32_e32 v71, 0xffff0000, v97
	v_add_f32_e32 v65, 1.0, v65
	v_pk_mul_f32 v[68:69], v[68:69], v[70:71]
	v_rcp_f32_e32 v70, v65
	v_add_f32_e32 v65, 1.0, v72
	v_mul_f32_e32 v66, 0xbfb8aa3b, v66
	v_rcp_f32_e32 v71, v65
	v_exp_f32_e32 v72, v66
	v_mul_f32_e32 v66, 0xbfb8aa3b, v67
	v_exp_f32_e32 v73, v66
	v_cvt_pk_bf16_f32 v65, v68, v69
	v_lshlrev_b32_e32 v68, 16, v102
	v_and_b32_e32 v69, 0xffff0000, v102
	v_pk_mul_f32 v[68:69], v[70:71], v[68:69]
	v_lshlrev_b32_e32 v70, 16, v98
	v_and_b32_e32 v71, 0xffff0000, v98
	v_pk_mul_f32 v[66:67], v[68:69], v[70:71]
	v_add_f32_e32 v68, 1.0, v72
	v_add_f32_e32 v69, 1.0, v73
	v_rcp_f32_e32 v68, v68
	v_rcp_f32_e32 v69, v69
	v_lshlrev_b32_e32 v70, 16, v103
	v_and_b32_e32 v71, 0xffff0000, v103
	v_cvt_pk_bf16_f32 v66, v66, v67
	v_pk_mul_f32 v[68:69], v[68:69], v[70:71]
	v_lshlrev_b32_e32 v70, 16, v99
	v_and_b32_e32 v71, 0xffff0000, v99
	v_pk_mul_f32 v[68:69], v[68:69], v[70:71]
	v_or_b32_e32 v72, 0x80, v174
	v_cvt_pk_bf16_f32 v67, v68, v69
; __host__ __device__ __forceinline__ size_t ys_off(int m, int ch) { return ((size_t)(ch >> 4) * PT + m) * 16 + (ch & 15); }
; __device__ __forceinline__ unsigned pk2(float lo, float hi) { typedef __bf16 bf16x2_t_ __attribute__((ext_vector_type(2))); f32x2 v = {lo, hi}; return __builtin_bit_cast(unsigned, __builtin_convertvector(v, bf16x2_t_)); }
; __device__ __forceinline__ float sigmoidf_(float x) { return __builtin_amdgcn_rcpf(1.f + __expf(-x)); }
;     __device__ __forceinline__ void operator()(const f32x4 (&acc)[2][2][4][2], const pg8::Unit& u, int wr, int wc, int fr, int fq) const {
;     ...
;         for (int bj = 0; bj < 2; ++bj) {
;             const int col = u.pn * 256 + bj * 128 + wc * 32 + fq * 8;
;             const f32x4 b0 = *(const f32x4*)(bglu + col), b1 = *(const f32x4*)(bglu + col + 4);
; #pragma unroll
;             for (int ai = 0; ai < 2; ++ai) {
;                 u32x4 ysv[4], zsv[4];
; #pragma unroll
;                 for (int m = 0; m < 4; ++m) { const int row = u.pm * 256 + ai * 128 + wr * 64 + m * 16 + fr;
;                     ysv[m] = *(const u32x4*)(YS_ + ys_off(row, col)); zsv[m] = *(const u32x4*)(ZS_ + (size_t)row * 512 + col); }
;                 asm volatile("" ::: "memory");
; #pragma unroll
;                 for (int m = 0; m < 4; ++m) {
;                     const int row = u.pm * 256 + ai * 128 + wr * 64 + m * 16 + fr;
;                     const u32x4 ys = ysv[m], zs = zsv[m];
;                     const f32x4 a = acc[ai][bj][m][0] + b0, b = acc[ai][bj][m][1] + b1;
;                     u32x4 w;
;                     w.x = pk2(bflo(ys.x) * sigmoidf_(a[0]) * bflo(zs.x), bfhi(ys.x) * sigmoidf_(a[1]) * bfhi(zs.x));
;                     w.y = pk2(bflo(ys.y) * sigmoidf_(a[2]) * bflo(zs.y), bfhi(ys.y) * sigmoidf_(a[3]) * bfhi(zs.y));
;                     w.z = pk2(bflo(ys.z) * sigmoidf_(b[0]) * bflo(zs.z), bfhi(ys.z) * sigmoidf_(b[1]) * bfhi(zs.z));
;                     w.w = pk2(bflo(ys.w) * sigmoidf_(b[2]) * bflo(zs.w), bfhi(ys.w) * sigmoidf_(b[3]) * bfhi(zs.w));
;                     *(u32x4*)(MX_ + (size_t)row * 1024 + col) = w;
	v_lshlrev_b64 v[68:69], 11, v[144:145]
	v_lshl_add_u64 v[68:69], s[40:41], 0, v[68:69]
	v_lshl_add_u64 v[94:95], v[68:69], 0, v[182:183]
	global_store_dwordx4 v[94:95], v[64:67], off nt
	global_load_dwordx4 v[68:71], v[176:177], off offset:512
	global_load_dwordx4 v[64:67], v[176:177], off offset:528
	v_ashrrev_i32_e32 v74, 4, v72
	v_ashrrev_i32_e32 v75, 31, v74
	v_lshlrev_b64 v[74:75], 21, v[74:75]
	v_lshl_add_u64 v[96:97], v[164:165], 0, v[74:75]
	v_ashrrev_i32_e32 v73, 31, v72
	v_lshl_add_u64 v[74:75], v[96:97], 0, v[178:179]
	global_load_dwordx4 v[100:103], v[74:75], off
	v_lshl_add_u64 v[74:75], s[18:19], 0, v[180:181]
	v_lshlrev_b64 v[98:99], 1, v[72:73]
	v_lshl_add_u64 v[72:73], v[74:75], 0, v[98:99]
	global_load_dwordx4 v[104:107], v[72:73], off
	v_lshl_add_u64 v[72:73], v[96:97], 0, v[194:195]
	v_lshl_add_u64 v[74:75], s[18:19], 0, v[192:193]
	v_lshl_add_u64 v[74:75], v[74:75], 0, v[98:99]
	global_load_dwordx4 v[108:111], v[72:73], off
	global_load_dwordx4 v[112:115], v[74:75], off
	v_lshl_add_u64 v[72:73], v[96:97], 0, v[190:191]
	v_lshl_add_u64 v[74:75], s[18:19], 0, v[186:187]
	v_lshl_add_u64 v[74:75], v[74:75], 0, v[98:99]
	global_load_dwordx4 v[84:87], v[72:73], off
	global_load_dwordx4 v[80:83], v[74:75], off
	v_lshl_add_u64 v[74:75], s[18:19], 0, v[188:189]
	v_lshl_add_u64 v[72:73], v[96:97], 0, v[184:185]
	v_lshl_add_u64 v[74:75], v[74:75], 0, v[98:99]
	global_load_dwordx4 v[76:79], v[72:73], off
	s_nop 0
	global_load_dwordx4 v[72:75], v[74:75], off
	s_waitcnt vmcnt(9)
	v_pk_add_f32 v[60:61], v[60:61], v[68:69]
	s_nop 0
	v_mul_f32_e32 v60, 0xbfb8aa3b, v60
	v_mul_f32_e32 v61, 0xbfb8aa3b, v61
	v_exp_f32_e32 v60, v60
	v_exp_f32_e32 v61, v61
	v_pk_add_f32 v[62:63], v[62:63], v[70:71]
	s_waitcnt vmcnt(8)
	v_pk_add_f32 v[116:117], v[56:57], v[64:65]
	v_add_f32_e32 v60, 1.0, v60
	v_add_f32_e32 v61, 1.0, v61
	v_rcp_f32_e32 v60, v60
	v_rcp_f32_e32 v61, v61
	v_mul_f32_e32 v62, 0xbfb8aa3b, v62
	v_mul_f32_e32 v63, 0xbfb8aa3b, v63
	v_exp_f32_e32 v62, v62
	v_exp_f32_e32 v63, v63
	s_waitcnt vmcnt(7)
	v_lshlrev_b32_e32 v56, 16, v100
	v_and_b32_e32 v57, 0xffff0000, v100
	v_pk_mul_f32 v[56:57], v[60:61], v[56:57]
	s_waitcnt vmcnt(6)
	v_lshlrev_b32_e32 v60, 16, v104
	v_and_b32_e32 v61, 0xffff0000, v104
	v_pk_mul_f32 v[56:57], v[56:57], v[60:61]
	v_add_f32_e32 v60, 1.0, v62
	v_add_f32_e32 v61, 1.0, v63
	v_cvt_pk_bf16_f32 v56, v56, v57
	v_mul_f32_e32 v57, 0xbfb8aa3b, v116
	v_rcp_f32_e32 v60, v60
	v_rcp_f32_e32 v61, v61
	v_exp_f32_e32 v57, v57
	v_mul_f32_e32 v100, 0xbfb8aa3b, v117
	v_exp_f32_e32 v100, v100
	v_lshlrev_b32_e32 v62, 16, v101
	v_and_b32_e32 v63, 0xffff0000, v101
	v_pk_add_f32 v[58:59], v[58:59], v[66:67]
	v_pk_mul_f32 v[60:61], v[60:61], v[62:63]
	v_lshlrev_b32_e32 v62, 16, v105
	v_and_b32_e32 v63, 0xffff0000, v105
	v_add_f32_e32 v57, 1.0, v57
	v_pk_mul_f32 v[60:61], v[60:61], v[62:63]
	v_rcp_f32_e32 v62, v57
	v_add_f32_e32 v57, 1.0, v100
	v_mul_f32_e32 v58, 0xbfb8aa3b, v58
	v_rcp_f32_e32 v63, v57
	v_exp_f32_e32 v100, v58
	v_mul_f32_e32 v58, 0xbfb8aa3b, v59
	v_exp_f32_e32 v101, v58
	v_cvt_pk_bf16_f32 v57, v60, v61
	v_lshlrev_b32_e32 v60, 16, v102
	v_and_b32_e32 v61, 0xffff0000, v102
	v_pk_add_f32 v[52:53], v[52:53], v[68:69]
	v_pk_mul_f32 v[60:61], v[62:63], v[60:61]
	v_lshlrev_b32_e32 v62, 16, v106
	v_and_b32_e32 v63, 0xffff0000, v106
	v_mul_f32_e32 v52, 0xbfb8aa3b, v52
	v_mul_f32_e32 v53, 0xbfb8aa3b, v53
	v_pk_mul_f32 v[58:59], v[60:61], v[62:63]
	v_add_f32_e32 v60, 1.0, v100
	v_add_f32_e32 v61, 1.0, v101
	v_exp_f32_e32 v52, v52
	v_exp_f32_e32 v53, v53
	v_rcp_f32_e32 v60, v60
	v_rcp_f32_e32 v61, v61
	v_lshlrev_b32_e32 v62, 16, v103
	v_and_b32_e32 v63, 0xffff0000, v103
	v_add_f32_e32 v52, 1.0, v52
	v_add_f32_e32 v53, 1.0, v53
	v_pk_mul_f32 v[60:61], v[60:61], v[62:63]
	v_lshlrev_b32_e32 v62, 16, v107
	v_and_b32_e32 v63, 0xffff0000, v107
	v_pk_add_f32 v[54:55], v[54:55], v[70:71]
	v_rcp_f32_e32 v52, v52
	v_rcp_f32_e32 v53, v53
	v_pk_mul_f32 v[60:61], v[60:61], v[62:63]
	v_mul_f32_e32 v54, 0xbfb8aa3b, v54
	v_mul_f32_e32 v55, 0xbfb8aa3b, v55
	v_cvt_pk_bf16_f32 v58, v58, v59
	v_cvt_pk_bf16_f32 v59, v60, v61
	v_exp_f32_e32 v54, v54
	v_exp_f32_e32 v55, v55
	global_store_dwordx4 v[128:129], v[56:59], off offset:256 nt
	v_pk_add_f32 v[50:51], v[50:51], v[66:67]
	v_pk_add_f32 v[44:45], v[44:45], v[68:69]
	v_pk_add_f32 v[56:57], v[48:49], v[64:65]
	s_waitcnt vmcnt(6)
	v_lshlrev_b32_e32 v48, 16, v108
	v_and_b32_e32 v49, 0xffff0000, v108
	v_pk_mul_f32 v[48:49], v[52:53], v[48:49]
	s_waitcnt vmcnt(5)
	v_lshlrev_b32_e32 v52, 16, v112
	v_and_b32_e32 v53, 0xffff0000, v112
	v_pk_mul_f32 v[48:49], v[48:49], v[52:53]
	v_add_f32_e32 v52, 1.0, v54
	v_add_f32_e32 v53, 1.0, v55
	v_cvt_pk_bf16_f32 v48, v48, v49
	v_mul_f32_e32 v49, 0xbfb8aa3b, v56
	v_rcp_f32_e32 v52, v52
	v_rcp_f32_e32 v53, v53
	v_exp_f32_e32 v49, v49
	v_mul_f32_e32 v56, 0xbfb8aa3b, v57
	v_exp_f32_e32 v56, v56
	v_lshlrev_b32_e32 v54, 16, v109
	v_and_b32_e32 v55, 0xffff0000, v109
	v_pk_mul_f32 v[52:53], v[52:53], v[54:55]
	v_lshlrev_b32_e32 v54, 16, v113
	v_and_b32_e32 v55, 0xffff0000, v113
	v_add_f32_e32 v49, 1.0, v49
	v_pk_mul_f32 v[52:53], v[52:53], v[54:55]
	v_rcp_f32_e32 v54, v49
	v_add_f32_e32 v49, 1.0, v56
	v_mul_f32_e32 v50, 0xbfb8aa3b, v50
	v_rcp_f32_e32 v55, v49
	v_exp_f32_e32 v56, v50
	v_mul_f32_e32 v50, 0xbfb8aa3b, v51
	v_exp_f32_e32 v57, v50
	v_cvt_pk_bf16_f32 v49, v52, v53
	v_lshlrev_b32_e32 v52, 16, v110
	v_and_b32_e32 v53, 0xffff0000, v110
	v_pk_mul_f32 v[52:53], v[54:55], v[52:53]
	v_lshlrev_b32_e32 v54, 16, v114
	v_and_b32_e32 v55, 0xffff0000, v114
	v_mul_f32_e32 v44, 0xbfb8aa3b, v44
	v_mul_f32_e32 v45, 0xbfb8aa3b, v45
	v_pk_mul_f32 v[50:51], v[52:53], v[54:55]
	v_add_f32_e32 v52, 1.0, v56
	v_add_f32_e32 v53, 1.0, v57
	v_exp_f32_e32 v44, v44
	v_exp_f32_e32 v45, v45
	v_rcp_f32_e32 v52, v52
	v_rcp_f32_e32 v53, v53
	v_lshlrev_b32_e32 v54, 16, v111
	v_and_b32_e32 v55, 0xffff0000, v111
	v_add_f32_e32 v44, 1.0, v44
	v_add_f32_e32 v45, 1.0, v45
	v_pk_mul_f32 v[52:53], v[52:53], v[54:55]
	v_lshlrev_b32_e32 v54, 16, v115
	v_and_b32_e32 v55, 0xffff0000, v115
	v_pk_add_f32 v[46:47], v[46:47], v[70:71]
	v_rcp_f32_e32 v44, v44
	v_rcp_f32_e32 v45, v45
	v_pk_mul_f32 v[52:53], v[52:53], v[54:55]
	v_mul_f32_e32 v46, 0xbfb8aa3b, v46
	v_mul_f32_e32 v47, 0xbfb8aa3b, v47
	v_cvt_pk_bf16_f32 v50, v50, v51
	v_cvt_pk_bf16_f32 v51, v52, v53
	v_exp_f32_e32 v46, v46
	v_exp_f32_e32 v47, v47
	global_store_dwordx4 v[120:121], v[48:51], off offset:256 nt
	v_pk_add_f32 v[42:43], v[42:43], v[66:67]
	v_pk_add_f32 v[36:37], v[36:37], v[68:69]
	v_pk_add_f32 v[48:49], v[40:41], v[64:65]
	s_waitcnt vmcnt(5)
; __host__ __device__ __forceinline__ size_t ys_off(int m, int ch) { return ((size_t)(ch >> 4) * PT + m) * 16 + (ch & 15); }
; __device__ __forceinline__ unsigned pk2(float lo, float hi) { typedef __bf16 bf16x2_t_ __attribute__((ext_vector_type(2))); f32x2 v = {lo, hi}; return __builtin_bit_cast(unsigned, __builtin_convertvector(v, bf16x2_t_)); }
; __device__ __forceinline__ float sigmoidf_(float x) { return __builtin_amdgcn_rcpf(1.f + __expf(-x)); }
;     __device__ __forceinline__ void operator()(const f32x4 (&acc)[2][2][4][2], const pg8::Unit& u, int wr, int wc, int fr, int fq) const {
;     ...
;                 u32x4 ysv[4], zsv[4];
; #pragma unroll
;                 for (int m = 0; m < 4; ++m) { const int row = u.pm * 256 + ai * 128 + wr * 64 + m * 16 + fr;
;                     ysv[m] = *(const u32x4*)(YS_ + ys_off(row, col)); zsv[m] = *(const u32x4*)(ZS_ + (size_t)row * 512 + col); }
;                 asm volatile("" ::: "memory");
; #pragma unroll
;                 for (int m = 0; m < 4; ++m) {
;                     const int row = u.pm * 256 + ai * 128 + wr * 64 + m * 16 + fr;
;                     const u32x4 ys = ysv[m], zs = zsv[m];
;                     const f32x4 a = acc[ai][bj][m][0] + b0, b = acc[ai][bj][m][1] + b1;
;                     u32x4 w;
;                     w.x = pk2(bflo(ys.x) * sigmoidf_(a[0]) * bflo(zs.x), bfhi(ys.x) * sigmoidf_(a[1]) * bfhi(zs.x));
;                     w.y = pk2(bflo(ys.y) * sigmoidf_(a[2]) * bflo(zs.y), bfhi(ys.y) * sigmoidf_(a[3]) * bfhi(zs.y));
;                     w.z = pk2(bflo(ys.z) * sigmoidf_(b[0]) * bflo(zs.z), bfhi(ys.z) * sigmoidf_(b[1]) * bfhi(zs.z));
;                     w.w = pk2(bflo(ys.w) * sigmoidf_(b[2]) * bflo(zs.w), bfhi(ys.w) * sigmoidf_(b[3]) * bfhi(zs.w));
;                     *(u32x4*)(MX_ + (size_t)row * 1024 + col) = w;
	v_lshlrev_b32_e32 v40, 16, v84
	v_and_b32_e32 v41, 0xffff0000, v84
	v_pk_mul_f32 v[40:41], v[44:45], v[40:41]
	s_waitcnt vmcnt(4)
	v_lshlrev_b32_e32 v44, 16, v80
	v_and_b32_e32 v45, 0xffff0000, v80
	v_pk_mul_f32 v[40:41], v[40:41], v[44:45]
	v_add_f32_e32 v44, 1.0, v46
	v_add_f32_e32 v45, 1.0, v47
	v_cvt_pk_bf16_f32 v40, v40, v41
	v_mul_f32_e32 v41, 0xbfb8aa3b, v48
	v_rcp_f32_e32 v44, v44
	v_rcp_f32_e32 v45, v45
	v_exp_f32_e32 v41, v41
	v_mul_f32_e32 v48, 0xbfb8aa3b, v49
	v_exp_f32_e32 v48, v48
	v_lshlrev_b32_e32 v46, 16, v85
	v_and_b32_e32 v47, 0xffff0000, v85
	v_pk_mul_f32 v[44:45], v[44:45], v[46:47]
	v_lshlrev_b32_e32 v46, 16, v81
	v_and_b32_e32 v47, 0xffff0000, v81
	v_add_f32_e32 v41, 1.0, v41
	v_pk_mul_f32 v[44:45], v[44:45], v[46:47]
	v_rcp_f32_e32 v46, v41
	v_add_f32_e32 v41, 1.0, v48
	v_mul_f32_e32 v42, 0xbfb8aa3b, v42
	v_rcp_f32_e32 v47, v41
	v_exp_f32_e32 v48, v42
	v_mul_f32_e32 v42, 0xbfb8aa3b, v43
	v_exp_f32_e32 v49, v42
	v_cvt_pk_bf16_f32 v41, v44, v45
	v_lshlrev_b32_e32 v44, 16, v86
	v_and_b32_e32 v45, 0xffff0000, v86
	v_pk_mul_f32 v[44:45], v[46:47], v[44:45]
	v_lshlrev_b32_e32 v46, 16, v82
	v_and_b32_e32 v47, 0xffff0000, v82
	v_mul_f32_e32 v36, 0xbfb8aa3b, v36
	v_mul_f32_e32 v37, 0xbfb8aa3b, v37
	v_pk_mul_f32 v[42:43], v[44:45], v[46:47]
	v_add_f32_e32 v44, 1.0, v48
	v_add_f32_e32 v45, 1.0, v49
	v_exp_f32_e32 v36, v36
	v_exp_f32_e32 v37, v37
	v_rcp_f32_e32 v44, v44
	v_rcp_f32_e32 v45, v45
	v_lshlrev_b32_e32 v46, 16, v87
	v_and_b32_e32 v47, 0xffff0000, v87
	v_add_f32_e32 v36, 1.0, v36
	v_add_f32_e32 v37, 1.0, v37
	v_pk_mul_f32 v[44:45], v[44:45], v[46:47]
	v_lshlrev_b32_e32 v46, 16, v83
	v_and_b32_e32 v47, 0xffff0000, v83
	v_pk_add_f32 v[38:39], v[38:39], v[70:71]
	v_rcp_f32_e32 v36, v36
	v_rcp_f32_e32 v37, v37
	v_pk_mul_f32 v[44:45], v[44:45], v[46:47]
	v_mul_f32_e32 v38, 0xbfb8aa3b, v38
	v_mul_f32_e32 v39, 0xbfb8aa3b, v39
	v_cvt_pk_bf16_f32 v42, v42, v43
	v_cvt_pk_bf16_f32 v43, v44, v45
	v_exp_f32_e32 v38, v38
	v_exp_f32_e32 v39, v39
	global_store_dwordx4 v[122:123], v[40:43], off offset:256 nt
	v_pk_add_f32 v[34:35], v[34:35], v[66:67]
	v_pk_add_f32 v[28:29], v[28:29], v[68:69]
	v_pk_add_f32 v[40:41], v[32:33], v[64:65]
	s_waitcnt vmcnt(4)
	v_lshlrev_b32_e32 v32, 16, v76
	v_and_b32_e32 v33, 0xffff0000, v76
	v_pk_mul_f32 v[32:33], v[36:37], v[32:33]
	s_waitcnt vmcnt(3)
	v_lshlrev_b32_e32 v36, 16, v72
	v_and_b32_e32 v37, 0xffff0000, v72
	v_pk_mul_f32 v[32:33], v[32:33], v[36:37]
	v_add_f32_e32 v36, 1.0, v38
	v_add_f32_e32 v37, 1.0, v39
	v_cvt_pk_bf16_f32 v32, v32, v33
	v_mul_f32_e32 v33, 0xbfb8aa3b, v40
	v_rcp_f32_e32 v36, v36
	v_rcp_f32_e32 v37, v37
	v_exp_f32_e32 v33, v33
	v_mul_f32_e32 v40, 0xbfb8aa3b, v41
	v_exp_f32_e32 v40, v40
	v_lshlrev_b32_e32 v38, 16, v77
	v_and_b32_e32 v39, 0xffff0000, v77
	v_pk_mul_f32 v[36:37], v[36:37], v[38:39]
	v_lshlrev_b32_e32 v38, 16, v73
	v_and_b32_e32 v39, 0xffff0000, v73
	v_add_f32_e32 v33, 1.0, v33
	v_pk_mul_f32 v[36:37], v[36:37], v[38:39]
	v_rcp_f32_e32 v38, v33
	v_add_f32_e32 v33, 1.0, v40
	v_mul_f32_e32 v34, 0xbfb8aa3b, v34
	v_rcp_f32_e32 v39, v33
	v_exp_f32_e32 v40, v34
	v_mul_f32_e32 v34, 0xbfb8aa3b, v35
	v_exp_f32_e32 v41, v34
	v_cvt_pk_bf16_f32 v33, v36, v37
	v_lshlrev_b32_e32 v36, 16, v78
	v_and_b32_e32 v37, 0xffff0000, v78
	v_pk_mul_f32 v[36:37], v[38:39], v[36:37]
	v_lshlrev_b32_e32 v38, 16, v74
	v_and_b32_e32 v39, 0xffff0000, v74
	v_pk_mul_f32 v[34:35], v[36:37], v[38:39]
	v_add_f32_e32 v36, 1.0, v40
	v_add_f32_e32 v37, 1.0, v41
	v_rcp_f32_e32 v36, v36
	v_rcp_f32_e32 v37, v37
	v_lshlrev_b32_e32 v38, 16, v79
	v_and_b32_e32 v39, 0xffff0000, v79
	v_cvt_pk_bf16_f32 v34, v34, v35
	v_pk_mul_f32 v[36:37], v[36:37], v[38:39]
	v_lshlrev_b32_e32 v38, 16, v75
	v_and_b32_e32 v39, 0xffff0000, v75
	v_pk_mul_f32 v[36:37], v[36:37], v[38:39]
	v_mul_f32_e32 v28, 0xbfb8aa3b, v28
	v_cvt_pk_bf16_f32 v35, v36, v37
	global_store_dwordx4 v[124:125], v[32:35], off offset:256 nt
	v_mul_f32_e32 v29, 0xbfb8aa3b, v29
	v_exp_f32_e32 v28, v28
	v_lshl_add_u64 v[32:33], v[96:97], 0, v[126:127]
	global_load_dwordx4 v[48:51], v[32:33], off
	v_lshl_add_u64 v[32:33], s[18:19], 0, v[130:131]
	v_lshl_add_u64 v[32:33], v[32:33], 0, v[98:99]
	global_load_dwordx4 v[52:55], v[32:33], off
	v_lshl_add_u64 v[32:33], v[96:97], 0, v[132:133]
	v_lshl_add_u64 v[34:35], s[18:19], 0, v[134:135]
	v_lshl_add_u64 v[34:35], v[34:35], 0, v[98:99]
	global_load_dwordx4 v[56:59], v[32:33], off
	global_load_dwordx4 v[60:63], v[34:35], off
	v_lshl_add_u64 v[32:33], v[96:97], 0, v[136:137]
	v_lshl_add_u64 v[34:35], s[18:19], 0, v[138:139]
	v_lshl_add_u64 v[34:35], v[34:35], 0, v[98:99]
	global_load_dwordx4 v[44:47], v[32:33], off
	global_load_dwordx4 v[40:43], v[34:35], off
	v_lshl_add_u64 v[34:35], s[18:19], 0, v[142:143]
	v_lshl_add_u64 v[32:33], v[96:97], 0, v[140:141]
	v_lshl_add_u64 v[34:35], v[34:35], 0, v[98:99]
	global_load_dwordx4 v[36:39], v[32:33], off
	s_nop 0
	global_load_dwordx4 v[32:35], v[34:35], off
	v_exp_f32_e32 v29, v29
	v_add_f32_e32 v28, 1.0, v28
	v_pk_add_f32 v[30:31], v[30:31], v[70:71]
	v_rcp_f32_e32 v28, v28
	v_add_f32_e32 v29, 1.0, v29
	v_rcp_f32_e32 v29, v29
	v_mul_f32_e32 v30, 0xbfb8aa3b, v30
	v_mul_f32_e32 v31, 0xbfb8aa3b, v31
	v_exp_f32_e32 v30, v30
	v_exp_f32_e32 v31, v31
	v_pk_add_f32 v[72:73], v[24:25], v[64:65]
	v_pk_add_f32 v[26:27], v[26:27], v[66:67]
	v_pk_add_f32 v[20:21], v[20:21], v[68:69]
	v_mul_f32_e32 v26, 0xbfb8aa3b, v26
	v_mul_f32_e32 v20, 0xbfb8aa3b, v20
	v_mul_f32_e32 v21, 0xbfb8aa3b, v21
	v_exp_f32_e32 v20, v20
	v_exp_f32_e32 v21, v21
	v_pk_add_f32 v[22:23], v[22:23], v[70:71]
	v_add_f32_e32 v20, 1.0, v20
	v_add_f32_e32 v21, 1.0, v21
	v_rcp_f32_e32 v20, v20
	v_rcp_f32_e32 v21, v21
	v_mul_f32_e32 v22, 0xbfb8aa3b, v22
	v_mul_f32_e32 v23, 0xbfb8aa3b, v23
	v_exp_f32_e32 v22, v22
	v_exp_f32_e32 v23, v23
	v_pk_add_f32 v[18:19], v[18:19], v[66:67]
	v_pk_add_f32 v[12:13], v[12:13], v[68:69]
	v_mul_f32_e32 v18, 0xbfb8aa3b, v18
	v_mul_f32_e32 v12, 0xbfb8aa3b, v12
	v_mul_f32_e32 v13, 0xbfb8aa3b, v13
	v_exp_f32_e32 v12, v12
	v_exp_f32_e32 v13, v13
	v_pk_add_f32 v[14:15], v[14:15], v[70:71]
	v_pk_add_f32 v[10:11], v[10:11], v[66:67]
	v_add_f32_e32 v12, 1.0, v12
	v_add_f32_e32 v13, 1.0, v13
	v_rcp_f32_e32 v12, v12
	v_rcp_f32_e32 v13, v13
	v_mul_f32_e32 v14, 0xbfb8aa3b, v14
	v_mul_f32_e32 v15, 0xbfb8aa3b, v15
	v_exp_f32_e32 v14, v14
	v_exp_f32_e32 v15, v15
	v_mul_f32_e32 v10, 0xbfb8aa3b, v10
	v_pk_add_f32 v[4:5], v[4:5], v[68:69]
	v_pk_add_f32 v[6:7], v[6:7], v[70:71]
	v_mul_f32_e32 v4, 0xbfb8aa3b, v4
	v_mul_f32_e32 v5, 0xbfb8aa3b, v5
	v_exp_f32_e32 v4, v4
	v_exp_f32_e32 v5, v5
	v_mul_f32_e32 v6, 0xbfb8aa3b, v6
	v_mul_f32_e32 v7, 0xbfb8aa3b, v7
	v_add_f32_e32 v4, 1.0, v4
	v_add_f32_e32 v5, 1.0, v5
	v_rcp_f32_e32 v4, v4
	v_rcp_f32_e32 v5, v5
	v_exp_f32_e32 v6, v6
	v_exp_f32_e32 v7, v7
	v_pk_add_f32 v[2:3], v[2:3], v[66:67]
	s_waitcnt vmcnt(7)
; __device__ __forceinline__ unsigned pk2(float lo, float hi) { typedef __bf16 bf16x2_t_ __attribute__((ext_vector_type(2))); f32x2 v = {lo, hi}; return __builtin_bit_cast(unsigned, __builtin_convertvector(v, bf16x2_t_)); }
; __device__ __forceinline__ float sigmoidf_(float x) { return __builtin_amdgcn_rcpf(1.f + __expf(-x)); }
; #define PG8_BAR __builtin_amdgcn_s_barrier()
; template <class Epi, class Sched>
; __device__ __forceinline__ void gemm_phase(LAS unsigned char* lds, const Gemm g, const Sched& S, const Epi& E) {
;     ...
;         if (wr == 0) PG8_BAR;
;         E(acc, cur, wr, wc, fr, fq);
;         if (!has_next) break;
; #pragma unroll
;         for (int a = 0; a < 2; ++a)
; #pragma unroll
;             for (int b = 0; b < 2; ++b)
; #pragma unroll
;                 for (int m = 0; m < 4; ++m)
; #pragma unroll
;                     for (int n = 0; n < 2; ++n) acc[a][b][m][n] = (f32x4){0.f, 0.f, 0.f, 0.f};
;         cur = nxt; cA = nA; cB = nB; ++ui;
;         if (wr == 1) PG8_BAR;
;     __device__ __forceinline__ void operator()(const f32x4 (&acc)[2][2][4][2], const pg8::Unit& u, int wr, int wc, int fr, int fq) const {
;     ...
;                 for (int m = 0; m < 4; ++m) {
;                     const int row = u.pm * 256 + ai * 128 + wr * 64 + m * 16 + fr;
;                     const u32x4 ys = ysv[m], zs = zsv[m];
;                     const f32x4 a = acc[ai][bj][m][0] + b0, b = acc[ai][bj][m][1] + b1;
;                     u32x4 w;
;                     w.x = pk2(bflo(ys.x) * sigmoidf_(a[0]) * bflo(zs.x), bfhi(ys.x) * sigmoidf_(a[1]) * bfhi(zs.x));
;                     w.y = pk2(bflo(ys.y) * sigmoidf_(a[2]) * bflo(zs.y), bfhi(ys.y) * sigmoidf_(a[3]) * bfhi(zs.y));
;                     w.z = pk2(bflo(ys.z) * sigmoidf_(b[0]) * bflo(zs.z), bfhi(ys.z) * sigmoidf_(b[1]) * bfhi(zs.z));
;                     w.w = pk2(bflo(ys.w) * sigmoidf_(b[2]) * bflo(zs.w), bfhi(ys.w) * sigmoidf_(b[3]) * bfhi(zs.w));
;                     *(u32x4*)(MX_ + (size_t)row * 1024 + col) = w;
	v_lshlrev_b32_e32 v24, 16, v48
	v_and_b32_e32 v25, 0xffff0000, v48
	v_pk_mul_f32 v[24:25], v[28:29], v[24:25]
	s_waitcnt vmcnt(6)
	v_lshlrev_b32_e32 v28, 16, v52
	v_and_b32_e32 v29, 0xffff0000, v52
	v_pk_mul_f32 v[24:25], v[24:25], v[28:29]
	v_add_f32_e32 v28, 1.0, v30
	v_add_f32_e32 v29, 1.0, v31
	v_cvt_pk_bf16_f32 v24, v24, v25
	v_mul_f32_e32 v25, 0xbfb8aa3b, v72
	v_rcp_f32_e32 v28, v28
	v_rcp_f32_e32 v29, v29
	v_exp_f32_e32 v25, v25
	v_mul_f32_e32 v48, 0xbfb8aa3b, v73
	v_exp_f32_e32 v48, v48
	v_lshlrev_b32_e32 v30, 16, v49
	v_and_b32_e32 v31, 0xffff0000, v49
	v_pk_mul_f32 v[28:29], v[28:29], v[30:31]
	v_lshlrev_b32_e32 v30, 16, v53
	v_and_b32_e32 v31, 0xffff0000, v53
	v_add_f32_e32 v25, 1.0, v25
	v_pk_mul_f32 v[28:29], v[28:29], v[30:31]
	v_rcp_f32_e32 v30, v25
	v_add_f32_e32 v25, 1.0, v48
	v_rcp_f32_e32 v31, v25
	v_exp_f32_e32 v48, v26
	v_mul_f32_e32 v26, 0xbfb8aa3b, v27
	v_exp_f32_e32 v49, v26
	v_cvt_pk_bf16_f32 v25, v28, v29
	v_lshlrev_b32_e32 v28, 16, v50
	v_and_b32_e32 v29, 0xffff0000, v50
	v_pk_mul_f32 v[28:29], v[30:31], v[28:29]
	v_lshlrev_b32_e32 v30, 16, v54
	v_and_b32_e32 v31, 0xffff0000, v54
	v_pk_mul_f32 v[26:27], v[28:29], v[30:31]
	v_add_f32_e32 v28, 1.0, v48
	v_add_f32_e32 v29, 1.0, v49
	v_rcp_f32_e32 v28, v28
	v_rcp_f32_e32 v29, v29
	v_lshlrev_b32_e32 v30, 16, v51
	v_and_b32_e32 v31, 0xffff0000, v51
	v_cvt_pk_bf16_f32 v26, v26, v27
	v_pk_mul_f32 v[28:29], v[28:29], v[30:31]
	v_lshlrev_b32_e32 v30, 16, v55
	v_and_b32_e32 v31, 0xffff0000, v55
	v_pk_mul_f32 v[28:29], v[28:29], v[30:31]
	v_mul_f32_e32 v2, 0xbfb8aa3b, v2
	v_cvt_pk_bf16_f32 v27, v28, v29
	global_store_dwordx4 v[88:89], v[24:27], off offset:256 nt
	s_nop 1
	v_pk_add_f32 v[24:25], v[16:17], v[64:65]
	s_waitcnt vmcnt(6)
	v_lshlrev_b32_e32 v16, 16, v56
	v_and_b32_e32 v17, 0xffff0000, v56
	v_pk_mul_f32 v[16:17], v[20:21], v[16:17]
	s_waitcnt vmcnt(5)
	v_lshlrev_b32_e32 v20, 16, v60
	v_and_b32_e32 v21, 0xffff0000, v60
	v_pk_mul_f32 v[16:17], v[16:17], v[20:21]
	v_add_f32_e32 v20, 1.0, v22
	v_add_f32_e32 v21, 1.0, v23
	v_cvt_pk_bf16_f32 v16, v16, v17
	v_mul_f32_e32 v17, 0xbfb8aa3b, v24
	v_rcp_f32_e32 v20, v20
	v_rcp_f32_e32 v21, v21
	v_exp_f32_e32 v17, v17
	v_mul_f32_e32 v24, 0xbfb8aa3b, v25
	v_exp_f32_e32 v24, v24
	v_lshlrev_b32_e32 v22, 16, v57
	v_and_b32_e32 v23, 0xffff0000, v57
	v_pk_mul_f32 v[20:21], v[20:21], v[22:23]
	v_lshlrev_b32_e32 v22, 16, v61
	v_and_b32_e32 v23, 0xffff0000, v61
	v_add_f32_e32 v17, 1.0, v17
	v_pk_mul_f32 v[20:21], v[20:21], v[22:23]
	v_rcp_f32_e32 v22, v17
	v_add_f32_e32 v17, 1.0, v24
	v_rcp_f32_e32 v23, v17
	v_exp_f32_e32 v24, v18
	v_mul_f32_e32 v18, 0xbfb8aa3b, v19
	v_exp_f32_e32 v25, v18
	v_cvt_pk_bf16_f32 v17, v20, v21
	v_lshlrev_b32_e32 v20, 16, v58
	v_and_b32_e32 v21, 0xffff0000, v58
	v_pk_mul_f32 v[20:21], v[22:23], v[20:21]
	v_lshlrev_b32_e32 v22, 16, v62
	v_and_b32_e32 v23, 0xffff0000, v62
	v_pk_mul_f32 v[18:19], v[20:21], v[22:23]
	v_add_f32_e32 v20, 1.0, v24
	v_add_f32_e32 v21, 1.0, v25
	v_rcp_f32_e32 v20, v20
	v_rcp_f32_e32 v21, v21
	v_lshlrev_b32_e32 v22, 16, v59
	v_and_b32_e32 v23, 0xffff0000, v59
	v_cvt_pk_bf16_f32 v18, v18, v19
	v_pk_mul_f32 v[20:21], v[20:21], v[22:23]
	v_lshlrev_b32_e32 v22, 16, v63
	v_and_b32_e32 v23, 0xffff0000, v63
	v_pk_mul_f32 v[20:21], v[20:21], v[22:23]
	s_nop 0
	v_cvt_pk_bf16_f32 v19, v20, v21
	global_store_dwordx4 v[90:91], v[16:19], off offset:256 nt
	s_nop 1
	v_pk_add_f32 v[16:17], v[8:9], v[64:65]
	s_waitcnt vmcnt(5)
	v_lshlrev_b32_e32 v8, 16, v44
	v_and_b32_e32 v9, 0xffff0000, v44
	v_pk_mul_f32 v[8:9], v[12:13], v[8:9]
	s_waitcnt vmcnt(4)
	v_lshlrev_b32_e32 v12, 16, v40
	v_and_b32_e32 v13, 0xffff0000, v40
	v_pk_mul_f32 v[8:9], v[8:9], v[12:13]
	v_add_f32_e32 v12, 1.0, v14
	v_add_f32_e32 v13, 1.0, v15
	v_cvt_pk_bf16_f32 v8, v8, v9
	v_mul_f32_e32 v9, 0xbfb8aa3b, v16
	v_rcp_f32_e32 v12, v12
	v_rcp_f32_e32 v13, v13
	v_exp_f32_e32 v9, v9
	v_mul_f32_e32 v16, 0xbfb8aa3b, v17
	v_exp_f32_e32 v16, v16
	v_lshlrev_b32_e32 v14, 16, v45
	v_and_b32_e32 v15, 0xffff0000, v45
	v_pk_mul_f32 v[12:13], v[12:13], v[14:15]
	v_lshlrev_b32_e32 v14, 16, v41
	v_and_b32_e32 v15, 0xffff0000, v41
	v_add_f32_e32 v9, 1.0, v9
	v_pk_mul_f32 v[12:13], v[12:13], v[14:15]
	v_rcp_f32_e32 v14, v9
	v_add_f32_e32 v9, 1.0, v16
	v_rcp_f32_e32 v15, v9
	v_exp_f32_e32 v16, v10
	v_mul_f32_e32 v10, 0xbfb8aa3b, v11
	v_exp_f32_e32 v17, v10
	v_cvt_pk_bf16_f32 v9, v12, v13
	v_lshlrev_b32_e32 v12, 16, v46
	v_and_b32_e32 v13, 0xffff0000, v46
	v_pk_mul_f32 v[12:13], v[14:15], v[12:13]
	v_lshlrev_b32_e32 v14, 16, v42
	v_and_b32_e32 v15, 0xffff0000, v42
	v_pk_mul_f32 v[10:11], v[12:13], v[14:15]
	v_add_f32_e32 v12, 1.0, v16
	v_add_f32_e32 v13, 1.0, v17
	v_rcp_f32_e32 v12, v12
	v_rcp_f32_e32 v13, v13
	v_lshlrev_b32_e32 v14, 16, v47
	v_and_b32_e32 v15, 0xffff0000, v47
	v_cvt_pk_bf16_f32 v10, v10, v11
	v_pk_mul_f32 v[12:13], v[12:13], v[14:15]
	v_lshlrev_b32_e32 v14, 16, v43
	v_and_b32_e32 v15, 0xffff0000, v43
	v_pk_mul_f32 v[12:13], v[12:13], v[14:15]
	s_nop 0
	v_cvt_pk_bf16_f32 v11, v12, v13
	global_store_dwordx4 v[92:93], v[8:11], off offset:256 nt
	s_nop 1
	v_pk_add_f32 v[8:9], v[0:1], v[64:65]
	s_waitcnt vmcnt(4)
	v_lshlrev_b32_e32 v0, 16, v36
	v_and_b32_e32 v1, 0xffff0000, v36
	v_pk_mul_f32 v[0:1], v[4:5], v[0:1]
	s_waitcnt vmcnt(3)
	v_lshlrev_b32_e32 v4, 16, v32
	v_and_b32_e32 v5, 0xffff0000, v32
	v_pk_mul_f32 v[0:1], v[0:1], v[4:5]
	v_add_f32_e32 v4, 1.0, v6
	v_add_f32_e32 v5, 1.0, v7
	v_cvt_pk_bf16_f32 v0, v0, v1
	v_mul_f32_e32 v1, 0xbfb8aa3b, v8
	v_rcp_f32_e32 v4, v4
	v_rcp_f32_e32 v5, v5
	v_exp_f32_e32 v1, v1
	v_mul_f32_e32 v8, 0xbfb8aa3b, v9
	v_exp_f32_e32 v8, v8
	v_lshlrev_b32_e32 v6, 16, v37
	v_and_b32_e32 v7, 0xffff0000, v37
	v_pk_mul_f32 v[4:5], v[4:5], v[6:7]
	v_lshlrev_b32_e32 v6, 16, v33
	v_and_b32_e32 v7, 0xffff0000, v33
	v_add_f32_e32 v1, 1.0, v1
	v_pk_mul_f32 v[4:5], v[4:5], v[6:7]
	v_rcp_f32_e32 v6, v1
	v_add_f32_e32 v1, 1.0, v8
	v_rcp_f32_e32 v7, v1
	v_exp_f32_e32 v8, v2
	v_mul_f32_e32 v2, 0xbfb8aa3b, v3
	v_exp_f32_e32 v9, v2
	v_cvt_pk_bf16_f32 v1, v4, v5
	v_lshlrev_b32_e32 v4, 16, v38
	v_and_b32_e32 v5, 0xffff0000, v38
	v_pk_mul_f32 v[4:5], v[6:7], v[4:5]
	v_lshlrev_b32_e32 v6, 16, v34
	v_and_b32_e32 v7, 0xffff0000, v34
	v_pk_mul_f32 v[2:3], v[4:5], v[6:7]
	v_add_f32_e32 v4, 1.0, v8
	v_add_f32_e32 v5, 1.0, v9
	v_rcp_f32_e32 v4, v4
	v_rcp_f32_e32 v5, v5
	v_lshlrev_b32_e32 v6, 16, v39
	v_and_b32_e32 v7, 0xffff0000, v39
	v_cvt_pk_bf16_f32 v2, v2, v3
	v_pk_mul_f32 v[4:5], v[4:5], v[6:7]
	v_lshlrev_b32_e32 v6, 16, v35
	v_and_b32_e32 v7, 0xffff0000, v35
	v_pk_mul_f32 v[4:5], v[4:5], v[6:7]
	s_nop 0
	v_cvt_pk_bf16_f32 v3, v4, v5
	global_store_dwordx4 v[94:95], v[0:3], off offset:256 nt
	s_cbranch_vccnz .LBB0_966
	s_andn2_b64 vcc, exec, s[6:7]
	s_cbranch_vccnz .LBB0_965
	s_barrier
	s_branch .LBB0_965
